# all nine GEMM K-loops: per-tile accumulator zeroing (128 v_mov) removed, first K-iteration peeled with the first MFMA on each accumulator taking inline 0 as C
# speedup vs baseline: 1.0060x; 1.0059x over previous
; #define PG8_STAGE(bufoff, gbase, voff) do { _Pragma("unroll") for (int _i = 0; _i < 2; ++_i) \
;         __builtin_amdgcn_global_load_lds((const unsigned*)((const char*)(gbase) + (voff)[_i]), (PG8_LAS unsigned*)(lds + (bufoff) + ldsw + _i * 8192), 16, 0, 0); } while (0)
; #define PG8_LDA(dst, b, h) do { _Pragma("unroll") for (int m = 0; m < 4; ++m) _Pragma("unroll") for (int k = 0; k < 2; ++k) dst[m][k] = *(const PG8_LAS bf16x8*)(lds + PG8_SA(b, h) + aoff + m * 2048 + k * 1024); } while (0)
; #define PG8_LDB(dst, b, h) do { _Pragma("unroll") for (int n = 0; n < 2; ++n) _Pragma("unroll") for (int k = 0; k < 2; ++k) dst[n][k] = *(const PG8_LAS bf16x8*)(lds + PG8_SB(b, h) + boff + n * 2048 + k * 1024); } while (0)
; #define PG8_WAIT_V(n) asm volatile("s_waitcnt vmcnt(" #n ")" ::: "memory")
; #define PG8_WAIT_L(n) asm volatile("s_waitcnt lgkmcnt(" #n ")" ::: "memory")
; #define PG8_BAR __builtin_amdgcn_s_barrier()
; #define PG8_SCHED __builtin_amdgcn_sched_barrier(0)
; template <class Epi, class Sched, bool ALIGN_EPI = false, bool SP2 = false>
; __device__ __forceinline__ void gemm_phase(PG8_LAS unsigned char* lds, const Gemm g, const Sched& S, const Epi& E) {
;     ...
;         const char* nA = has_next ? (const char*)g.A + (size_t)nxt.pm * tstep : cA; const char* nB = has_next ? (const char*)g.Bt + (size_t)nxt.pn * tstep : cB;
;         for (int t = 0; t < nt; t += 2) {
;             const bool last = (t == nt - 2);
;             const char* a1 = cA + (size_t)(t + 1) * kstep;
;             const char* a2 = last ? nA : cA + (size_t)(t + 2) * kstep; const char* b2 = last ? nB : cB + (size_t)(t + 2) * kstep;
;             const char* a3 = a2 + kstep; const char* b3 = b2 + kstep;
;             if (last && has_next) S.a_ready(nxt);
;             if constexpr (SP2) {
;             PG8_LDB(B0, 0, 0); PG8_LDB(B1, 0, 1); PG8_SCHED; PG8_LDA(At, 0, 0); PG8_STAGE(PG8_SA(1, 1), a1 + hstep, voffA);
;             PG8_WAIT_V(8); PG8_WAIT_L(0); PG8_BAR; PG8_MMA(0, 0, At, B0); PG8_MMA(0, 1, At, B1); PG8_BAR; PG8_SCHED;
;             PG8_LDA(At, 0, 1); PG8_STAGE(PG8_SB(0, 0), b2, voffB); PG8_STAGE(PG8_SB(0, 1), b2 + hstep, voffB); PG8_STAGE(PG8_SA(0, 0), a2, voffA);
;             PG8_WAIT_V(8); PG8_WAIT_L(0); PG8_BAR; PG8_MMA(1, 0, At, B0); PG8_MMA(1, 1, At, B1); PG8_BAR; PG8_SCHED;
.LBB0_157:
	s_ashr_i32 s21, s20, 31
	s_lshl_b64 s[42:43], s[20:21], 20
	s_add_u32 s42, s28, s42
	s_addc_u32 s43, s29, s43
	s_and_b64 s[44:45], s[2:3], exec
	s_cselect_b32 s21, s43, s49
	s_cselect_b32 s73, s42, s48
	s_ashr_i32 s19, s18, 31
	s_lshl_b64 s[44:45], s[18:19], 20
	s_add_u32 s44, s31, s44
	s_addc_u32 s45, s35, s45
	s_and_b64 s[54:55], s[2:3], exec
	s_cselect_b32 s19, s45, s51
	s_cselect_b32 s74, s44, s50
	s_add_u32 s48, s48, 0x80080
	s_addc_u32 s49, s49, 0
	s_add_u32 s75, s50, 0x100
	s_addc_u32 s76, s51, 0
	s_mov_b32 s77, -2
	ds_read_b128 v[144:147], v151
	ds_read_b128 v[154:157], v151 offset:1024
	ds_read_b128 v[158:161], v151 offset:2048
	ds_read_b128 v[162:165], v151 offset:3072
	ds_read_b128 v[166:169], v152
	ds_read_b128 v[170:173], v152 offset:1024
	ds_read_b128 v[174:177], v152 offset:2048
	ds_read_b128 v[178:181], v152 offset:3072
	s_add_u32 s50, s48, 0xfff80080
	s_addc_u32 s51, s49, -1
	s_cmp_eq_u32 s77, 28
	s_cselect_b32 s55, s21, s51
	s_cselect_b32 s54, s73, s50
	s_cselect_b32 s51, s19, s76
	s_cselect_b32 s50, s74, s75
	v_lshl_add_u64 v[214:215], s[48:49], 0, v[136:137]
	s_add_i32 m0, s47, 0xc000
	ds_read_b128 v[182:185], v153
	ds_read_b128 v[186:189], v153 offset:1024
	ds_read_b128 v[190:193], v153 offset:2048
	ds_read_b128 v[194:197], v153 offset:3072
	ds_read_b128 v[198:201], v153 offset:4096
	ds_read_b128 v[202:205], v153 offset:5120
	ds_read_b128 v[206:209], v153 offset:6144
	ds_read_b128 v[210:213], v153 offset:7168
	global_load_lds_dwordx4 v[214:215], off
	v_lshl_add_u64 v[214:215], s[48:49], 0, v[138:139]
	s_add_i32 m0, s47, 0xe000
	s_nop 0
	global_load_lds_dwordx4 v[214:215], off
	s_waitcnt vmcnt(8)
	s_waitcnt lgkmcnt(0)
	s_barrier
	s_setprio 1
	s_waitcnt lgkmcnt(0)
	v_mfma_f32_16x16x32_bf16 v[124:127], v[144:147], v[182:185], 0
	v_mfma_f32_16x16x32_bf16 v[116:119], v[158:161], v[182:185], 0
	v_mfma_f32_16x16x32_bf16 v[108:111], v[144:147], v[190:193], 0
	v_mfma_f32_16x16x32_bf16 v[100:103], v[158:161], v[190:193], 0
	v_mfma_f32_16x16x32_bf16 v[92:95], v[144:147], v[198:201], 0
	v_mfma_f32_16x16x32_bf16 v[84:87], v[158:161], v[198:201], 0
	v_mfma_f32_16x16x32_bf16 v[76:79], v[144:147], v[206:209], 0
	v_mfma_f32_16x16x32_bf16 v[68:71], v[158:161], v[206:209], 0
	v_mfma_f32_16x16x32_bf16 v[124:127], v[154:157], v[186:189], v[124:127]
	v_mfma_f32_16x16x32_bf16 v[116:119], v[162:165], v[186:189], v[116:119]
	v_mfma_f32_16x16x32_bf16 v[108:111], v[154:157], v[194:197], v[108:111]
	v_mfma_f32_16x16x32_bf16 v[100:103], v[162:165], v[194:197], v[100:103]
	v_mfma_f32_16x16x32_bf16 v[92:95], v[154:157], v[202:205], v[92:95]
	v_mfma_f32_16x16x32_bf16 v[84:87], v[162:165], v[202:205], v[84:87]
	v_mfma_f32_16x16x32_bf16 v[76:79], v[154:157], v[210:213], v[76:79]
	v_mfma_f32_16x16x32_bf16 v[68:71], v[162:165], v[210:213], v[68:71]
	s_setprio 0
	s_setprio 1
	v_mfma_f32_16x16x32_bf16 v[120:123], v[166:169], v[182:185], 0
	v_mfma_f32_16x16x32_bf16 v[112:115], v[174:177], v[182:185], 0
	v_mfma_f32_16x16x32_bf16 v[104:107], v[166:169], v[190:193], 0
	v_mfma_f32_16x16x32_bf16 v[96:99], v[174:177], v[190:193], 0
	v_mfma_f32_16x16x32_bf16 v[88:91], v[166:169], v[198:201], 0
	v_mfma_f32_16x16x32_bf16 v[80:83], v[174:177], v[198:201], 0
	v_mfma_f32_16x16x32_bf16 v[72:75], v[166:169], v[206:209], 0
	v_mfma_f32_16x16x32_bf16 v[64:67], v[174:177], v[206:209], 0
	v_mfma_f32_16x16x32_bf16 v[120:123], v[170:173], v[186:189], v[120:123]
	v_mfma_f32_16x16x32_bf16 v[112:115], v[178:181], v[186:189], v[112:115]
	v_mfma_f32_16x16x32_bf16 v[104:107], v[170:173], v[194:197], v[104:107]
	v_mfma_f32_16x16x32_bf16 v[96:99], v[178:181], v[194:197], v[96:99]
	v_mfma_f32_16x16x32_bf16 v[88:91], v[170:173], v[202:205], v[88:91]
	v_mfma_f32_16x16x32_bf16 v[80:83], v[178:181], v[202:205], v[80:83]
	v_mfma_f32_16x16x32_bf16 v[72:75], v[170:173], v[210:213], v[72:75]
	v_mfma_f32_16x16x32_bf16 v[64:67], v[178:181], v[210:213], v[64:67]
	s_setprio 0
	s_barrier
	s_add_i32 s78, s66, s56
	v_lshl_add_u64 v[214:215], s[50:51], 0, v[132:133]
	s_mov_b32 m0, s78
	ds_read_b128 v[182:185], v153 offset:16384
	ds_read_b128 v[186:189], v153 offset:17408
	ds_read_b128 v[190:193], v153 offset:18432
	ds_read_b128 v[194:197], v153 offset:19456
	ds_read_b128 v[198:201], v153 offset:20480
	ds_read_b128 v[202:205], v153 offset:21504
	ds_read_b128 v[206:209], v153 offset:22528
	ds_read_b128 v[210:213], v153 offset:23552
	global_load_lds_dwordx4 v[214:215], off
	s_add_i32 m0, s78, 0x2000
	s_add_u32 s78, s50, 0x80000
	v_lshl_add_u64 v[216:217], s[50:51], 0, v[128:129]
	s_addc_u32 s79, s51, 0
	s_add_i32 s80, s67, s56
	global_load_lds_dwordx4 v[216:217], off
	v_lshl_add_u64 v[220:221], s[78:79], 0, v[132:133]
	s_mov_b32 m0, s80
	v_lshl_add_u64 v[222:223], s[54:55], 0, v[130:131]
	global_load_lds_dwordx4 v[220:221], off
	v_lshl_add_u64 v[220:221], s[78:79], 0, v[128:129]
	s_add_i32 m0, s80, 0x2000
	s_nop 0
	global_load_lds_dwordx4 v[220:221], off
	v_lshl_add_u64 v[220:221], s[54:55], 0, v[134:135]
	s_mov_b32 m0, s47
	s_nop 0
	global_load_lds_dwordx4 v[220:221], off
	s_mov_b32 m0, s59
	s_nop 0
	global_load_lds_dwordx4 v[222:223], off
	s_waitcnt vmcnt(8)
	s_waitcnt lgkmcnt(0)
	s_barrier
; #define PG8_STAGE(bufoff, gbase, voff) do { _Pragma("unroll") for (int _i = 0; _i < 2; ++_i) \
;         __builtin_amdgcn_global_load_lds((const unsigned*)((const char*)(gbase) + (voff)[_i]), (PG8_LAS unsigned*)(lds + (bufoff) + ldsw + _i * 8192), 16, 0, 0); } while (0)
; #define PG8_LDA(dst, b, h) do { _Pragma("unroll") for (int m = 0; m < 4; ++m) _Pragma("unroll") for (int k = 0; k < 2; ++k) dst[m][k] = *(const PG8_LAS bf16x8*)(lds + PG8_SA(b, h) + aoff + m * 2048 + k * 1024); } while (0)
; #define PG8_LDB(dst, b, h) do { _Pragma("unroll") for (int n = 0; n < 2; ++n) _Pragma("unroll") for (int k = 0; k < 2; ++k) dst[n][k] = *(const PG8_LAS bf16x8*)(lds + PG8_SB(b, h) + boff + n * 2048 + k * 1024); } while (0)
; #define PG8_MMA(ai, bj, At, Bt) do { __builtin_amdgcn_s_setprio(1); _Pragma("unroll") for (int m = 0; m < 4; ++m) _Pragma("unroll") for (int n = 0; n < 2; ++n) _Pragma("unroll") for (int k = 0; k < 2; ++k) \
;         acc[ai][bj][m][n] = __builtin_amdgcn_mfma_f32_16x16x32_bf16(Bt[n][k], At[m][k], acc[ai][bj][m][n], 0, 0, 0); __builtin_amdgcn_s_setprio(0); } while (0)
; #define PG8_WAIT_V(n) asm volatile("s_waitcnt vmcnt(" #n ")" ::: "memory")
; #define PG8_WAIT_L(n) asm volatile("s_waitcnt lgkmcnt(" #n ")" ::: "memory")
; #define PG8_BAR __builtin_amdgcn_s_barrier()
; #define PG8_SCHED __builtin_amdgcn_sched_barrier(0)
; template <class Epi, class Sched, bool ALIGN_EPI = false, bool SP2 = false>
; __device__ __forceinline__ void gemm_phase(PG8_LAS unsigned char* lds, const Gemm g, const Sched& S, const Epi& E) {
;     ...
;             PG8_WAIT_V(8); PG8_WAIT_L(0); PG8_BAR; PG8_MMA(1, 0, At, B0); PG8_MMA(1, 1, At, B1); PG8_BAR; PG8_SCHED;
;             PG8_LDB(B0, 1, 0); PG8_LDB(B1, 1, 1); PG8_SCHED; PG8_LDA(At, 1, 0); PG8_STAGE(PG8_SA(0, 1), a2 + hstep, voffA);
;             PG8_WAIT_V(8); PG8_WAIT_L(0); PG8_BAR; PG8_MMA(0, 0, At, B0); PG8_MMA(0, 1, At, B1); PG8_BAR; PG8_SCHED;
	s_setprio 1
	s_waitcnt lgkmcnt(0)
	v_mfma_f32_16x16x32_bf16 v[60:63], v[144:147], v[182:185], 0
	v_mfma_f32_16x16x32_bf16 v[52:55], v[158:161], v[182:185], 0
	v_mfma_f32_16x16x32_bf16 v[44:47], v[144:147], v[190:193], 0
	v_mfma_f32_16x16x32_bf16 v[36:39], v[158:161], v[190:193], 0
	v_mfma_f32_16x16x32_bf16 v[28:31], v[144:147], v[198:201], 0
	v_mfma_f32_16x16x32_bf16 v[20:23], v[158:161], v[198:201], 0
	v_mfma_f32_16x16x32_bf16 v[12:15], v[144:147], v[206:209], 0
	v_mfma_f32_16x16x32_bf16 v[4:7], v[158:161], v[206:209], 0
	v_mfma_f32_16x16x32_bf16 v[60:63], v[154:157], v[186:189], v[60:63]
	v_mfma_f32_16x16x32_bf16 v[52:55], v[162:165], v[186:189], v[52:55]
	v_mfma_f32_16x16x32_bf16 v[44:47], v[154:157], v[194:197], v[44:47]
	v_mfma_f32_16x16x32_bf16 v[36:39], v[162:165], v[194:197], v[36:39]
	v_mfma_f32_16x16x32_bf16 v[28:31], v[154:157], v[202:205], v[28:31]
	v_mfma_f32_16x16x32_bf16 v[20:23], v[162:165], v[202:205], v[20:23]
	v_mfma_f32_16x16x32_bf16 v[12:15], v[154:157], v[210:213], v[12:15]
	v_mfma_f32_16x16x32_bf16 v[4:7], v[162:165], v[210:213], v[4:7]
	s_setprio 0
	s_setprio 1
	v_mfma_f32_16x16x32_bf16 v[56:59], v[166:169], v[182:185], 0
	v_mfma_f32_16x16x32_bf16 v[48:51], v[174:177], v[182:185], 0
	v_mfma_f32_16x16x32_bf16 v[40:43], v[166:169], v[190:193], 0
	v_mfma_f32_16x16x32_bf16 v[32:35], v[174:177], v[190:193], 0
	v_mfma_f32_16x16x32_bf16 v[24:27], v[166:169], v[198:201], 0
	v_mfma_f32_16x16x32_bf16 v[16:19], v[174:177], v[198:201], 0
	v_mfma_f32_16x16x32_bf16 v[8:11], v[166:169], v[206:209], 0
	v_mfma_f32_16x16x32_bf16 v[0:3], v[174:177], v[206:209], 0
	v_mfma_f32_16x16x32_bf16 v[56:59], v[170:173], v[186:189], v[56:59]
	v_mfma_f32_16x16x32_bf16 v[48:51], v[178:181], v[186:189], v[48:51]
	v_mfma_f32_16x16x32_bf16 v[40:43], v[170:173], v[194:197], v[40:43]
	v_mfma_f32_16x16x32_bf16 v[32:35], v[178:181], v[194:197], v[32:35]
	v_mfma_f32_16x16x32_bf16 v[24:27], v[170:173], v[202:205], v[24:27]
	v_mfma_f32_16x16x32_bf16 v[16:19], v[178:181], v[202:205], v[16:19]
	v_mfma_f32_16x16x32_bf16 v[8:11], v[170:173], v[210:213], v[8:11]
	v_mfma_f32_16x16x32_bf16 v[0:3], v[178:181], v[210:213], v[0:3]
	s_setprio 0
	s_barrier
	s_add_i32 s78, 0, 0x18000
	s_add_i32 s79, 0, 0x1c000
	v_add_u32_e32 v162, s78, v149
	v_add_u32_e32 v178, s79, v149
	ds_read_b128 v[144:147], v162
	ds_read_b128 v[154:157], v162 offset:1024
	ds_read_b128 v[158:161], v162 offset:2048
	ds_read_b128 v[162:165], v162 offset:3072
	ds_read_b128 v[166:169], v178
	ds_read_b128 v[170:173], v178 offset:1024
	ds_read_b128 v[174:177], v178 offset:2048
	ds_read_b128 v[178:181], v178 offset:3072
	s_add_u32 s54, s54, 0x80000
	s_addc_u32 s55, s55, 0
	s_mov_b32 m0, s60
	v_lshl_add_u64 v[224:225], s[54:55], 0, v[134:135]
	ds_read_b128 v[182:185], v153 offset:32768
	ds_read_b128 v[186:189], v153 offset:33792
	ds_read_b128 v[190:193], v153 offset:34816
	ds_read_b128 v[194:197], v153 offset:35840
	ds_read_b128 v[198:201], v153 offset:36864
	ds_read_b128 v[202:205], v153 offset:37888
	ds_read_b128 v[206:209], v153 offset:38912
	ds_read_b128 v[210:213], v153 offset:39936
	global_load_lds_dwordx4 v[224:225], off
	v_lshl_add_u64 v[224:225], s[54:55], 0, v[130:131]
	s_mov_b32 m0, s61
	s_nop 0
	global_load_lds_dwordx4 v[224:225], off
	s_waitcnt vmcnt(8)
	s_waitcnt lgkmcnt(0)
	s_barrier
	s_setprio 1
	s_waitcnt lgkmcnt(0)
	v_mfma_f32_16x16x32_bf16 v[124:127], v[144:147], v[182:185], v[124:127]
	v_mfma_f32_16x16x32_bf16 v[116:119], v[158:161], v[182:185], v[116:119]
	v_mfma_f32_16x16x32_bf16 v[108:111], v[144:147], v[190:193], v[108:111]
	v_mfma_f32_16x16x32_bf16 v[100:103], v[158:161], v[190:193], v[100:103]
	v_mfma_f32_16x16x32_bf16 v[92:95], v[144:147], v[198:201], v[92:95]
	v_mfma_f32_16x16x32_bf16 v[84:87], v[158:161], v[198:201], v[84:87]
	v_mfma_f32_16x16x32_bf16 v[76:79], v[144:147], v[206:209], v[76:79]
	v_mfma_f32_16x16x32_bf16 v[68:71], v[158:161], v[206:209], v[68:71]
	v_mfma_f32_16x16x32_bf16 v[124:127], v[154:157], v[186:189], v[124:127]
	v_mfma_f32_16x16x32_bf16 v[116:119], v[162:165], v[186:189], v[116:119]
	v_mfma_f32_16x16x32_bf16 v[108:111], v[154:157], v[194:197], v[108:111]
	v_mfma_f32_16x16x32_bf16 v[100:103], v[162:165], v[194:197], v[100:103]
	v_mfma_f32_16x16x32_bf16 v[92:95], v[154:157], v[202:205], v[92:95]
	v_mfma_f32_16x16x32_bf16 v[84:87], v[162:165], v[202:205], v[84:87]
	v_mfma_f32_16x16x32_bf16 v[76:79], v[154:157], v[210:213], v[76:79]
	v_mfma_f32_16x16x32_bf16 v[68:71], v[162:165], v[210:213], v[68:71]
	s_setprio 0
	s_setprio 1
	v_mfma_f32_16x16x32_bf16 v[120:123], v[166:169], v[182:185], v[120:123]
	v_mfma_f32_16x16x32_bf16 v[112:115], v[174:177], v[182:185], v[112:115]
	v_mfma_f32_16x16x32_bf16 v[104:107], v[166:169], v[190:193], v[104:107]
	v_mfma_f32_16x16x32_bf16 v[96:99], v[174:177], v[190:193], v[96:99]
	v_mfma_f32_16x16x32_bf16 v[88:91], v[166:169], v[198:201], v[88:91]
	v_mfma_f32_16x16x32_bf16 v[80:83], v[174:177], v[198:201], v[80:83]
	v_mfma_f32_16x16x32_bf16 v[72:75], v[166:169], v[206:209], v[72:75]
	v_mfma_f32_16x16x32_bf16 v[64:67], v[174:177], v[206:209], v[64:67]
	v_mfma_f32_16x16x32_bf16 v[120:123], v[170:173], v[186:189], v[120:123]
	v_mfma_f32_16x16x32_bf16 v[112:115], v[178:181], v[186:189], v[112:115]
	v_mfma_f32_16x16x32_bf16 v[104:107], v[170:173], v[194:197], v[104:107]
	v_mfma_f32_16x16x32_bf16 v[96:99], v[178:181], v[194:197], v[96:99]
	v_mfma_f32_16x16x32_bf16 v[88:91], v[170:173], v[202:205], v[88:91]
	v_mfma_f32_16x16x32_bf16 v[80:83], v[178:181], v[202:205], v[80:83]
	v_mfma_f32_16x16x32_bf16 v[72:75], v[170:173], v[210:213], v[72:75]
	v_mfma_f32_16x16x32_bf16 v[64:67], v[178:181], v[210:213], v[64:67]
	s_setprio 0
	s_barrier
; #define PG8_STAGE(bufoff, gbase, voff) do { _Pragma("unroll") for (int _i = 0; _i < 2; ++_i) \
;         __builtin_amdgcn_global_load_lds((const unsigned*)((const char*)(gbase) + (voff)[_i]), (PG8_LAS unsigned*)(lds + (bufoff) + ldsw + _i * 8192), 16, 0, 0); } while (0)
; #define PG8_LDA(dst, b, h) do { _Pragma("unroll") for (int m = 0; m < 4; ++m) _Pragma("unroll") for (int k = 0; k < 2; ++k) dst[m][k] = *(const PG8_LAS bf16x8*)(lds + PG8_SA(b, h) + aoff + m * 2048 + k * 1024); } while (0)
; #define PG8_MMA(ai, bj, At, Bt) do { __builtin_amdgcn_s_setprio(1); _Pragma("unroll") for (int m = 0; m < 4; ++m) _Pragma("unroll") for (int n = 0; n < 2; ++n) _Pragma("unroll") for (int k = 0; k < 2; ++k) \
;         acc[ai][bj][m][n] = __builtin_amdgcn_mfma_f32_16x16x32_bf16(Bt[n][k], At[m][k], acc[ai][bj][m][n], 0, 0, 0); __builtin_amdgcn_s_setprio(0); } while (0)
; #define PG8_WAIT_V(n) asm volatile("s_waitcnt vmcnt(" #n ")" ::: "memory")
; #define PG8_WAIT_L(n) asm volatile("s_waitcnt lgkmcnt(" #n ")" ::: "memory")
; #define PG8_BAR __builtin_amdgcn_s_barrier()
; #define PG8_SCHED __builtin_amdgcn_sched_barrier(0)
; template <class Epi, class Sched, bool ALIGN_EPI = false, bool SP2 = false>
; __device__ __forceinline__ void gemm_phase(PG8_LAS unsigned char* lds, const Gemm g, const Sched& S, const Epi& E) {
;     ...
;             PG8_LDA(At, 1, 1); PG8_STAGE(PG8_SB(1, 0), b3, voffB); PG8_STAGE(PG8_SB(1, 1), b3 + hstep, voffB); PG8_STAGE(PG8_SA(1, 0), a3, voffA);
;             PG8_WAIT_V(8); PG8_WAIT_L(0); PG8_BAR; PG8_MMA(1, 0, At, B0); PG8_MMA(1, 1, At, B1); PG8_BAR; PG8_SCHED;
	s_add_i32 s54, s78, s56
	v_lshl_add_u64 v[214:215], v[214:215], 0, s[14:15]
	s_mov_b32 m0, s54
	ds_read_b128 v[182:185], v153 offset:49152
	ds_read_b128 v[186:189], v153 offset:50176
	ds_read_b128 v[190:193], v153 offset:51200
	ds_read_b128 v[194:197], v153 offset:52224
	ds_read_b128 v[198:201], v153 offset:53248
	ds_read_b128 v[202:205], v153 offset:54272
	ds_read_b128 v[206:209], v153 offset:55296
	ds_read_b128 v[210:213], v153 offset:56320
	global_load_lds_dwordx4 v[214:215], off
	s_add_i32 m0, s54, 0x2000
	s_add_u32 s50, s50, 0x80080
	v_lshl_add_u64 v[214:215], v[216:217], 0, s[14:15]
	s_addc_u32 s51, s51, 0
	s_add_i32 s54, s79, s56
	global_load_lds_dwordx4 v[214:215], off
	v_lshl_add_u64 v[214:215], s[50:51], 0, v[132:133]
	s_mov_b32 m0, s54
	s_nop 0
	global_load_lds_dwordx4 v[214:215], off
	v_lshl_add_u64 v[214:215], s[50:51], 0, v[128:129]
	s_add_i32 m0, s54, 0x2000
	s_nop 0
	global_load_lds_dwordx4 v[214:215], off
	v_lshl_add_u64 v[214:215], v[220:221], 0, s[14:15]
	s_mov_b32 m0, s63
	s_nop 0
	global_load_lds_dwordx4 v[214:215], off
	v_lshl_add_u64 v[214:215], v[222:223], 0, s[14:15]
	s_mov_b32 m0, s64
	s_nop 0
	global_load_lds_dwordx4 v[214:215], off
	s_waitcnt vmcnt(8)
	s_waitcnt lgkmcnt(0)
	s_barrier
	s_setprio 1
	s_waitcnt lgkmcnt(0)
	v_mfma_f32_16x16x32_bf16 v[60:63], v[144:147], v[182:185], v[60:63]
	v_mfma_f32_16x16x32_bf16 v[52:55], v[158:161], v[182:185], v[52:55]
	v_mfma_f32_16x16x32_bf16 v[44:47], v[144:147], v[190:193], v[44:47]
	v_mfma_f32_16x16x32_bf16 v[36:39], v[158:161], v[190:193], v[36:39]
	v_mfma_f32_16x16x32_bf16 v[28:31], v[144:147], v[198:201], v[28:31]
	v_mfma_f32_16x16x32_bf16 v[20:23], v[158:161], v[198:201], v[20:23]
	v_mfma_f32_16x16x32_bf16 v[12:15], v[144:147], v[206:209], v[12:15]
	v_mfma_f32_16x16x32_bf16 v[4:7], v[158:161], v[206:209], v[4:7]
	v_mfma_f32_16x16x32_bf16 v[60:63], v[154:157], v[186:189], v[60:63]
	v_mfma_f32_16x16x32_bf16 v[52:55], v[162:165], v[186:189], v[52:55]
	v_mfma_f32_16x16x32_bf16 v[44:47], v[154:157], v[194:197], v[44:47]
	v_mfma_f32_16x16x32_bf16 v[36:39], v[162:165], v[194:197], v[36:39]
	v_mfma_f32_16x16x32_bf16 v[28:31], v[154:157], v[202:205], v[28:31]
	v_mfma_f32_16x16x32_bf16 v[20:23], v[162:165], v[202:205], v[20:23]
	v_mfma_f32_16x16x32_bf16 v[12:15], v[154:157], v[210:213], v[12:15]
	v_mfma_f32_16x16x32_bf16 v[4:7], v[162:165], v[210:213], v[4:7]
	s_setprio 0
	s_setprio 1
	v_mfma_f32_16x16x32_bf16 v[56:59], v[166:169], v[182:185], v[56:59]
	v_mfma_f32_16x16x32_bf16 v[48:51], v[174:177], v[182:185], v[48:51]
	v_mfma_f32_16x16x32_bf16 v[40:43], v[166:169], v[190:193], v[40:43]
	v_mfma_f32_16x16x32_bf16 v[32:35], v[174:177], v[190:193], v[32:35]
	v_mfma_f32_16x16x32_bf16 v[24:27], v[166:169], v[198:201], v[24:27]
	v_mfma_f32_16x16x32_bf16 v[16:19], v[174:177], v[198:201], v[16:19]
	v_mfma_f32_16x16x32_bf16 v[8:11], v[166:169], v[206:209], v[8:11]
	v_mfma_f32_16x16x32_bf16 v[0:3], v[174:177], v[206:209], v[0:3]
	v_mfma_f32_16x16x32_bf16 v[56:59], v[170:173], v[186:189], v[56:59]
	v_mfma_f32_16x16x32_bf16 v[48:51], v[178:181], v[186:189], v[48:51]
	v_mfma_f32_16x16x32_bf16 v[40:43], v[170:173], v[194:197], v[40:43]
	v_mfma_f32_16x16x32_bf16 v[32:35], v[178:181], v[194:197], v[32:35]
	v_mfma_f32_16x16x32_bf16 v[24:27], v[170:173], v[202:205], v[24:27]
	v_mfma_f32_16x16x32_bf16 v[16:19], v[178:181], v[202:205], v[16:19]
	v_mfma_f32_16x16x32_bf16 v[8:11], v[170:173], v[210:213], v[8:11]
	v_mfma_f32_16x16x32_bf16 v[0:3], v[178:181], v[210:213], v[0:3]
	s_setprio 0
	s_barrier
	s_add_i32 s77, s77, 2
	s_add_u32 s48, s48, 0x100
	s_addc_u32 s49, s49, 0
	s_add_u32 s75, s75, 0x100
	s_addc_u32 s76, s76, 0
	s_cmp_gt_u32 s77, 29

; #define PG8_STAGE(bufoff, gbase, voff) do { _Pragma("unroll") for (int _i = 0; _i < 2; ++_i) \
;         __builtin_amdgcn_global_load_lds((const unsigned*)((const char*)(gbase) + (voff)[_i]), (PG8_LAS unsigned*)(lds + (bufoff) + ldsw + _i * 8192), 16, 0, 0); } while (0)
; #define PG8_LDA(dst, b, h) do { _Pragma("unroll") for (int m = 0; m < 4; ++m) _Pragma("unroll") for (int k = 0; k < 2; ++k) dst[m][k] = *(const PG8_LAS bf16x8*)(lds + PG8_SA(b, h) + aoff + m * 2048 + k * 1024); } while (0)
; #define PG8_LDB(dst, b, h) do { _Pragma("unroll") for (int n = 0; n < 2; ++n) _Pragma("unroll") for (int k = 0; k < 2; ++k) dst[n][k] = *(const PG8_LAS bf16x8*)(lds + PG8_SB(b, h) + boff + n * 2048 + k * 1024); } while (0)
; #define PG8_WAIT_V(n) asm volatile("s_waitcnt vmcnt(" #n ")" ::: "memory")
; #define PG8_WAIT_L(n) asm volatile("s_waitcnt lgkmcnt(" #n ")" ::: "memory")
; #define PG8_BAR __builtin_amdgcn_s_barrier()
; #define PG8_SCHED __builtin_amdgcn_sched_barrier(0)
; template <class Epi, class Sched, bool ALIGN_EPI = false, bool SP2 = false>
; __device__ __forceinline__ void gemm_phase(PG8_LAS unsigned char* lds, const Gemm g, const Sched& S, const Epi& E) {
;     ...
;         const char* nA = has_next ? (const char*)g.A + (size_t)nxt.pm * tstep : cA; const char* nB = has_next ? (const char*)g.Bt + (size_t)nxt.pn * tstep : cB;
;         for (int t = 0; t < nt; t += 2) {
;             const bool last = (t == nt - 2);
;             const char* a1 = cA + (size_t)(t + 1) * kstep;
;             const char* a2 = last ? nA : cA + (size_t)(t + 2) * kstep; const char* b2 = last ? nB : cB + (size_t)(t + 2) * kstep;
;             const char* a3 = a2 + kstep; const char* b3 = b2 + kstep;
;             if (last && has_next) S.a_ready(nxt);
;             if constexpr (SP2) {
;             PG8_LDB(B0, 0, 0); PG8_LDB(B1, 0, 1); PG8_SCHED; PG8_LDA(At, 0, 0); PG8_STAGE(PG8_SA(1, 1), a1 + hstep, voffA);
;             PG8_WAIT_V(8); PG8_WAIT_L(0); PG8_BAR; PG8_MMA(0, 0, At, B0); PG8_MMA(0, 1, At, B1); PG8_BAR; PG8_SCHED;
;             PG8_LDA(At, 0, 1); PG8_STAGE(PG8_SB(0, 0), b2, voffB); PG8_STAGE(PG8_SB(0, 1), b2 + hstep, voffB); PG8_STAGE(PG8_SA(0, 0), a2, voffA);
;             PG8_WAIT_V(8); PG8_WAIT_L(0); PG8_BAR; PG8_MMA(1, 0, At, B0); PG8_MMA(1, 1, At, B1); PG8_BAR; PG8_SCHED;
.LBB0_173:
	s_ashr_i32 s47, s46, 31
	s_lshl_b64 s[50:51], s[46:47], 20
	s_add_u32 s50, s28, s50
	s_addc_u32 s51, s29, s51
	s_and_b64 s[54:55], s[48:49], exec
	s_cselect_b32 s47, s51, s59
	s_cselect_b32 s83, s50, s58
	s_ashr_i32 s45, s44, 31
	s_lshl_b64 s[54:55], s[44:45], 20
	s_add_u32 s54, s31, s54
	s_addc_u32 s55, s35, s55
	s_and_b64 s[62:63], s[48:49], exec
	s_cselect_b32 s45, s55, s61
	s_cselect_b32 s84, s54, s60
	s_add_u32 s58, s58, 0x80080
	s_addc_u32 s59, s59, 0
	s_add_u32 s85, s60, 0x100
	s_addc_u32 s86, s61, 0
	s_mov_b32 s87, -2
	ds_read_b128 v[148:151], v145
	ds_read_b128 v[152:155], v145 offset:1024
	ds_read_b128 v[156:159], v145 offset:2048
	ds_read_b128 v[160:163], v145 offset:3072
	ds_read_b128 v[164:167], v146
	ds_read_b128 v[168:171], v146 offset:1024
	ds_read_b128 v[172:175], v146 offset:2048
	ds_read_b128 v[176:179], v146 offset:3072
	s_add_u32 s60, s58, 0xfff80080
	s_addc_u32 s61, s59, -1
	s_cmp_eq_u32 s87, 28
	s_cselect_b32 s63, s47, s61
	s_cselect_b32 s62, s83, s60
	s_cselect_b32 s61, s45, s86
	s_cselect_b32 s60, s84, s85
	v_lshl_add_u64 v[140:141], s[58:59], 0, v[136:137]
	s_add_i32 m0, s57, 0xc000
	ds_read_b128 v[180:183], v147
	ds_read_b128 v[184:187], v147 offset:1024
	ds_read_b128 v[188:191], v147 offset:2048
	ds_read_b128 v[192:195], v147 offset:3072
	ds_read_b128 v[196:199], v147 offset:4096
	ds_read_b128 v[200:203], v147 offset:5120
	ds_read_b128 v[204:207], v147 offset:6144
	ds_read_b128 v[208:211], v147 offset:7168
	global_load_lds_dwordx4 v[140:141], off
	v_lshl_add_u64 v[140:141], s[58:59], 0, v[138:139]
	s_add_i32 m0, s57, 0xe000
	s_nop 0
	global_load_lds_dwordx4 v[140:141], off
	s_waitcnt vmcnt(8)
	s_waitcnt lgkmcnt(0)
	s_barrier
	s_setprio 1
	s_waitcnt lgkmcnt(0)
	v_mfma_f32_16x16x32_bf16 v[124:127], v[148:151], v[180:183], 0
	v_mfma_f32_16x16x32_bf16 v[120:123], v[156:159], v[180:183], 0
	v_mfma_f32_16x16x32_bf16 v[116:119], v[148:151], v[188:191], 0
	v_mfma_f32_16x16x32_bf16 v[108:111], v[156:159], v[188:191], 0
	v_mfma_f32_16x16x32_bf16 v[100:103], v[148:151], v[196:199], 0
	v_mfma_f32_16x16x32_bf16 v[92:95], v[156:159], v[196:199], 0
	v_mfma_f32_16x16x32_bf16 v[84:87], v[148:151], v[204:207], 0
	v_mfma_f32_16x16x32_bf16 v[76:79], v[156:159], v[204:207], 0
	v_mfma_f32_16x16x32_bf16 v[124:127], v[152:155], v[184:187], v[124:127]
	v_mfma_f32_16x16x32_bf16 v[120:123], v[160:163], v[184:187], v[120:123]
	v_mfma_f32_16x16x32_bf16 v[116:119], v[152:155], v[192:195], v[116:119]
	v_mfma_f32_16x16x32_bf16 v[108:111], v[160:163], v[192:195], v[108:111]
	v_mfma_f32_16x16x32_bf16 v[100:103], v[152:155], v[200:203], v[100:103]
	v_mfma_f32_16x16x32_bf16 v[92:95], v[160:163], v[200:203], v[92:95]
	v_mfma_f32_16x16x32_bf16 v[84:87], v[152:155], v[208:211], v[84:87]
	v_mfma_f32_16x16x32_bf16 v[76:79], v[160:163], v[208:211], v[76:79]
	s_setprio 0
	s_setprio 1
	v_mfma_f32_16x16x32_bf16 v[112:115], v[164:167], v[180:183], 0
	v_mfma_f32_16x16x32_bf16 v[104:107], v[172:175], v[180:183], 0
	v_mfma_f32_16x16x32_bf16 v[96:99], v[164:167], v[188:191], 0
	v_mfma_f32_16x16x32_bf16 v[88:91], v[172:175], v[188:191], 0
	v_mfma_f32_16x16x32_bf16 v[80:83], v[164:167], v[196:199], 0
	v_mfma_f32_16x16x32_bf16 v[72:75], v[172:175], v[196:199], 0
	v_mfma_f32_16x16x32_bf16 v[68:71], v[164:167], v[204:207], 0
	v_mfma_f32_16x16x32_bf16 v[64:67], v[172:175], v[204:207], 0
	v_mfma_f32_16x16x32_bf16 v[112:115], v[168:171], v[184:187], v[112:115]
	v_mfma_f32_16x16x32_bf16 v[104:107], v[176:179], v[184:187], v[104:107]
	v_mfma_f32_16x16x32_bf16 v[96:99], v[168:171], v[192:195], v[96:99]
	v_mfma_f32_16x16x32_bf16 v[88:91], v[176:179], v[192:195], v[88:91]
	v_mfma_f32_16x16x32_bf16 v[80:83], v[168:171], v[200:203], v[80:83]
	v_mfma_f32_16x16x32_bf16 v[72:75], v[176:179], v[200:203], v[72:75]
	v_mfma_f32_16x16x32_bf16 v[68:71], v[168:171], v[208:211], v[68:71]
	v_mfma_f32_16x16x32_bf16 v[64:67], v[176:179], v[208:211], v[64:67]
	s_setprio 0
	s_barrier
	s_add_i32 s88, s76, s64
	v_lshl_add_u64 v[140:141], s[60:61], 0, v[132:133]
	s_mov_b32 m0, s88
	ds_read_b128 v[180:183], v147 offset:16384
	ds_read_b128 v[184:187], v147 offset:17408
	ds_read_b128 v[188:191], v147 offset:18432
	ds_read_b128 v[192:195], v147 offset:19456
	ds_read_b128 v[196:199], v147 offset:20480
	ds_read_b128 v[200:203], v147 offset:21504
	ds_read_b128 v[204:207], v147 offset:22528
	ds_read_b128 v[208:211], v147 offset:23552
	global_load_lds_dwordx4 v[140:141], off
	s_add_i32 m0, s88, 0x2000
	s_add_u32 s88, s60, 0x80000
	v_lshl_add_u64 v[212:213], s[60:61], 0, v[128:129]
	s_addc_u32 s89, s61, 0
	s_add_i32 s90, s77, s64
	global_load_lds_dwordx4 v[212:213], off
	v_lshl_add_u64 v[214:215], s[88:89], 0, v[132:133]
	s_mov_b32 m0, s90
	v_lshl_add_u64 v[216:217], s[62:63], 0, v[130:131]
	global_load_lds_dwordx4 v[214:215], off
	v_lshl_add_u64 v[214:215], s[88:89], 0, v[128:129]
	s_add_i32 m0, s90, 0x2000
	s_nop 0
	global_load_lds_dwordx4 v[214:215], off
	v_lshl_add_u64 v[214:215], s[62:63], 0, v[134:135]
	s_mov_b32 m0, s57
	s_nop 0
	global_load_lds_dwordx4 v[214:215], off
	s_mov_b32 m0, s66
	s_nop 0
	global_load_lds_dwordx4 v[216:217], off
	s_waitcnt vmcnt(8)
	s_waitcnt lgkmcnt(0)
	s_barrier
; #define PG8_STAGE(bufoff, gbase, voff) do { _Pragma("unroll") for (int _i = 0; _i < 2; ++_i) \
;         __builtin_amdgcn_global_load_lds((const unsigned*)((const char*)(gbase) + (voff)[_i]), (PG8_LAS unsigned*)(lds + (bufoff) + ldsw + _i * 8192), 16, 0, 0); } while (0)
; #define PG8_LDA(dst, b, h) do { _Pragma("unroll") for (int m = 0; m < 4; ++m) _Pragma("unroll") for (int k = 0; k < 2; ++k) dst[m][k] = *(const PG8_LAS bf16x8*)(lds + PG8_SA(b, h) + aoff + m * 2048 + k * 1024); } while (0)
; #define PG8_LDB(dst, b, h) do { _Pragma("unroll") for (int n = 0; n < 2; ++n) _Pragma("unroll") for (int k = 0; k < 2; ++k) dst[n][k] = *(const PG8_LAS bf16x8*)(lds + PG8_SB(b, h) + boff + n * 2048 + k * 1024); } while (0)
; #define PG8_MMA(ai, bj, At, Bt) do { __builtin_amdgcn_s_setprio(1); _Pragma("unroll") for (int m = 0; m < 4; ++m) _Pragma("unroll") for (int n = 0; n < 2; ++n) _Pragma("unroll") for (int k = 0; k < 2; ++k) \
;         acc[ai][bj][m][n] = __builtin_amdgcn_mfma_f32_16x16x32_bf16(Bt[n][k], At[m][k], acc[ai][bj][m][n], 0, 0, 0); __builtin_amdgcn_s_setprio(0); } while (0)
; #define PG8_WAIT_V(n) asm volatile("s_waitcnt vmcnt(" #n ")" ::: "memory")
; #define PG8_WAIT_L(n) asm volatile("s_waitcnt lgkmcnt(" #n ")" ::: "memory")
; #define PG8_BAR __builtin_amdgcn_s_barrier()
; #define PG8_SCHED __builtin_amdgcn_sched_barrier(0)
; template <class Epi, class Sched, bool ALIGN_EPI = false, bool SP2 = false>
; __device__ __forceinline__ void gemm_phase(PG8_LAS unsigned char* lds, const Gemm g, const Sched& S, const Epi& E) {
;     ...
;             PG8_WAIT_V(8); PG8_WAIT_L(0); PG8_BAR; PG8_MMA(1, 0, At, B0); PG8_MMA(1, 1, At, B1); PG8_BAR; PG8_SCHED;
;             PG8_LDB(B0, 1, 0); PG8_LDB(B1, 1, 1); PG8_SCHED; PG8_LDA(At, 1, 0); PG8_STAGE(PG8_SA(0, 1), a2 + hstep, voffA);
;             PG8_WAIT_V(8); PG8_WAIT_L(0); PG8_BAR; PG8_MMA(0, 0, At, B0); PG8_MMA(0, 1, At, B1); PG8_BAR; PG8_SCHED;
	s_setprio 1
	s_waitcnt lgkmcnt(0)
	v_mfma_f32_16x16x32_bf16 v[60:63], v[148:151], v[180:183], 0
	v_mfma_f32_16x16x32_bf16 v[56:59], v[156:159], v[180:183], 0
	v_mfma_f32_16x16x32_bf16 v[52:55], v[148:151], v[188:191], 0
	v_mfma_f32_16x16x32_bf16 v[44:47], v[156:159], v[188:191], 0
	v_mfma_f32_16x16x32_bf16 v[36:39], v[148:151], v[196:199], 0
	v_mfma_f32_16x16x32_bf16 v[28:31], v[156:159], v[196:199], 0
	v_mfma_f32_16x16x32_bf16 v[20:23], v[148:151], v[204:207], 0
	v_mfma_f32_16x16x32_bf16 v[12:15], v[156:159], v[204:207], 0
	v_mfma_f32_16x16x32_bf16 v[60:63], v[152:155], v[184:187], v[60:63]
	v_mfma_f32_16x16x32_bf16 v[56:59], v[160:163], v[184:187], v[56:59]
	v_mfma_f32_16x16x32_bf16 v[52:55], v[152:155], v[192:195], v[52:55]
	v_mfma_f32_16x16x32_bf16 v[44:47], v[160:163], v[192:195], v[44:47]
	v_mfma_f32_16x16x32_bf16 v[36:39], v[152:155], v[200:203], v[36:39]
	v_mfma_f32_16x16x32_bf16 v[28:31], v[160:163], v[200:203], v[28:31]
	v_mfma_f32_16x16x32_bf16 v[20:23], v[152:155], v[208:211], v[20:23]
	v_mfma_f32_16x16x32_bf16 v[12:15], v[160:163], v[208:211], v[12:15]
	s_setprio 0
	s_setprio 1
	v_mfma_f32_16x16x32_bf16 v[48:51], v[164:167], v[180:183], 0
	v_mfma_f32_16x16x32_bf16 v[40:43], v[172:175], v[180:183], 0
	v_mfma_f32_16x16x32_bf16 v[32:35], v[164:167], v[188:191], 0
	v_mfma_f32_16x16x32_bf16 v[24:27], v[172:175], v[188:191], 0
	v_mfma_f32_16x16x32_bf16 v[16:19], v[164:167], v[196:199], 0
	v_mfma_f32_16x16x32_bf16 v[8:11], v[172:175], v[196:199], 0
	v_mfma_f32_16x16x32_bf16 v[4:7], v[164:167], v[204:207], 0
	v_mfma_f32_16x16x32_bf16 v[0:3], v[172:175], v[204:207], 0
	v_mfma_f32_16x16x32_bf16 v[48:51], v[168:171], v[184:187], v[48:51]
	v_mfma_f32_16x16x32_bf16 v[40:43], v[176:179], v[184:187], v[40:43]
	v_mfma_f32_16x16x32_bf16 v[32:35], v[168:171], v[192:195], v[32:35]
	v_mfma_f32_16x16x32_bf16 v[24:27], v[176:179], v[192:195], v[24:27]
	v_mfma_f32_16x16x32_bf16 v[16:19], v[168:171], v[200:203], v[16:19]
	v_mfma_f32_16x16x32_bf16 v[8:11], v[176:179], v[200:203], v[8:11]
	v_mfma_f32_16x16x32_bf16 v[4:7], v[168:171], v[208:211], v[4:7]
	v_mfma_f32_16x16x32_bf16 v[0:3], v[176:179], v[208:211], v[0:3]
	s_setprio 0
	s_barrier
	s_add_i32 s88, 0, 0x18000
	s_add_i32 s89, 0, 0x1c000
	v_add_u32_e32 v160, s88, v143
	v_add_u32_e32 v176, s89, v143
	ds_read_b128 v[148:151], v160
	ds_read_b128 v[152:155], v160 offset:1024
	ds_read_b128 v[156:159], v160 offset:2048
	ds_read_b128 v[160:163], v160 offset:3072
	ds_read_b128 v[164:167], v176
	ds_read_b128 v[168:171], v176 offset:1024
	ds_read_b128 v[172:175], v176 offset:2048
	ds_read_b128 v[176:179], v176 offset:3072
	s_add_u32 s62, s62, 0x80000
	s_addc_u32 s63, s63, 0
	s_mov_b32 m0, s67
	v_lshl_add_u64 v[220:221], s[62:63], 0, v[134:135]
	ds_read_b128 v[180:183], v147 offset:32768
	ds_read_b128 v[184:187], v147 offset:33792
	ds_read_b128 v[188:191], v147 offset:34816
	ds_read_b128 v[192:195], v147 offset:35840
	ds_read_b128 v[196:199], v147 offset:36864
	ds_read_b128 v[200:203], v147 offset:37888
	ds_read_b128 v[204:207], v147 offset:38912
	ds_read_b128 v[208:211], v147 offset:39936
	global_load_lds_dwordx4 v[220:221], off
	v_lshl_add_u64 v[220:221], s[62:63], 0, v[130:131]
	s_mov_b32 m0, s71
	s_nop 0
	global_load_lds_dwordx4 v[220:221], off
	s_waitcnt vmcnt(8)
	s_waitcnt lgkmcnt(0)
	s_barrier
	s_setprio 1
	s_waitcnt lgkmcnt(0)
	v_mfma_f32_16x16x32_bf16 v[124:127], v[148:151], v[180:183], v[124:127]
	v_mfma_f32_16x16x32_bf16 v[120:123], v[156:159], v[180:183], v[120:123]
	v_mfma_f32_16x16x32_bf16 v[116:119], v[148:151], v[188:191], v[116:119]
	v_mfma_f32_16x16x32_bf16 v[108:111], v[156:159], v[188:191], v[108:111]
	v_mfma_f32_16x16x32_bf16 v[100:103], v[148:151], v[196:199], v[100:103]
	v_mfma_f32_16x16x32_bf16 v[92:95], v[156:159], v[196:199], v[92:95]
	v_mfma_f32_16x16x32_bf16 v[84:87], v[148:151], v[204:207], v[84:87]
	v_mfma_f32_16x16x32_bf16 v[76:79], v[156:159], v[204:207], v[76:79]
	v_mfma_f32_16x16x32_bf16 v[124:127], v[152:155], v[184:187], v[124:127]
	v_mfma_f32_16x16x32_bf16 v[120:123], v[160:163], v[184:187], v[120:123]
	v_mfma_f32_16x16x32_bf16 v[116:119], v[152:155], v[192:195], v[116:119]
	v_mfma_f32_16x16x32_bf16 v[108:111], v[160:163], v[192:195], v[108:111]
	v_mfma_f32_16x16x32_bf16 v[100:103], v[152:155], v[200:203], v[100:103]
	v_mfma_f32_16x16x32_bf16 v[92:95], v[160:163], v[200:203], v[92:95]
	v_mfma_f32_16x16x32_bf16 v[84:87], v[152:155], v[208:211], v[84:87]
	v_mfma_f32_16x16x32_bf16 v[76:79], v[160:163], v[208:211], v[76:79]
	s_setprio 0
	s_setprio 1
	v_mfma_f32_16x16x32_bf16 v[112:115], v[164:167], v[180:183], v[112:115]
	v_mfma_f32_16x16x32_bf16 v[104:107], v[172:175], v[180:183], v[104:107]
	v_mfma_f32_16x16x32_bf16 v[96:99], v[164:167], v[188:191], v[96:99]
	v_mfma_f32_16x16x32_bf16 v[88:91], v[172:175], v[188:191], v[88:91]
	v_mfma_f32_16x16x32_bf16 v[80:83], v[164:167], v[196:199], v[80:83]
	v_mfma_f32_16x16x32_bf16 v[72:75], v[172:175], v[196:199], v[72:75]
	v_mfma_f32_16x16x32_bf16 v[68:71], v[164:167], v[204:207], v[68:71]
	v_mfma_f32_16x16x32_bf16 v[64:67], v[172:175], v[204:207], v[64:67]
	v_mfma_f32_16x16x32_bf16 v[112:115], v[168:171], v[184:187], v[112:115]
	v_mfma_f32_16x16x32_bf16 v[104:107], v[176:179], v[184:187], v[104:107]
	v_mfma_f32_16x16x32_bf16 v[96:99], v[168:171], v[192:195], v[96:99]
	v_mfma_f32_16x16x32_bf16 v[88:91], v[176:179], v[192:195], v[88:91]
	v_mfma_f32_16x16x32_bf16 v[80:83], v[168:171], v[200:203], v[80:83]
	v_mfma_f32_16x16x32_bf16 v[72:75], v[176:179], v[200:203], v[72:75]
	v_mfma_f32_16x16x32_bf16 v[68:71], v[168:171], v[208:211], v[68:71]
	v_mfma_f32_16x16x32_bf16 v[64:67], v[176:179], v[208:211], v[64:67]
	s_setprio 0
	s_barrier
; #define PG8_STAGE(bufoff, gbase, voff) do { _Pragma("unroll") for (int _i = 0; _i < 2; ++_i) \
;         __builtin_amdgcn_global_load_lds((const unsigned*)((const char*)(gbase) + (voff)[_i]), (PG8_LAS unsigned*)(lds + (bufoff) + ldsw + _i * 8192), 16, 0, 0); } while (0)
; #define PG8_LDA(dst, b, h) do { _Pragma("unroll") for (int m = 0; m < 4; ++m) _Pragma("unroll") for (int k = 0; k < 2; ++k) dst[m][k] = *(const PG8_LAS bf16x8*)(lds + PG8_SA(b, h) + aoff + m * 2048 + k * 1024); } while (0)
; #define PG8_MMA(ai, bj, At, Bt) do { __builtin_amdgcn_s_setprio(1); _Pragma("unroll") for (int m = 0; m < 4; ++m) _Pragma("unroll") for (int n = 0; n < 2; ++n) _Pragma("unroll") for (int k = 0; k < 2; ++k) \
;         acc[ai][bj][m][n] = __builtin_amdgcn_mfma_f32_16x16x32_bf16(Bt[n][k], At[m][k], acc[ai][bj][m][n], 0, 0, 0); __builtin_amdgcn_s_setprio(0); } while (0)
; #define PG8_WAIT_V(n) asm volatile("s_waitcnt vmcnt(" #n ")" ::: "memory")
; #define PG8_WAIT_L(n) asm volatile("s_waitcnt lgkmcnt(" #n ")" ::: "memory")
; #define PG8_BAR __builtin_amdgcn_s_barrier()
; #define PG8_SCHED __builtin_amdgcn_sched_barrier(0)
; template <class Epi, class Sched, bool ALIGN_EPI = false, bool SP2 = false>
; __device__ __forceinline__ void gemm_phase(PG8_LAS unsigned char* lds, const Gemm g, const Sched& S, const Epi& E) {
;     ...
;             PG8_LDA(At, 1, 1); PG8_STAGE(PG8_SB(1, 0), b3, voffB); PG8_STAGE(PG8_SB(1, 1), b3 + hstep, voffB); PG8_STAGE(PG8_SA(1, 0), a3, voffA);
;             PG8_WAIT_V(8); PG8_WAIT_L(0); PG8_BAR; PG8_MMA(1, 0, At, B0); PG8_MMA(1, 1, At, B1); PG8_BAR; PG8_SCHED;
	s_add_i32 s62, s88, s64
	v_lshl_add_u64 v[140:141], v[140:141], 0, s[12:13]
	s_mov_b32 m0, s62
	ds_read_b128 v[180:183], v147 offset:49152
	ds_read_b128 v[184:187], v147 offset:50176
	ds_read_b128 v[188:191], v147 offset:51200
	ds_read_b128 v[192:195], v147 offset:52224
	ds_read_b128 v[196:199], v147 offset:53248
	ds_read_b128 v[200:203], v147 offset:54272
	ds_read_b128 v[204:207], v147 offset:55296
	ds_read_b128 v[208:211], v147 offset:56320
	global_load_lds_dwordx4 v[140:141], off
	s_add_i32 m0, s62, 0x2000
	s_add_u32 s60, s60, 0x80080
	v_lshl_add_u64 v[140:141], v[212:213], 0, s[12:13]
	s_addc_u32 s61, s61, 0
	s_add_i32 s62, s89, s64
	global_load_lds_dwordx4 v[140:141], off
	v_lshl_add_u64 v[140:141], s[60:61], 0, v[132:133]
	s_mov_b32 m0, s62
	s_nop 0
	global_load_lds_dwordx4 v[140:141], off
	v_lshl_add_u64 v[140:141], s[60:61], 0, v[128:129]
	s_add_i32 m0, s62, 0x2000
	s_nop 0
	global_load_lds_dwordx4 v[140:141], off
	v_lshl_add_u64 v[140:141], v[214:215], 0, s[12:13]
	s_mov_b32 m0, s73
	s_nop 0
	global_load_lds_dwordx4 v[140:141], off
	v_lshl_add_u64 v[140:141], v[216:217], 0, s[12:13]
	s_mov_b32 m0, s74
	s_nop 0
	global_load_lds_dwordx4 v[140:141], off
	s_waitcnt vmcnt(8)
	s_waitcnt lgkmcnt(0)
	s_barrier
	s_setprio 1
	s_waitcnt lgkmcnt(0)
	v_mfma_f32_16x16x32_bf16 v[60:63], v[148:151], v[180:183], v[60:63]
	v_mfma_f32_16x16x32_bf16 v[56:59], v[156:159], v[180:183], v[56:59]
	v_mfma_f32_16x16x32_bf16 v[52:55], v[148:151], v[188:191], v[52:55]
	v_mfma_f32_16x16x32_bf16 v[44:47], v[156:159], v[188:191], v[44:47]
	v_mfma_f32_16x16x32_bf16 v[36:39], v[148:151], v[196:199], v[36:39]
	v_mfma_f32_16x16x32_bf16 v[28:31], v[156:159], v[196:199], v[28:31]
	v_mfma_f32_16x16x32_bf16 v[20:23], v[148:151], v[204:207], v[20:23]
	v_mfma_f32_16x16x32_bf16 v[12:15], v[156:159], v[204:207], v[12:15]
	v_mfma_f32_16x16x32_bf16 v[60:63], v[152:155], v[184:187], v[60:63]
	v_mfma_f32_16x16x32_bf16 v[56:59], v[160:163], v[184:187], v[56:59]
	v_mfma_f32_16x16x32_bf16 v[52:55], v[152:155], v[192:195], v[52:55]
	v_mfma_f32_16x16x32_bf16 v[44:47], v[160:163], v[192:195], v[44:47]
	v_mfma_f32_16x16x32_bf16 v[36:39], v[152:155], v[200:203], v[36:39]
	v_mfma_f32_16x16x32_bf16 v[28:31], v[160:163], v[200:203], v[28:31]
	v_mfma_f32_16x16x32_bf16 v[20:23], v[152:155], v[208:211], v[20:23]
	v_mfma_f32_16x16x32_bf16 v[12:15], v[160:163], v[208:211], v[12:15]
	s_setprio 0
	s_setprio 1
	v_mfma_f32_16x16x32_bf16 v[48:51], v[164:167], v[180:183], v[48:51]
	v_mfma_f32_16x16x32_bf16 v[40:43], v[172:175], v[180:183], v[40:43]
	v_mfma_f32_16x16x32_bf16 v[32:35], v[164:167], v[188:191], v[32:35]
	v_mfma_f32_16x16x32_bf16 v[24:27], v[172:175], v[188:191], v[24:27]
	v_mfma_f32_16x16x32_bf16 v[16:19], v[164:167], v[196:199], v[16:19]
	v_mfma_f32_16x16x32_bf16 v[8:11], v[172:175], v[196:199], v[8:11]
	v_mfma_f32_16x16x32_bf16 v[4:7], v[164:167], v[204:207], v[4:7]
	v_mfma_f32_16x16x32_bf16 v[0:3], v[172:175], v[204:207], v[0:3]
	v_mfma_f32_16x16x32_bf16 v[48:51], v[168:171], v[184:187], v[48:51]
	v_mfma_f32_16x16x32_bf16 v[40:43], v[176:179], v[184:187], v[40:43]
	v_mfma_f32_16x16x32_bf16 v[32:35], v[168:171], v[192:195], v[32:35]
	v_mfma_f32_16x16x32_bf16 v[24:27], v[176:179], v[192:195], v[24:27]
	v_mfma_f32_16x16x32_bf16 v[16:19], v[168:171], v[200:203], v[16:19]
	v_mfma_f32_16x16x32_bf16 v[8:11], v[176:179], v[200:203], v[8:11]
	v_mfma_f32_16x16x32_bf16 v[4:7], v[168:171], v[208:211], v[4:7]
	v_mfma_f32_16x16x32_bf16 v[0:3], v[176:179], v[208:211], v[0:3]
	s_setprio 0
	s_barrier
	s_add_i32 s87, s87, 2
	s_add_u32 s58, s58, 0x100
	s_addc_u32 s59, s59, 0
	s_add_u32 s85, s85, 0x100
	s_addc_u32 s86, s86, 0
	s_cmp_gt_u32 s87, 29

; #define PG8_STAGE(bufoff, gbase, voff) do { _Pragma("unroll") for (int _i = 0; _i < 2; ++_i) \
;         __builtin_amdgcn_global_load_lds((const unsigned*)((const char*)(gbase) + (voff)[_i]), (PG8_LAS unsigned*)(lds + (bufoff) + ldsw + _i * 8192), 16, 0, 0); } while (0)
; #define PG8_LDA(dst, b, h) do { _Pragma("unroll") for (int m = 0; m < 4; ++m) _Pragma("unroll") for (int k = 0; k < 2; ++k) dst[m][k] = *(const PG8_LAS bf16x8*)(lds + PG8_SA(b, h) + aoff + m * 2048 + k * 1024); } while (0)
; #define PG8_LDB(dst, b, h) do { _Pragma("unroll") for (int n = 0; n < 2; ++n) _Pragma("unroll") for (int k = 0; k < 2; ++k) dst[n][k] = *(const PG8_LAS bf16x8*)(lds + PG8_SB(b, h) + boff + n * 2048 + k * 1024); } while (0)
; #define PG8_WAIT_V(n) asm volatile("s_waitcnt vmcnt(" #n ")" ::: "memory")
; #define PG8_WAIT_L(n) asm volatile("s_waitcnt lgkmcnt(" #n ")" ::: "memory")
; #define PG8_BAR __builtin_amdgcn_s_barrier()
; #define PG8_SCHED __builtin_amdgcn_sched_barrier(0)
; template <class Epi, class Sched, bool ALIGN_EPI = false, bool SP2 = false>
; __device__ __forceinline__ void gemm_phase(PG8_LAS unsigned char* lds, const Gemm g, const Sched& S, const Epi& E) {
;     ...
;         const char* nA = has_next ? (const char*)g.A + (size_t)nxt.pm * tstep : cA; const char* nB = has_next ? (const char*)g.Bt + (size_t)nxt.pn * tstep : cB;
;         for (int t = 0; t < nt; t += 2) {
;             const bool last = (t == nt - 2);
;             const char* a1 = cA + (size_t)(t + 1) * kstep;
;             const char* a2 = last ? nA : cA + (size_t)(t + 2) * kstep; const char* b2 = last ? nB : cB + (size_t)(t + 2) * kstep;
;             const char* a3 = a2 + kstep; const char* b3 = b2 + kstep;
;             if (last && has_next) S.a_ready(nxt);
;             if constexpr (SP2) {
;             PG8_LDB(B0, 0, 0); PG8_LDB(B1, 0, 1); PG8_SCHED; PG8_LDA(At, 0, 0); PG8_STAGE(PG8_SA(1, 1), a1 + hstep, voffA);
;             PG8_WAIT_V(8); PG8_WAIT_L(0); PG8_BAR; PG8_MMA(0, 0, At, B0); PG8_MMA(0, 1, At, B1); PG8_BAR; PG8_SCHED;
;             PG8_LDA(At, 0, 1); PG8_STAGE(PG8_SB(0, 0), b2, voffB); PG8_STAGE(PG8_SB(0, 1), b2 + hstep, voffB); PG8_STAGE(PG8_SA(0, 0), a2, voffA);
;             PG8_WAIT_V(8); PG8_WAIT_L(0); PG8_BAR; PG8_MMA(1, 0, At, B0); PG8_MMA(1, 1, At, B1); PG8_BAR; PG8_SCHED;
.LBB0_258:
	s_add_u32 s75, s48, 0x100
	s_addc_u32 s76, s49, 0
	s_mov_b32 s77, -2
	s_waitcnt lgkmcnt(0)
	ds_read_b128 v[144:147], v151
	ds_read_b128 v[156:159], v151 offset:1024
	ds_read_b128 v[160:163], v151 offset:2048
	ds_read_b128 v[164:167], v151 offset:3072
	ds_read_b128 v[168:171], v152
	ds_read_b128 v[172:175], v152 offset:1024
	ds_read_b128 v[176:179], v152 offset:2048
	ds_read_b128 v[180:183], v152 offset:3072
	s_add_u32 s48, s46, 0x100
	s_addc_u32 s49, s47, 0
	s_cmpk_eq_i32 s77, 0x54
	s_cselect_b32 s55, s1, s49
	s_cselect_b32 s54, s0, s48
	s_cselect_b32 s51, s45, s76
	s_cselect_b32 s50, s44, s75
	v_lshl_add_u64 v[216:217], s[46:47], 0, v[136:137]
	s_add_i32 m0, s59, 0xc000
	ds_read_b128 v[184:187], v153
	ds_read_b128 v[188:191], v153 offset:1024
	ds_read_b128 v[192:195], v153 offset:2048
	ds_read_b128 v[196:199], v153 offset:3072
	ds_read_b128 v[200:203], v153 offset:4096
	ds_read_b128 v[204:207], v153 offset:5120
	ds_read_b128 v[208:211], v153 offset:6144
	ds_read_b128 v[212:215], v153 offset:7168
	global_load_lds_dwordx4 v[216:217], off
	v_lshl_add_u64 v[216:217], s[46:47], 0, v[138:139]
	s_add_i32 m0, s59, 0xe000
	s_nop 0
	global_load_lds_dwordx4 v[216:217], off
	s_waitcnt vmcnt(8)
	s_waitcnt lgkmcnt(0)
	s_barrier
	s_setprio 1
	s_waitcnt lgkmcnt(0)
	v_mfma_f32_16x16x32_bf16 v[124:127], v[144:147], v[184:187], 0
	v_mfma_f32_16x16x32_bf16 v[120:123], v[160:163], v[184:187], 0
	v_mfma_f32_16x16x32_bf16 v[108:111], v[144:147], v[192:195], 0
	v_mfma_f32_16x16x32_bf16 v[104:107], v[160:163], v[192:195], 0
	v_mfma_f32_16x16x32_bf16 v[92:95], v[144:147], v[200:203], 0
	v_mfma_f32_16x16x32_bf16 v[88:91], v[160:163], v[200:203], 0
	v_mfma_f32_16x16x32_bf16 v[76:79], v[144:147], v[208:211], 0
	v_mfma_f32_16x16x32_bf16 v[72:75], v[160:163], v[208:211], 0
	v_mfma_f32_16x16x32_bf16 v[124:127], v[156:159], v[188:191], v[124:127]
	v_mfma_f32_16x16x32_bf16 v[120:123], v[164:167], v[188:191], v[120:123]
	v_mfma_f32_16x16x32_bf16 v[108:111], v[156:159], v[196:199], v[108:111]
	v_mfma_f32_16x16x32_bf16 v[104:107], v[164:167], v[196:199], v[104:107]
	v_mfma_f32_16x16x32_bf16 v[92:95], v[156:159], v[204:207], v[92:95]
	v_mfma_f32_16x16x32_bf16 v[88:91], v[164:167], v[204:207], v[88:91]
	v_mfma_f32_16x16x32_bf16 v[76:79], v[156:159], v[212:215], v[76:79]
	v_mfma_f32_16x16x32_bf16 v[72:75], v[164:167], v[212:215], v[72:75]
	s_setprio 0
	s_setprio 1
	v_mfma_f32_16x16x32_bf16 v[116:119], v[168:171], v[184:187], 0
	v_mfma_f32_16x16x32_bf16 v[112:115], v[176:179], v[184:187], 0
	v_mfma_f32_16x16x32_bf16 v[100:103], v[168:171], v[192:195], 0
	v_mfma_f32_16x16x32_bf16 v[96:99], v[176:179], v[192:195], 0
	v_mfma_f32_16x16x32_bf16 v[84:87], v[168:171], v[200:203], 0
	v_mfma_f32_16x16x32_bf16 v[80:83], v[176:179], v[200:203], 0
	v_mfma_f32_16x16x32_bf16 v[68:71], v[168:171], v[208:211], 0
	v_mfma_f32_16x16x32_bf16 v[64:67], v[176:179], v[208:211], 0
	v_mfma_f32_16x16x32_bf16 v[116:119], v[172:175], v[188:191], v[116:119]
	v_mfma_f32_16x16x32_bf16 v[112:115], v[180:183], v[188:191], v[112:115]
	v_mfma_f32_16x16x32_bf16 v[100:103], v[172:175], v[196:199], v[100:103]
	v_mfma_f32_16x16x32_bf16 v[96:99], v[180:183], v[196:199], v[96:99]
	v_mfma_f32_16x16x32_bf16 v[84:87], v[172:175], v[204:207], v[84:87]
	v_mfma_f32_16x16x32_bf16 v[80:83], v[180:183], v[204:207], v[80:83]
	v_mfma_f32_16x16x32_bf16 v[68:71], v[172:175], v[212:215], v[68:71]
	v_mfma_f32_16x16x32_bf16 v[64:67], v[180:183], v[212:215], v[64:67]
	s_setprio 0
	s_barrier
	s_add_i32 s46, s71, s58
	v_lshl_add_u64 v[216:217], s[50:51], 0, v[130:131]
	s_mov_b32 m0, s46
	ds_read_b128 v[184:187], v153 offset:16384
	ds_read_b128 v[188:191], v153 offset:17408
	ds_read_b128 v[192:195], v153 offset:18432
	ds_read_b128 v[196:199], v153 offset:19456
	ds_read_b128 v[200:203], v153 offset:20480
	ds_read_b128 v[204:207], v153 offset:21504
	ds_read_b128 v[208:211], v153 offset:22528
	ds_read_b128 v[212:215], v153 offset:23552
	global_load_lds_dwordx4 v[216:217], off
	s_add_i32 m0, s46, 0x2000
	s_add_u32 s46, s50, 0x160000
	v_lshl_add_u64 v[220:221], s[50:51], 0, v[134:135]
	s_addc_u32 s47, s51, 0
	s_add_i32 s78, s72, s58
	global_load_lds_dwordx4 v[220:221], off
	v_lshl_add_u64 v[222:223], s[46:47], 0, v[130:131]
	s_mov_b32 m0, s78
	v_lshl_add_u64 v[224:225], s[54:55], 0, v[132:133]
	global_load_lds_dwordx4 v[222:223], off
	v_lshl_add_u64 v[222:223], s[46:47], 0, v[134:135]
	s_add_i32 m0, s78, 0x2000
	s_nop 0
	global_load_lds_dwordx4 v[222:223], off
	v_lshl_add_u64 v[222:223], s[54:55], 0, v[128:129]
	s_mov_b32 m0, s59
	s_nop 0
	global_load_lds_dwordx4 v[222:223], off
	s_mov_b32 m0, s60
	s_nop 0
	global_load_lds_dwordx4 v[224:225], off
	s_waitcnt vmcnt(8)
	s_waitcnt lgkmcnt(0)
	s_barrier
; #define PG8_STAGE(bufoff, gbase, voff) do { _Pragma("unroll") for (int _i = 0; _i < 2; ++_i) \
;         __builtin_amdgcn_global_load_lds((const unsigned*)((const char*)(gbase) + (voff)[_i]), (PG8_LAS unsigned*)(lds + (bufoff) + ldsw + _i * 8192), 16, 0, 0); } while (0)
; #define PG8_LDA(dst, b, h) do { _Pragma("unroll") for (int m = 0; m < 4; ++m) _Pragma("unroll") for (int k = 0; k < 2; ++k) dst[m][k] = *(const PG8_LAS bf16x8*)(lds + PG8_SA(b, h) + aoff + m * 2048 + k * 1024); } while (0)
; #define PG8_LDB(dst, b, h) do { _Pragma("unroll") for (int n = 0; n < 2; ++n) _Pragma("unroll") for (int k = 0; k < 2; ++k) dst[n][k] = *(const PG8_LAS bf16x8*)(lds + PG8_SB(b, h) + boff + n * 2048 + k * 1024); } while (0)
; #define PG8_MMA(ai, bj, At, Bt) do { __builtin_amdgcn_s_setprio(1); _Pragma("unroll") for (int m = 0; m < 4; ++m) _Pragma("unroll") for (int n = 0; n < 2; ++n) _Pragma("unroll") for (int k = 0; k < 2; ++k) \
;         acc[ai][bj][m][n] = __builtin_amdgcn_mfma_f32_16x16x32_bf16(Bt[n][k], At[m][k], acc[ai][bj][m][n], 0, 0, 0); __builtin_amdgcn_s_setprio(0); } while (0)
; #define PG8_WAIT_V(n) asm volatile("s_waitcnt vmcnt(" #n ")" ::: "memory")
; #define PG8_WAIT_L(n) asm volatile("s_waitcnt lgkmcnt(" #n ")" ::: "memory")
; #define PG8_BAR __builtin_amdgcn_s_barrier()
; #define PG8_SCHED __builtin_amdgcn_sched_barrier(0)
; template <class Epi, class Sched, bool ALIGN_EPI = false, bool SP2 = false>
; __device__ __forceinline__ void gemm_phase(PG8_LAS unsigned char* lds, const Gemm g, const Sched& S, const Epi& E) {
;     ...
;             PG8_WAIT_V(8); PG8_WAIT_L(0); PG8_BAR; PG8_MMA(1, 0, At, B0); PG8_MMA(1, 1, At, B1); PG8_BAR; PG8_SCHED;
;             PG8_LDB(B0, 1, 0); PG8_LDB(B1, 1, 1); PG8_SCHED; PG8_LDA(At, 1, 0); PG8_STAGE(PG8_SA(0, 1), a2 + hstep, voffA);
;             PG8_WAIT_V(8); PG8_WAIT_L(0); PG8_BAR; PG8_MMA(0, 0, At, B0); PG8_MMA(0, 1, At, B1); PG8_BAR; PG8_SCHED;
	s_setprio 1
	s_waitcnt lgkmcnt(0)
	v_mfma_f32_16x16x32_bf16 v[60:63], v[144:147], v[184:187], 0
	v_mfma_f32_16x16x32_bf16 v[56:59], v[160:163], v[184:187], 0
	v_mfma_f32_16x16x32_bf16 v[44:47], v[144:147], v[192:195], 0
	v_mfma_f32_16x16x32_bf16 v[40:43], v[160:163], v[192:195], 0
	v_mfma_f32_16x16x32_bf16 v[28:31], v[144:147], v[200:203], 0
	v_mfma_f32_16x16x32_bf16 v[24:27], v[160:163], v[200:203], 0
	v_mfma_f32_16x16x32_bf16 v[12:15], v[144:147], v[208:211], 0
	v_mfma_f32_16x16x32_bf16 v[8:11], v[160:163], v[208:211], 0
	v_mfma_f32_16x16x32_bf16 v[60:63], v[156:159], v[188:191], v[60:63]
	v_mfma_f32_16x16x32_bf16 v[56:59], v[164:167], v[188:191], v[56:59]
	v_mfma_f32_16x16x32_bf16 v[44:47], v[156:159], v[196:199], v[44:47]
	v_mfma_f32_16x16x32_bf16 v[40:43], v[164:167], v[196:199], v[40:43]
	v_mfma_f32_16x16x32_bf16 v[28:31], v[156:159], v[204:207], v[28:31]
	v_mfma_f32_16x16x32_bf16 v[24:27], v[164:167], v[204:207], v[24:27]
	v_mfma_f32_16x16x32_bf16 v[12:15], v[156:159], v[212:215], v[12:15]
	v_mfma_f32_16x16x32_bf16 v[8:11], v[164:167], v[212:215], v[8:11]
	s_setprio 0
	s_setprio 1
	v_mfma_f32_16x16x32_bf16 v[52:55], v[168:171], v[184:187], 0
	v_mfma_f32_16x16x32_bf16 v[48:51], v[176:179], v[184:187], 0
	v_mfma_f32_16x16x32_bf16 v[36:39], v[168:171], v[192:195], 0
	v_mfma_f32_16x16x32_bf16 v[32:35], v[176:179], v[192:195], 0
	v_mfma_f32_16x16x32_bf16 v[20:23], v[168:171], v[200:203], 0
	v_mfma_f32_16x16x32_bf16 v[16:19], v[176:179], v[200:203], 0
	v_mfma_f32_16x16x32_bf16 v[4:7], v[168:171], v[208:211], 0
	v_mfma_f32_16x16x32_bf16 v[0:3], v[176:179], v[208:211], 0
	v_mfma_f32_16x16x32_bf16 v[52:55], v[172:175], v[188:191], v[52:55]
	v_mfma_f32_16x16x32_bf16 v[48:51], v[180:183], v[188:191], v[48:51]
	v_mfma_f32_16x16x32_bf16 v[36:39], v[172:175], v[196:199], v[36:39]
	v_mfma_f32_16x16x32_bf16 v[32:35], v[180:183], v[196:199], v[32:35]
	v_mfma_f32_16x16x32_bf16 v[20:23], v[172:175], v[204:207], v[20:23]
	v_mfma_f32_16x16x32_bf16 v[16:19], v[180:183], v[204:207], v[16:19]
	v_mfma_f32_16x16x32_bf16 v[4:7], v[172:175], v[212:215], v[4:7]
	v_mfma_f32_16x16x32_bf16 v[0:3], v[180:183], v[212:215], v[0:3]
	s_setprio 0
	s_barrier
	s_add_i32 s78, 0, 0x18000
	v_add_u32_e32 v155, s78, v149
	s_add_i32 s79, 0, 0x1c000
	ds_read_b128 v[144:147], v155
	ds_read_b128 v[156:159], v155 offset:1024
	ds_read_b128 v[160:163], v155 offset:2048
	ds_read_b128 v[164:167], v155 offset:3072
	v_add_u32_e32 v155, s79, v149
	ds_read_b128 v[168:171], v155
	ds_read_b128 v[172:175], v155 offset:1024
	ds_read_b128 v[176:179], v155 offset:2048
	ds_read_b128 v[180:183], v155 offset:3072
	s_add_u32 s46, s54, 0x160000
	s_addc_u32 s47, s55, 0
	s_mov_b32 m0, s61
	v_lshl_add_u64 v[226:227], s[46:47], 0, v[128:129]
	ds_read_b128 v[184:187], v153 offset:32768
	ds_read_b128 v[188:191], v153 offset:33792
	ds_read_b128 v[192:195], v153 offset:34816
	ds_read_b128 v[196:199], v153 offset:35840
	ds_read_b128 v[200:203], v153 offset:36864
	ds_read_b128 v[204:207], v153 offset:37888
	ds_read_b128 v[208:211], v153 offset:38912
	ds_read_b128 v[212:215], v153 offset:39936
	global_load_lds_dwordx4 v[226:227], off
	v_lshl_add_u64 v[226:227], s[46:47], 0, v[132:133]
	s_mov_b32 m0, s62
	s_nop 0
	global_load_lds_dwordx4 v[226:227], off
	s_waitcnt vmcnt(8)
	s_waitcnt lgkmcnt(0)
	s_barrier
	s_setprio 1
	s_waitcnt lgkmcnt(0)
	v_mfma_f32_16x16x32_bf16 v[124:127], v[144:147], v[184:187], v[124:127]
	v_mfma_f32_16x16x32_bf16 v[120:123], v[160:163], v[184:187], v[120:123]
	v_mfma_f32_16x16x32_bf16 v[108:111], v[144:147], v[192:195], v[108:111]
	v_mfma_f32_16x16x32_bf16 v[104:107], v[160:163], v[192:195], v[104:107]
	v_mfma_f32_16x16x32_bf16 v[92:95], v[144:147], v[200:203], v[92:95]
	v_mfma_f32_16x16x32_bf16 v[88:91], v[160:163], v[200:203], v[88:91]
	v_mfma_f32_16x16x32_bf16 v[76:79], v[144:147], v[208:211], v[76:79]
	v_mfma_f32_16x16x32_bf16 v[72:75], v[160:163], v[208:211], v[72:75]
	v_mfma_f32_16x16x32_bf16 v[124:127], v[156:159], v[188:191], v[124:127]
	v_mfma_f32_16x16x32_bf16 v[120:123], v[164:167], v[188:191], v[120:123]
	v_mfma_f32_16x16x32_bf16 v[108:111], v[156:159], v[196:199], v[108:111]
	v_mfma_f32_16x16x32_bf16 v[104:107], v[164:167], v[196:199], v[104:107]
	v_mfma_f32_16x16x32_bf16 v[92:95], v[156:159], v[204:207], v[92:95]
	v_mfma_f32_16x16x32_bf16 v[88:91], v[164:167], v[204:207], v[88:91]
	v_mfma_f32_16x16x32_bf16 v[76:79], v[156:159], v[212:215], v[76:79]
	v_mfma_f32_16x16x32_bf16 v[72:75], v[164:167], v[212:215], v[72:75]
	s_setprio 0
	s_setprio 1
	v_mfma_f32_16x16x32_bf16 v[116:119], v[168:171], v[184:187], v[116:119]
	v_mfma_f32_16x16x32_bf16 v[112:115], v[176:179], v[184:187], v[112:115]
	v_mfma_f32_16x16x32_bf16 v[100:103], v[168:171], v[192:195], v[100:103]
	v_mfma_f32_16x16x32_bf16 v[96:99], v[176:179], v[192:195], v[96:99]
	v_mfma_f32_16x16x32_bf16 v[84:87], v[168:171], v[200:203], v[84:87]
	v_mfma_f32_16x16x32_bf16 v[80:83], v[176:179], v[200:203], v[80:83]
	v_mfma_f32_16x16x32_bf16 v[68:71], v[168:171], v[208:211], v[68:71]
	v_mfma_f32_16x16x32_bf16 v[64:67], v[176:179], v[208:211], v[64:67]
	v_mfma_f32_16x16x32_bf16 v[116:119], v[172:175], v[188:191], v[116:119]
	v_mfma_f32_16x16x32_bf16 v[112:115], v[180:183], v[188:191], v[112:115]
	v_mfma_f32_16x16x32_bf16 v[100:103], v[172:175], v[196:199], v[100:103]
	v_mfma_f32_16x16x32_bf16 v[96:99], v[180:183], v[196:199], v[96:99]
	v_mfma_f32_16x16x32_bf16 v[84:87], v[172:175], v[204:207], v[84:87]
	v_mfma_f32_16x16x32_bf16 v[80:83], v[180:183], v[204:207], v[80:83]
	v_mfma_f32_16x16x32_bf16 v[68:71], v[172:175], v[212:215], v[68:71]
	v_mfma_f32_16x16x32_bf16 v[64:67], v[180:183], v[212:215], v[64:67]
	s_setprio 0
	s_barrier
; #define PG8_STAGE(bufoff, gbase, voff) do { _Pragma("unroll") for (int _i = 0; _i < 2; ++_i) \
;         __builtin_amdgcn_global_load_lds((const unsigned*)((const char*)(gbase) + (voff)[_i]), (PG8_LAS unsigned*)(lds + (bufoff) + ldsw + _i * 8192), 16, 0, 0); } while (0)
; #define PG8_LDA(dst, b, h) do { _Pragma("unroll") for (int m = 0; m < 4; ++m) _Pragma("unroll") for (int k = 0; k < 2; ++k) dst[m][k] = *(const PG8_LAS bf16x8*)(lds + PG8_SA(b, h) + aoff + m * 2048 + k * 1024); } while (0)
; #define PG8_MMA(ai, bj, At, Bt) do { __builtin_amdgcn_s_setprio(1); _Pragma("unroll") for (int m = 0; m < 4; ++m) _Pragma("unroll") for (int n = 0; n < 2; ++n) _Pragma("unroll") for (int k = 0; k < 2; ++k) \
;         acc[ai][bj][m][n] = __builtin_amdgcn_mfma_f32_16x16x32_bf16(Bt[n][k], At[m][k], acc[ai][bj][m][n], 0, 0, 0); __builtin_amdgcn_s_setprio(0); } while (0)
; #define PG8_WAIT_V(n) asm volatile("s_waitcnt vmcnt(" #n ")" ::: "memory")
; #define PG8_WAIT_L(n) asm volatile("s_waitcnt lgkmcnt(" #n ")" ::: "memory")
; #define PG8_BAR __builtin_amdgcn_s_barrier()
; #define PG8_SCHED __builtin_amdgcn_sched_barrier(0)
; template <class Epi, class Sched, bool ALIGN_EPI = false, bool SP2 = false>
; __device__ __forceinline__ void gemm_phase(PG8_LAS unsigned char* lds, const Gemm g, const Sched& S, const Epi& E) {
;     ...
;             PG8_LDA(At, 1, 1); PG8_STAGE(PG8_SB(1, 0), b3, voffB); PG8_STAGE(PG8_SB(1, 1), b3 + hstep, voffB); PG8_STAGE(PG8_SA(1, 0), a3, voffA);
;             PG8_WAIT_V(8); PG8_WAIT_L(0); PG8_BAR; PG8_MMA(1, 0, At, B0); PG8_MMA(1, 1, At, B1); PG8_BAR; PG8_SCHED;
	s_add_i32 s46, s78, s58
	v_lshl_add_u64 v[216:217], v[216:217], 0, s[20:21]
	s_mov_b32 m0, s46
	ds_read_b128 v[184:187], v153 offset:49152
	ds_read_b128 v[188:191], v153 offset:50176
	ds_read_b128 v[192:195], v153 offset:51200
	ds_read_b128 v[196:199], v153 offset:52224
	ds_read_b128 v[200:203], v153 offset:53248
	ds_read_b128 v[204:207], v153 offset:54272
	ds_read_b128 v[208:211], v153 offset:55296
	ds_read_b128 v[212:215], v153 offset:56320
	global_load_lds_dwordx4 v[216:217], off
	s_add_i32 m0, s46, 0x2000
	s_add_u32 s46, s50, 0x160080
	v_lshl_add_u64 v[216:217], v[220:221], 0, s[20:21]
	s_addc_u32 s47, s51, 0
	s_add_i32 s50, s79, s58
	global_load_lds_dwordx4 v[216:217], off
	v_lshl_add_u64 v[216:217], s[46:47], 0, v[130:131]
	s_mov_b32 m0, s50
	s_nop 0
	global_load_lds_dwordx4 v[216:217], off
	v_lshl_add_u64 v[216:217], s[46:47], 0, v[134:135]
	s_add_i32 m0, s50, 0x2000
	s_nop 0
	global_load_lds_dwordx4 v[216:217], off
	v_lshl_add_u64 v[216:217], v[222:223], 0, s[20:21]
	s_mov_b32 m0, s64
	s_nop 0
	global_load_lds_dwordx4 v[216:217], off
	v_lshl_add_u64 v[216:217], v[224:225], 0, s[20:21]
	s_mov_b32 m0, s65
	s_nop 0
	global_load_lds_dwordx4 v[216:217], off
	s_waitcnt vmcnt(8)
	s_waitcnt lgkmcnt(0)
	s_barrier
	s_setprio 1
	s_waitcnt lgkmcnt(0)
	v_mfma_f32_16x16x32_bf16 v[60:63], v[144:147], v[184:187], v[60:63]
	v_mfma_f32_16x16x32_bf16 v[56:59], v[160:163], v[184:187], v[56:59]
	v_mfma_f32_16x16x32_bf16 v[44:47], v[144:147], v[192:195], v[44:47]
	v_mfma_f32_16x16x32_bf16 v[40:43], v[160:163], v[192:195], v[40:43]
	v_mfma_f32_16x16x32_bf16 v[28:31], v[144:147], v[200:203], v[28:31]
	v_mfma_f32_16x16x32_bf16 v[24:27], v[160:163], v[200:203], v[24:27]
	v_mfma_f32_16x16x32_bf16 v[12:15], v[144:147], v[208:211], v[12:15]
	v_mfma_f32_16x16x32_bf16 v[8:11], v[160:163], v[208:211], v[8:11]
	v_mfma_f32_16x16x32_bf16 v[60:63], v[156:159], v[188:191], v[60:63]
	v_mfma_f32_16x16x32_bf16 v[56:59], v[164:167], v[188:191], v[56:59]
	v_mfma_f32_16x16x32_bf16 v[44:47], v[156:159], v[196:199], v[44:47]
	v_mfma_f32_16x16x32_bf16 v[40:43], v[164:167], v[196:199], v[40:43]
	v_mfma_f32_16x16x32_bf16 v[28:31], v[156:159], v[204:207], v[28:31]
	v_mfma_f32_16x16x32_bf16 v[24:27], v[164:167], v[204:207], v[24:27]
	v_mfma_f32_16x16x32_bf16 v[12:15], v[156:159], v[212:215], v[12:15]
	v_mfma_f32_16x16x32_bf16 v[8:11], v[164:167], v[212:215], v[8:11]
	s_setprio 0
	s_setprio 1
	v_mfma_f32_16x16x32_bf16 v[52:55], v[168:171], v[184:187], v[52:55]
	v_mfma_f32_16x16x32_bf16 v[48:51], v[176:179], v[184:187], v[48:51]
	v_mfma_f32_16x16x32_bf16 v[36:39], v[168:171], v[192:195], v[36:39]
	v_mfma_f32_16x16x32_bf16 v[32:35], v[176:179], v[192:195], v[32:35]
	v_mfma_f32_16x16x32_bf16 v[20:23], v[168:171], v[200:203], v[20:23]
	v_mfma_f32_16x16x32_bf16 v[16:19], v[176:179], v[200:203], v[16:19]
	v_mfma_f32_16x16x32_bf16 v[4:7], v[168:171], v[208:211], v[4:7]
	v_mfma_f32_16x16x32_bf16 v[0:3], v[176:179], v[208:211], v[0:3]
	v_mfma_f32_16x16x32_bf16 v[52:55], v[172:175], v[188:191], v[52:55]
	v_mfma_f32_16x16x32_bf16 v[48:51], v[180:183], v[188:191], v[48:51]
	v_mfma_f32_16x16x32_bf16 v[36:39], v[172:175], v[196:199], v[36:39]
	v_mfma_f32_16x16x32_bf16 v[32:35], v[180:183], v[196:199], v[32:35]
	v_mfma_f32_16x16x32_bf16 v[20:23], v[172:175], v[204:207], v[20:23]
	v_mfma_f32_16x16x32_bf16 v[16:19], v[180:183], v[204:207], v[16:19]
	v_mfma_f32_16x16x32_bf16 v[4:7], v[172:175], v[212:215], v[4:7]
	v_mfma_f32_16x16x32_bf16 v[0:3], v[180:183], v[212:215], v[0:3]
	s_setprio 0
	s_barrier
	s_add_i32 s77, s77, 2
	s_add_u32 s75, s75, 0x100
	s_addc_u32 s76, s76, 0
	s_cmpk_gt_u32 s77, 0x55
	s_mov_b64 s[46:47], s[48:49]

; #define PG8_STAGE(bufoff, gbase, voff) do { _Pragma("unroll") for (int _i = 0; _i < 2; ++_i) \
;         __builtin_amdgcn_global_load_lds((const unsigned*)((const char*)(gbase) + (voff)[_i]), (PG8_LAS unsigned*)(lds + (bufoff) + ldsw + _i * 8192), 16, 0, 0); } while (0)
; #define PG8_LDA(dst, b, h) do { _Pragma("unroll") for (int m = 0; m < 4; ++m) _Pragma("unroll") for (int k = 0; k < 2; ++k) dst[m][k] = *(const PG8_LAS bf16x8*)(lds + PG8_SA(b, h) + aoff + m * 2048 + k * 1024); } while (0)
; #define PG8_LDB(dst, b, h) do { _Pragma("unroll") for (int n = 0; n < 2; ++n) _Pragma("unroll") for (int k = 0; k < 2; ++k) dst[n][k] = *(const PG8_LAS bf16x8*)(lds + PG8_SB(b, h) + boff + n * 2048 + k * 1024); } while (0)
; #define PG8_WAIT_V(n) asm volatile("s_waitcnt vmcnt(" #n ")" ::: "memory")
; #define PG8_WAIT_L(n) asm volatile("s_waitcnt lgkmcnt(" #n ")" ::: "memory")
; #define PG8_BAR __builtin_amdgcn_s_barrier()
; #define PG8_SCHED __builtin_amdgcn_sched_barrier(0)
; template <class Epi, class Sched, bool ALIGN_EPI = false, bool SP2 = false>
; __device__ __forceinline__ void gemm_phase(PG8_LAS unsigned char* lds, const Gemm g, const Sched& S, const Epi& E) {
;     ...
;         const char* nA = has_next ? (const char*)g.A + (size_t)nxt.pm * tstep : cA; const char* nB = has_next ? (const char*)g.Bt + (size_t)nxt.pn * tstep : cB;
;         for (int t = 0; t < nt; t += 2) {
;             const bool last = (t == nt - 2);
;             const char* a1 = cA + (size_t)(t + 1) * kstep;
;             const char* a2 = last ? nA : cA + (size_t)(t + 2) * kstep; const char* b2 = last ? nB : cB + (size_t)(t + 2) * kstep;
;             const char* a3 = a2 + kstep; const char* b3 = b2 + kstep;
;             if (last && has_next) S.a_ready(nxt);
;             if constexpr (SP2) {
;             PG8_LDB(B0, 0, 0); PG8_LDB(B1, 0, 1); PG8_SCHED; PG8_LDA(At, 0, 0); PG8_STAGE(PG8_SA(1, 1), a1 + hstep, voffA);
;             PG8_WAIT_V(8); PG8_WAIT_L(0); PG8_BAR; PG8_MMA(0, 0, At, B0); PG8_MMA(0, 1, At, B1); PG8_BAR; PG8_SCHED;
;             PG8_LDA(At, 0, 1); PG8_STAGE(PG8_SB(0, 0), b2, voffB); PG8_STAGE(PG8_SB(0, 1), b2 + hstep, voffB); PG8_STAGE(PG8_SA(0, 0), a2, voffA);
;             PG8_WAIT_V(8); PG8_WAIT_L(0); PG8_BAR; PG8_MMA(1, 0, At, B0); PG8_MMA(1, 1, At, B1); PG8_BAR; PG8_SCHED;
.LBB0_345:
	s_ashr_i32 s45, s44, 31
	s_lshl_b64 s[46:47], s[44:45], 20
	s_add_u32 s46, s31, s46
	s_addc_u32 s47, s35, s47
	s_and_b64 s[48:49], s[2:3], exec
	s_cselect_b32 s45, s47, s51
	s_cselect_b32 s74, s46, s50
	s_ashr_i32 s43, s42, 31
	s_lshl_b64 s[48:49], s[42:43], 20
	s_add_u32 s48, s56, s48
	s_addc_u32 s49, s57, s49
	s_and_b64 s[54:55], s[2:3], exec
	s_cselect_b32 s43, s49, s53
	s_cselect_b32 s75, s48, s52
	s_add_u32 s50, s50, 0x80080
	s_addc_u32 s51, s51, 0
	s_add_u32 s76, s52, 0x100
	s_addc_u32 s77, s53, 0
	s_mov_b32 s78, -2
	ds_read_b128 v[144:147], v155
	ds_read_b128 v[148:151], v155 offset:1024
	ds_read_b128 v[160:163], v155 offset:2048
	ds_read_b128 v[164:167], v155 offset:3072
	ds_read_b128 v[168:171], v156
	ds_read_b128 v[172:175], v156 offset:1024
	ds_read_b128 v[176:179], v156 offset:2048
	ds_read_b128 v[180:183], v156 offset:3072
	s_add_u32 s52, s50, 0xfff80080
	s_addc_u32 s53, s51, -1
	s_cmp_eq_u32 s78, 28
	s_cselect_b32 s55, s45, s53
	s_cselect_b32 s54, s74, s52
	s_cselect_b32 s53, s43, s77
	s_cselect_b32 s52, s75, s76
	v_lshl_add_u64 v[216:217], s[50:51], 0, v[136:137]
	s_add_i32 m0, s28, 0xc000
	ds_read_b128 v[184:187], v157
	ds_read_b128 v[188:191], v157 offset:1024
	ds_read_b128 v[192:195], v157 offset:2048
	ds_read_b128 v[196:199], v157 offset:3072
	ds_read_b128 v[200:203], v157 offset:4096
	ds_read_b128 v[204:207], v157 offset:5120
	ds_read_b128 v[208:211], v157 offset:6144
	ds_read_b128 v[212:215], v157 offset:7168
	global_load_lds_dwordx4 v[216:217], off
	v_lshl_add_u64 v[216:217], s[50:51], 0, v[138:139]
	s_add_i32 m0, s28, 0xe000
	s_nop 0
	global_load_lds_dwordx4 v[216:217], off
	s_waitcnt vmcnt(8)
	s_waitcnt lgkmcnt(0)
	s_barrier
	s_setprio 1
	s_waitcnt lgkmcnt(0)
	v_mfma_f32_16x16x32_bf16 v[124:127], v[144:147], v[184:187], 0
	v_mfma_f32_16x16x32_bf16 v[120:123], v[160:163], v[184:187], 0
	v_mfma_f32_16x16x32_bf16 v[108:111], v[144:147], v[192:195], 0
	v_mfma_f32_16x16x32_bf16 v[104:107], v[160:163], v[192:195], 0
	v_mfma_f32_16x16x32_bf16 v[92:95], v[144:147], v[200:203], 0
	v_mfma_f32_16x16x32_bf16 v[88:91], v[160:163], v[200:203], 0
	v_mfma_f32_16x16x32_bf16 v[76:79], v[144:147], v[208:211], 0
	v_mfma_f32_16x16x32_bf16 v[72:75], v[160:163], v[208:211], 0
	v_mfma_f32_16x16x32_bf16 v[124:127], v[148:151], v[188:191], v[124:127]
	v_mfma_f32_16x16x32_bf16 v[120:123], v[164:167], v[188:191], v[120:123]
	v_mfma_f32_16x16x32_bf16 v[108:111], v[148:151], v[196:199], v[108:111]
	v_mfma_f32_16x16x32_bf16 v[104:107], v[164:167], v[196:199], v[104:107]
	v_mfma_f32_16x16x32_bf16 v[92:95], v[148:151], v[204:207], v[92:95]
	v_mfma_f32_16x16x32_bf16 v[88:91], v[164:167], v[204:207], v[88:91]
	v_mfma_f32_16x16x32_bf16 v[76:79], v[148:151], v[212:215], v[76:79]
	v_mfma_f32_16x16x32_bf16 v[72:75], v[164:167], v[212:215], v[72:75]
	s_setprio 0
	s_setprio 1
	v_mfma_f32_16x16x32_bf16 v[116:119], v[168:171], v[184:187], 0
	v_mfma_f32_16x16x32_bf16 v[112:115], v[176:179], v[184:187], 0
	v_mfma_f32_16x16x32_bf16 v[100:103], v[168:171], v[192:195], 0
	v_mfma_f32_16x16x32_bf16 v[96:99], v[176:179], v[192:195], 0
	v_mfma_f32_16x16x32_bf16 v[84:87], v[168:171], v[200:203], 0
	v_mfma_f32_16x16x32_bf16 v[80:83], v[176:179], v[200:203], 0
	v_mfma_f32_16x16x32_bf16 v[68:71], v[168:171], v[208:211], 0
	v_mfma_f32_16x16x32_bf16 v[64:67], v[176:179], v[208:211], 0
	v_mfma_f32_16x16x32_bf16 v[116:119], v[172:175], v[188:191], v[116:119]
	v_mfma_f32_16x16x32_bf16 v[112:115], v[180:183], v[188:191], v[112:115]
	v_mfma_f32_16x16x32_bf16 v[100:103], v[172:175], v[196:199], v[100:103]
	v_mfma_f32_16x16x32_bf16 v[96:99], v[180:183], v[196:199], v[96:99]
	v_mfma_f32_16x16x32_bf16 v[84:87], v[172:175], v[204:207], v[84:87]
	v_mfma_f32_16x16x32_bf16 v[80:83], v[180:183], v[204:207], v[80:83]
	v_mfma_f32_16x16x32_bf16 v[68:71], v[172:175], v[212:215], v[68:71]
	v_mfma_f32_16x16x32_bf16 v[64:67], v[180:183], v[212:215], v[64:67]
	s_setprio 0
	s_barrier
	s_add_i32 s79, s67, s58
	v_lshl_add_u64 v[216:217], s[52:53], 0, v[132:133]
	s_mov_b32 m0, s79
	ds_read_b128 v[184:187], v157 offset:16384
	ds_read_b128 v[188:191], v157 offset:17408
	ds_read_b128 v[192:195], v157 offset:18432
	ds_read_b128 v[196:199], v157 offset:19456
	ds_read_b128 v[200:203], v157 offset:20480
	ds_read_b128 v[204:207], v157 offset:21504
	ds_read_b128 v[208:211], v157 offset:22528
	ds_read_b128 v[212:215], v157 offset:23552
	global_load_lds_dwordx4 v[216:217], off
	s_add_i32 m0, s79, 0x2000
	s_add_u32 s80, s52, 0x80000
	v_lshl_add_u64 v[220:221], s[52:53], 0, v[128:129]
	s_addc_u32 s81, s53, 0
	s_add_i32 s79, s71, s58
	global_load_lds_dwordx4 v[220:221], off
	v_lshl_add_u64 v[222:223], s[80:81], 0, v[132:133]
	s_mov_b32 m0, s79
	v_lshl_add_u64 v[224:225], s[54:55], 0, v[130:131]
	global_load_lds_dwordx4 v[222:223], off
	v_lshl_add_u64 v[222:223], s[80:81], 0, v[128:129]
	s_add_i32 m0, s79, 0x2000
	s_nop 0
	global_load_lds_dwordx4 v[222:223], off
	v_lshl_add_u64 v[222:223], s[54:55], 0, v[134:135]
	s_mov_b32 m0, s28
	s_nop 0
	global_load_lds_dwordx4 v[222:223], off
	s_mov_b32 m0, s29
	s_nop 0
	global_load_lds_dwordx4 v[224:225], off
	s_waitcnt vmcnt(8)
	s_waitcnt lgkmcnt(0)
	s_barrier
; #define PG8_STAGE(bufoff, gbase, voff) do { _Pragma("unroll") for (int _i = 0; _i < 2; ++_i) \
;         __builtin_amdgcn_global_load_lds((const unsigned*)((const char*)(gbase) + (voff)[_i]), (PG8_LAS unsigned*)(lds + (bufoff) + ldsw + _i * 8192), 16, 0, 0); } while (0)
; #define PG8_LDA(dst, b, h) do { _Pragma("unroll") for (int m = 0; m < 4; ++m) _Pragma("unroll") for (int k = 0; k < 2; ++k) dst[m][k] = *(const PG8_LAS bf16x8*)(lds + PG8_SA(b, h) + aoff + m * 2048 + k * 1024); } while (0)
; #define PG8_LDB(dst, b, h) do { _Pragma("unroll") for (int n = 0; n < 2; ++n) _Pragma("unroll") for (int k = 0; k < 2; ++k) dst[n][k] = *(const PG8_LAS bf16x8*)(lds + PG8_SB(b, h) + boff + n * 2048 + k * 1024); } while (0)
; #define PG8_MMA(ai, bj, At, Bt) do { __builtin_amdgcn_s_setprio(1); _Pragma("unroll") for (int m = 0; m < 4; ++m) _Pragma("unroll") for (int n = 0; n < 2; ++n) _Pragma("unroll") for (int k = 0; k < 2; ++k) \
;         acc[ai][bj][m][n] = __builtin_amdgcn_mfma_f32_16x16x32_bf16(Bt[n][k], At[m][k], acc[ai][bj][m][n], 0, 0, 0); __builtin_amdgcn_s_setprio(0); } while (0)
; #define PG8_WAIT_V(n) asm volatile("s_waitcnt vmcnt(" #n ")" ::: "memory")
; #define PG8_WAIT_L(n) asm volatile("s_waitcnt lgkmcnt(" #n ")" ::: "memory")
; #define PG8_BAR __builtin_amdgcn_s_barrier()
; #define PG8_SCHED __builtin_amdgcn_sched_barrier(0)
; template <class Epi, class Sched, bool ALIGN_EPI = false, bool SP2 = false>
; __device__ __forceinline__ void gemm_phase(PG8_LAS unsigned char* lds, const Gemm g, const Sched& S, const Epi& E) {
;     ...
;             PG8_WAIT_V(8); PG8_WAIT_L(0); PG8_BAR; PG8_MMA(1, 0, At, B0); PG8_MMA(1, 1, At, B1); PG8_BAR; PG8_SCHED;
;             PG8_LDB(B0, 1, 0); PG8_LDB(B1, 1, 1); PG8_SCHED; PG8_LDA(At, 1, 0); PG8_STAGE(PG8_SA(0, 1), a2 + hstep, voffA);
;             PG8_WAIT_V(8); PG8_WAIT_L(0); PG8_BAR; PG8_MMA(0, 0, At, B0); PG8_MMA(0, 1, At, B1); PG8_BAR; PG8_SCHED;
	s_setprio 1
	s_waitcnt lgkmcnt(0)
	v_mfma_f32_16x16x32_bf16 v[60:63], v[144:147], v[184:187], 0
	v_mfma_f32_16x16x32_bf16 v[56:59], v[160:163], v[184:187], 0
	v_mfma_f32_16x16x32_bf16 v[44:47], v[144:147], v[192:195], 0
	v_mfma_f32_16x16x32_bf16 v[40:43], v[160:163], v[192:195], 0
	v_mfma_f32_16x16x32_bf16 v[28:31], v[144:147], v[200:203], 0
	v_mfma_f32_16x16x32_bf16 v[24:27], v[160:163], v[200:203], 0
	v_mfma_f32_16x16x32_bf16 v[12:15], v[144:147], v[208:211], 0
	v_mfma_f32_16x16x32_bf16 v[8:11], v[160:163], v[208:211], 0
	v_mfma_f32_16x16x32_bf16 v[60:63], v[148:151], v[188:191], v[60:63]
	v_mfma_f32_16x16x32_bf16 v[56:59], v[164:167], v[188:191], v[56:59]
	v_mfma_f32_16x16x32_bf16 v[44:47], v[148:151], v[196:199], v[44:47]
	v_mfma_f32_16x16x32_bf16 v[40:43], v[164:167], v[196:199], v[40:43]
	v_mfma_f32_16x16x32_bf16 v[28:31], v[148:151], v[204:207], v[28:31]
	v_mfma_f32_16x16x32_bf16 v[24:27], v[164:167], v[204:207], v[24:27]
	v_mfma_f32_16x16x32_bf16 v[12:15], v[148:151], v[212:215], v[12:15]
	v_mfma_f32_16x16x32_bf16 v[8:11], v[164:167], v[212:215], v[8:11]
	s_setprio 0
	s_setprio 1
	v_mfma_f32_16x16x32_bf16 v[52:55], v[168:171], v[184:187], 0
	v_mfma_f32_16x16x32_bf16 v[48:51], v[176:179], v[184:187], 0
	v_mfma_f32_16x16x32_bf16 v[36:39], v[168:171], v[192:195], 0
	v_mfma_f32_16x16x32_bf16 v[32:35], v[176:179], v[192:195], 0
	v_mfma_f32_16x16x32_bf16 v[20:23], v[168:171], v[200:203], 0
	v_mfma_f32_16x16x32_bf16 v[16:19], v[176:179], v[200:203], 0
	v_mfma_f32_16x16x32_bf16 v[4:7], v[168:171], v[208:211], 0
	v_mfma_f32_16x16x32_bf16 v[0:3], v[176:179], v[208:211], 0
	v_mfma_f32_16x16x32_bf16 v[52:55], v[172:175], v[188:191], v[52:55]
	v_mfma_f32_16x16x32_bf16 v[48:51], v[180:183], v[188:191], v[48:51]
	v_mfma_f32_16x16x32_bf16 v[36:39], v[172:175], v[196:199], v[36:39]
	v_mfma_f32_16x16x32_bf16 v[32:35], v[180:183], v[196:199], v[32:35]
	v_mfma_f32_16x16x32_bf16 v[20:23], v[172:175], v[204:207], v[20:23]
	v_mfma_f32_16x16x32_bf16 v[16:19], v[180:183], v[204:207], v[16:19]
	v_mfma_f32_16x16x32_bf16 v[4:7], v[172:175], v[212:215], v[4:7]
	v_mfma_f32_16x16x32_bf16 v[0:3], v[180:183], v[212:215], v[0:3]
	s_setprio 0
	s_barrier
	s_add_i32 s79, 0, 0x18000
	s_add_i32 s80, 0, 0x1c000
	v_add_u32_e32 v164, s79, v153
	v_add_u32_e32 v180, s80, v153
	ds_read_b128 v[144:147], v164
	ds_read_b128 v[148:151], v164 offset:1024
	ds_read_b128 v[160:163], v164 offset:2048
	ds_read_b128 v[164:167], v164 offset:3072
	ds_read_b128 v[168:171], v180
	ds_read_b128 v[172:175], v180 offset:1024
	ds_read_b128 v[176:179], v180 offset:2048
	ds_read_b128 v[180:183], v180 offset:3072
	s_add_u32 s54, s54, 0x80000
	s_addc_u32 s55, s55, 0
	s_mov_b32 m0, s61
	v_lshl_add_u64 v[226:227], s[54:55], 0, v[134:135]
	ds_read_b128 v[184:187], v157 offset:32768
	ds_read_b128 v[188:191], v157 offset:33792
	ds_read_b128 v[192:195], v157 offset:34816
	ds_read_b128 v[196:199], v157 offset:35840
	ds_read_b128 v[200:203], v157 offset:36864
	ds_read_b128 v[204:207], v157 offset:37888
	ds_read_b128 v[208:211], v157 offset:38912
	ds_read_b128 v[212:215], v157 offset:39936
	global_load_lds_dwordx4 v[226:227], off
	v_lshl_add_u64 v[226:227], s[54:55], 0, v[130:131]
	s_mov_b32 m0, s62
	s_nop 0
	global_load_lds_dwordx4 v[226:227], off
	s_waitcnt vmcnt(8)
	s_waitcnt lgkmcnt(0)
	s_barrier
	s_setprio 1
	s_waitcnt lgkmcnt(0)
	v_mfma_f32_16x16x32_bf16 v[124:127], v[144:147], v[184:187], v[124:127]
	v_mfma_f32_16x16x32_bf16 v[120:123], v[160:163], v[184:187], v[120:123]
	v_mfma_f32_16x16x32_bf16 v[108:111], v[144:147], v[192:195], v[108:111]
	v_mfma_f32_16x16x32_bf16 v[104:107], v[160:163], v[192:195], v[104:107]
	v_mfma_f32_16x16x32_bf16 v[92:95], v[144:147], v[200:203], v[92:95]
	v_mfma_f32_16x16x32_bf16 v[88:91], v[160:163], v[200:203], v[88:91]
	v_mfma_f32_16x16x32_bf16 v[76:79], v[144:147], v[208:211], v[76:79]
	v_mfma_f32_16x16x32_bf16 v[72:75], v[160:163], v[208:211], v[72:75]
	v_mfma_f32_16x16x32_bf16 v[124:127], v[148:151], v[188:191], v[124:127]
	v_mfma_f32_16x16x32_bf16 v[120:123], v[164:167], v[188:191], v[120:123]
	v_mfma_f32_16x16x32_bf16 v[108:111], v[148:151], v[196:199], v[108:111]
	v_mfma_f32_16x16x32_bf16 v[104:107], v[164:167], v[196:199], v[104:107]
	v_mfma_f32_16x16x32_bf16 v[92:95], v[148:151], v[204:207], v[92:95]
	v_mfma_f32_16x16x32_bf16 v[88:91], v[164:167], v[204:207], v[88:91]
	v_mfma_f32_16x16x32_bf16 v[76:79], v[148:151], v[212:215], v[76:79]
	v_mfma_f32_16x16x32_bf16 v[72:75], v[164:167], v[212:215], v[72:75]
	s_setprio 0
	s_setprio 1
	v_mfma_f32_16x16x32_bf16 v[116:119], v[168:171], v[184:187], v[116:119]
	v_mfma_f32_16x16x32_bf16 v[112:115], v[176:179], v[184:187], v[112:115]
	v_mfma_f32_16x16x32_bf16 v[100:103], v[168:171], v[192:195], v[100:103]
	v_mfma_f32_16x16x32_bf16 v[96:99], v[176:179], v[192:195], v[96:99]
	v_mfma_f32_16x16x32_bf16 v[84:87], v[168:171], v[200:203], v[84:87]
	v_mfma_f32_16x16x32_bf16 v[80:83], v[176:179], v[200:203], v[80:83]
	v_mfma_f32_16x16x32_bf16 v[68:71], v[168:171], v[208:211], v[68:71]
	v_mfma_f32_16x16x32_bf16 v[64:67], v[176:179], v[208:211], v[64:67]
	v_mfma_f32_16x16x32_bf16 v[116:119], v[172:175], v[188:191], v[116:119]
	v_mfma_f32_16x16x32_bf16 v[112:115], v[180:183], v[188:191], v[112:115]
	v_mfma_f32_16x16x32_bf16 v[100:103], v[172:175], v[196:199], v[100:103]
	v_mfma_f32_16x16x32_bf16 v[96:99], v[180:183], v[196:199], v[96:99]
	v_mfma_f32_16x16x32_bf16 v[84:87], v[172:175], v[204:207], v[84:87]
	v_mfma_f32_16x16x32_bf16 v[80:83], v[180:183], v[204:207], v[80:83]
	v_mfma_f32_16x16x32_bf16 v[68:71], v[172:175], v[212:215], v[68:71]
	v_mfma_f32_16x16x32_bf16 v[64:67], v[180:183], v[212:215], v[64:67]
	s_setprio 0
	s_barrier
; #define PG8_STAGE(bufoff, gbase, voff) do { _Pragma("unroll") for (int _i = 0; _i < 2; ++_i) \
;         __builtin_amdgcn_global_load_lds((const unsigned*)((const char*)(gbase) + (voff)[_i]), (PG8_LAS unsigned*)(lds + (bufoff) + ldsw + _i * 8192), 16, 0, 0); } while (0)
; #define PG8_LDA(dst, b, h) do { _Pragma("unroll") for (int m = 0; m < 4; ++m) _Pragma("unroll") for (int k = 0; k < 2; ++k) dst[m][k] = *(const PG8_LAS bf16x8*)(lds + PG8_SA(b, h) + aoff + m * 2048 + k * 1024); } while (0)
; #define PG8_MMA(ai, bj, At, Bt) do { __builtin_amdgcn_s_setprio(1); _Pragma("unroll") for (int m = 0; m < 4; ++m) _Pragma("unroll") for (int n = 0; n < 2; ++n) _Pragma("unroll") for (int k = 0; k < 2; ++k) \
;         acc[ai][bj][m][n] = __builtin_amdgcn_mfma_f32_16x16x32_bf16(Bt[n][k], At[m][k], acc[ai][bj][m][n], 0, 0, 0); __builtin_amdgcn_s_setprio(0); } while (0)
; #define PG8_WAIT_V(n) asm volatile("s_waitcnt vmcnt(" #n ")" ::: "memory")
; #define PG8_WAIT_L(n) asm volatile("s_waitcnt lgkmcnt(" #n ")" ::: "memory")
; #define PG8_BAR __builtin_amdgcn_s_barrier()
; #define PG8_SCHED __builtin_amdgcn_sched_barrier(0)
; template <class Epi, class Sched, bool ALIGN_EPI = false, bool SP2 = false>
; __device__ __forceinline__ void gemm_phase(PG8_LAS unsigned char* lds, const Gemm g, const Sched& S, const Epi& E) {
;     ...
;             PG8_LDA(At, 1, 1); PG8_STAGE(PG8_SB(1, 0), b3, voffB); PG8_STAGE(PG8_SB(1, 1), b3 + hstep, voffB); PG8_STAGE(PG8_SA(1, 0), a3, voffA);
;             PG8_WAIT_V(8); PG8_WAIT_L(0); PG8_BAR; PG8_MMA(1, 0, At, B0); PG8_MMA(1, 1, At, B1); PG8_BAR; PG8_SCHED;
	s_add_i32 s54, s79, s58
	v_lshl_add_u64 v[216:217], v[216:217], 0, s[18:19]
	s_mov_b32 m0, s54
	ds_read_b128 v[184:187], v157 offset:49152
	ds_read_b128 v[188:191], v157 offset:50176
	ds_read_b128 v[192:195], v157 offset:51200
	ds_read_b128 v[196:199], v157 offset:52224
	ds_read_b128 v[200:203], v157 offset:53248
	ds_read_b128 v[204:207], v157 offset:54272
	ds_read_b128 v[208:211], v157 offset:55296
	ds_read_b128 v[212:215], v157 offset:56320
	global_load_lds_dwordx4 v[216:217], off
	s_add_i32 m0, s54, 0x2000
	s_add_u32 s52, s52, 0x80080
	v_lshl_add_u64 v[216:217], v[220:221], 0, s[18:19]
	s_addc_u32 s53, s53, 0
	s_add_i32 s54, s80, s58
	global_load_lds_dwordx4 v[216:217], off
	v_lshl_add_u64 v[216:217], s[52:53], 0, v[132:133]
	s_mov_b32 m0, s54
	s_nop 0
	global_load_lds_dwordx4 v[216:217], off
	v_lshl_add_u64 v[216:217], s[52:53], 0, v[128:129]
	s_add_i32 m0, s54, 0x2000
	s_nop 0
	global_load_lds_dwordx4 v[216:217], off
	v_lshl_add_u64 v[216:217], v[222:223], 0, s[18:19]
	s_mov_b32 m0, s64
	s_nop 0
	global_load_lds_dwordx4 v[216:217], off
	v_lshl_add_u64 v[216:217], v[224:225], 0, s[18:19]
	s_mov_b32 m0, s65
	s_nop 0
	global_load_lds_dwordx4 v[216:217], off
	s_waitcnt vmcnt(8)
	s_waitcnt lgkmcnt(0)
	s_barrier
	s_setprio 1
	s_waitcnt lgkmcnt(0)
	v_mfma_f32_16x16x32_bf16 v[60:63], v[144:147], v[184:187], v[60:63]
	v_mfma_f32_16x16x32_bf16 v[56:59], v[160:163], v[184:187], v[56:59]
	v_mfma_f32_16x16x32_bf16 v[44:47], v[144:147], v[192:195], v[44:47]
	v_mfma_f32_16x16x32_bf16 v[40:43], v[160:163], v[192:195], v[40:43]
	v_mfma_f32_16x16x32_bf16 v[28:31], v[144:147], v[200:203], v[28:31]
	v_mfma_f32_16x16x32_bf16 v[24:27], v[160:163], v[200:203], v[24:27]
	v_mfma_f32_16x16x32_bf16 v[12:15], v[144:147], v[208:211], v[12:15]
	v_mfma_f32_16x16x32_bf16 v[8:11], v[160:163], v[208:211], v[8:11]
	v_mfma_f32_16x16x32_bf16 v[60:63], v[148:151], v[188:191], v[60:63]
	v_mfma_f32_16x16x32_bf16 v[56:59], v[164:167], v[188:191], v[56:59]
	v_mfma_f32_16x16x32_bf16 v[44:47], v[148:151], v[196:199], v[44:47]
	v_mfma_f32_16x16x32_bf16 v[40:43], v[164:167], v[196:199], v[40:43]
	v_mfma_f32_16x16x32_bf16 v[28:31], v[148:151], v[204:207], v[28:31]
	v_mfma_f32_16x16x32_bf16 v[24:27], v[164:167], v[204:207], v[24:27]
	v_mfma_f32_16x16x32_bf16 v[12:15], v[148:151], v[212:215], v[12:15]
	v_mfma_f32_16x16x32_bf16 v[8:11], v[164:167], v[212:215], v[8:11]
	s_setprio 0
	s_setprio 1
	v_mfma_f32_16x16x32_bf16 v[52:55], v[168:171], v[184:187], v[52:55]
	v_mfma_f32_16x16x32_bf16 v[48:51], v[176:179], v[184:187], v[48:51]
	v_mfma_f32_16x16x32_bf16 v[36:39], v[168:171], v[192:195], v[36:39]
	v_mfma_f32_16x16x32_bf16 v[32:35], v[176:179], v[192:195], v[32:35]
	v_mfma_f32_16x16x32_bf16 v[20:23], v[168:171], v[200:203], v[20:23]
	v_mfma_f32_16x16x32_bf16 v[16:19], v[176:179], v[200:203], v[16:19]
	v_mfma_f32_16x16x32_bf16 v[4:7], v[168:171], v[208:211], v[4:7]
	v_mfma_f32_16x16x32_bf16 v[0:3], v[176:179], v[208:211], v[0:3]
	v_mfma_f32_16x16x32_bf16 v[52:55], v[172:175], v[188:191], v[52:55]
	v_mfma_f32_16x16x32_bf16 v[48:51], v[180:183], v[188:191], v[48:51]
	v_mfma_f32_16x16x32_bf16 v[36:39], v[172:175], v[196:199], v[36:39]
	v_mfma_f32_16x16x32_bf16 v[32:35], v[180:183], v[196:199], v[32:35]
	v_mfma_f32_16x16x32_bf16 v[20:23], v[172:175], v[204:207], v[20:23]
	v_mfma_f32_16x16x32_bf16 v[16:19], v[180:183], v[204:207], v[16:19]
	v_mfma_f32_16x16x32_bf16 v[4:7], v[172:175], v[212:215], v[4:7]
	v_mfma_f32_16x16x32_bf16 v[0:3], v[180:183], v[212:215], v[0:3]
	s_setprio 0
	s_barrier
	s_add_i32 s78, s78, 2
	s_add_u32 s50, s50, 0x100
	s_addc_u32 s51, s51, 0
	s_add_u32 s76, s76, 0x100
	s_addc_u32 s77, s77, 0
	s_cmp_gt_u32 s78, 29

; #define PG8_STAGE(bufoff, gbase, voff) do { _Pragma("unroll") for (int _i = 0; _i < 2; ++_i) \
;         __builtin_amdgcn_global_load_lds((const unsigned*)((const char*)(gbase) + (voff)[_i]), (PG8_LAS unsigned*)(lds + (bufoff) + ldsw + _i * 8192), 16, 0, 0); } while (0)
; #define PG8_LDA(dst, b, h) do { _Pragma("unroll") for (int m = 0; m < 4; ++m) _Pragma("unroll") for (int k = 0; k < 2; ++k) dst[m][k] = *(const PG8_LAS bf16x8*)(lds + PG8_SA(b, h) + aoff + m * 2048 + k * 1024); } while (0)
; #define PG8_LDB(dst, b, h) do { _Pragma("unroll") for (int n = 0; n < 2; ++n) _Pragma("unroll") for (int k = 0; k < 2; ++k) dst[n][k] = *(const PG8_LAS bf16x8*)(lds + PG8_SB(b, h) + boff + n * 2048 + k * 1024); } while (0)
; #define PG8_WAIT_V(n) asm volatile("s_waitcnt vmcnt(" #n ")" ::: "memory")
; #define PG8_WAIT_L(n) asm volatile("s_waitcnt lgkmcnt(" #n ")" ::: "memory")
; #define PG8_BAR __builtin_amdgcn_s_barrier()
; #define PG8_SCHED __builtin_amdgcn_sched_barrier(0)
; template <class Epi, class Sched, bool ALIGN_EPI = false, bool SP2 = false>
; __device__ __forceinline__ void gemm_phase(PG8_LAS unsigned char* lds, const Gemm g, const Sched& S, const Epi& E) {
;     ...
;         const char* nA = has_next ? (const char*)g.A + (size_t)nxt.pm * tstep : cA; const char* nB = has_next ? (const char*)g.Bt + (size_t)nxt.pn * tstep : cB;
;         for (int t = 0; t < nt; t += 2) {
;             const bool last = (t == nt - 2);
;             const char* a1 = cA + (size_t)(t + 1) * kstep;
;             const char* a2 = last ? nA : cA + (size_t)(t + 2) * kstep; const char* b2 = last ? nB : cB + (size_t)(t + 2) * kstep;
;             const char* a3 = a2 + kstep; const char* b3 = b2 + kstep;
;             if (last && has_next) S.a_ready(nxt);
;             if constexpr (SP2) {
;             PG8_LDB(B0, 0, 0); PG8_LDB(B1, 0, 1); PG8_SCHED; PG8_LDA(At, 0, 0); PG8_STAGE(PG8_SA(1, 1), a1 + hstep, voffA);
;             PG8_WAIT_V(8); PG8_WAIT_L(0); PG8_BAR; PG8_MMA(0, 0, At, B0); PG8_MMA(0, 1, At, B1); PG8_BAR; PG8_SCHED;
;             PG8_LDA(At, 0, 1); PG8_STAGE(PG8_SB(0, 0), b2, voffB); PG8_STAGE(PG8_SB(0, 1), b2 + hstep, voffB); PG8_STAGE(PG8_SA(0, 0), a2, voffA);
;             PG8_WAIT_V(8); PG8_WAIT_L(0); PG8_BAR; PG8_MMA(1, 0, At, B0); PG8_MMA(1, 1, At, B1); PG8_BAR; PG8_SCHED;
.LBB0_683:
	s_ashr_i32 s37, s36, 31
	s_lshl_b64 s[28:29], s[36:37], 20
	s_add_u32 s38, s24, s28
	s_addc_u32 s39, s25, s29
	s_and_b64 s[28:29], s[4:5], exec
	s_cselect_b32 s28, s39, s47
	s_cselect_b32 s29, s38, s46
	s_ashr_i32 s35, s34, 31
	s_lshl_b64 s[40:41], s[34:35], 20
	s_add_u32 s40, s52, s40
	s_addc_u32 s41, s53, s41
	s_and_b64 s[50:51], s[4:5], exec
	s_cselect_b32 s35, s41, s49
	s_cselect_b32 s37, s40, s48
	s_add_u32 s46, s46, 0x80080
	s_addc_u32 s47, s47, 0
	s_add_u32 s43, s48, 0x100
	s_addc_u32 s65, s49, 0
	s_mov_b32 s66, -2
	s_waitcnt lgkmcnt(0)
	ds_read_b128 v[144:147], v151
	ds_read_b128 v[156:159], v151 offset:1024
	ds_read_b128 v[160:163], v151 offset:2048
	ds_read_b128 v[164:167], v151 offset:3072
	ds_read_b128 v[168:171], v152
	ds_read_b128 v[172:175], v152 offset:1024
	ds_read_b128 v[176:179], v152 offset:2048
	ds_read_b128 v[180:183], v152 offset:3072
	s_add_u32 s48, s46, 0xfff80080
	s_addc_u32 s49, s47, -1
	s_cmp_eq_u32 s66, 28
	s_cselect_b32 s51, s28, s49
	s_cselect_b32 s50, s29, s48
	s_cselect_b32 s49, s35, s65
	s_cselect_b32 s48, s37, s43
	v_lshl_add_u64 v[216:217], s[46:47], 0, v[136:137]
	s_add_i32 m0, s45, 0xc000
	ds_read_b128 v[184:187], v153
	ds_read_b128 v[188:191], v153 offset:1024
	ds_read_b128 v[192:195], v153 offset:2048
	ds_read_b128 v[196:199], v153 offset:3072
	ds_read_b128 v[200:203], v153 offset:4096
	ds_read_b128 v[204:207], v153 offset:5120
	ds_read_b128 v[208:211], v153 offset:6144
	ds_read_b128 v[212:215], v153 offset:7168
	global_load_lds_dwordx4 v[216:217], off
	v_lshl_add_u64 v[216:217], s[46:47], 0, v[138:139]
	s_add_i32 m0, s45, 0xe000
	s_nop 0
	global_load_lds_dwordx4 v[216:217], off
	s_waitcnt vmcnt(8)
	s_waitcnt lgkmcnt(0)
	s_barrier
	s_setprio 1
	s_waitcnt lgkmcnt(0)
	v_mfma_f32_16x16x32_bf16 v[124:127], v[144:147], v[184:187], 0
	v_mfma_f32_16x16x32_bf16 v[120:123], v[160:163], v[184:187], 0
	v_mfma_f32_16x16x32_bf16 v[108:111], v[144:147], v[192:195], 0
	v_mfma_f32_16x16x32_bf16 v[104:107], v[160:163], v[192:195], 0
	v_mfma_f32_16x16x32_bf16 v[92:95], v[144:147], v[200:203], 0
	v_mfma_f32_16x16x32_bf16 v[88:91], v[160:163], v[200:203], 0
	v_mfma_f32_16x16x32_bf16 v[76:79], v[144:147], v[208:211], 0
	v_mfma_f32_16x16x32_bf16 v[72:75], v[160:163], v[208:211], 0
	v_mfma_f32_16x16x32_bf16 v[124:127], v[156:159], v[188:191], v[124:127]
	v_mfma_f32_16x16x32_bf16 v[120:123], v[164:167], v[188:191], v[120:123]
	v_mfma_f32_16x16x32_bf16 v[108:111], v[156:159], v[196:199], v[108:111]
	v_mfma_f32_16x16x32_bf16 v[104:107], v[164:167], v[196:199], v[104:107]
	v_mfma_f32_16x16x32_bf16 v[92:95], v[156:159], v[204:207], v[92:95]
	v_mfma_f32_16x16x32_bf16 v[88:91], v[164:167], v[204:207], v[88:91]
	v_mfma_f32_16x16x32_bf16 v[76:79], v[156:159], v[212:215], v[76:79]
	v_mfma_f32_16x16x32_bf16 v[72:75], v[164:167], v[212:215], v[72:75]
	s_setprio 0
	s_setprio 1
	v_mfma_f32_16x16x32_bf16 v[116:119], v[168:171], v[184:187], 0
	v_mfma_f32_16x16x32_bf16 v[112:115], v[176:179], v[184:187], 0
	v_mfma_f32_16x16x32_bf16 v[100:103], v[168:171], v[192:195], 0
	v_mfma_f32_16x16x32_bf16 v[96:99], v[176:179], v[192:195], 0
	v_mfma_f32_16x16x32_bf16 v[84:87], v[168:171], v[200:203], 0
	v_mfma_f32_16x16x32_bf16 v[80:83], v[176:179], v[200:203], 0
	v_mfma_f32_16x16x32_bf16 v[68:71], v[168:171], v[208:211], 0
	v_mfma_f32_16x16x32_bf16 v[64:67], v[176:179], v[208:211], 0
	v_mfma_f32_16x16x32_bf16 v[116:119], v[172:175], v[188:191], v[116:119]
	v_mfma_f32_16x16x32_bf16 v[112:115], v[180:183], v[188:191], v[112:115]
	v_mfma_f32_16x16x32_bf16 v[100:103], v[172:175], v[196:199], v[100:103]
	v_mfma_f32_16x16x32_bf16 v[96:99], v[180:183], v[196:199], v[96:99]
	v_mfma_f32_16x16x32_bf16 v[84:87], v[172:175], v[204:207], v[84:87]
	v_mfma_f32_16x16x32_bf16 v[80:83], v[180:183], v[204:207], v[80:83]
	v_mfma_f32_16x16x32_bf16 v[68:71], v[172:175], v[212:215], v[68:71]
	v_mfma_f32_16x16x32_bf16 v[64:67], v[180:183], v[212:215], v[64:67]
	s_setprio 0
	s_barrier
	s_add_i32 s67, s63, s54
	v_lshl_add_u64 v[216:217], s[48:49], 0, v[130:131]
	s_mov_b32 m0, s67
	ds_read_b128 v[184:187], v153 offset:16384
	ds_read_b128 v[188:191], v153 offset:17408
	ds_read_b128 v[192:195], v153 offset:18432
	ds_read_b128 v[196:199], v153 offset:19456
	ds_read_b128 v[200:203], v153 offset:20480
	ds_read_b128 v[204:207], v153 offset:21504
	ds_read_b128 v[208:211], v153 offset:22528
	ds_read_b128 v[212:215], v153 offset:23552
	global_load_lds_dwordx4 v[216:217], off
	s_add_i32 m0, s67, 0x2000
	s_add_u32 s68, s48, 0x80000
	v_lshl_add_u64 v[220:221], s[48:49], 0, v[134:135]
	s_addc_u32 s69, s49, 0
	s_add_i32 s67, s64, s54
	global_load_lds_dwordx4 v[220:221], off
	v_lshl_add_u64 v[222:223], s[68:69], 0, v[130:131]
	s_mov_b32 m0, s67
	v_lshl_add_u64 v[224:225], s[50:51], 0, v[132:133]
	global_load_lds_dwordx4 v[222:223], off
	v_lshl_add_u64 v[222:223], s[68:69], 0, v[134:135]
	s_add_i32 m0, s67, 0x2000
	s_nop 0
	global_load_lds_dwordx4 v[222:223], off
	v_lshl_add_u64 v[222:223], s[50:51], 0, v[128:129]
	s_mov_b32 m0, s45
	s_nop 0
	global_load_lds_dwordx4 v[222:223], off
	s_mov_b32 m0, s55
	s_nop 0
	global_load_lds_dwordx4 v[224:225], off
	s_waitcnt vmcnt(8)
	s_waitcnt lgkmcnt(0)
	s_barrier
; #define PG8_STAGE(bufoff, gbase, voff) do { _Pragma("unroll") for (int _i = 0; _i < 2; ++_i) \
;         __builtin_amdgcn_global_load_lds((const unsigned*)((const char*)(gbase) + (voff)[_i]), (PG8_LAS unsigned*)(lds + (bufoff) + ldsw + _i * 8192), 16, 0, 0); } while (0)
; #define PG8_LDA(dst, b, h) do { _Pragma("unroll") for (int m = 0; m < 4; ++m) _Pragma("unroll") for (int k = 0; k < 2; ++k) dst[m][k] = *(const PG8_LAS bf16x8*)(lds + PG8_SA(b, h) + aoff + m * 2048 + k * 1024); } while (0)
; #define PG8_LDB(dst, b, h) do { _Pragma("unroll") for (int n = 0; n < 2; ++n) _Pragma("unroll") for (int k = 0; k < 2; ++k) dst[n][k] = *(const PG8_LAS bf16x8*)(lds + PG8_SB(b, h) + boff + n * 2048 + k * 1024); } while (0)
; #define PG8_MMA(ai, bj, At, Bt) do { __builtin_amdgcn_s_setprio(1); _Pragma("unroll") for (int m = 0; m < 4; ++m) _Pragma("unroll") for (int n = 0; n < 2; ++n) _Pragma("unroll") for (int k = 0; k < 2; ++k) \
;         acc[ai][bj][m][n] = __builtin_amdgcn_mfma_f32_16x16x32_bf16(Bt[n][k], At[m][k], acc[ai][bj][m][n], 0, 0, 0); __builtin_amdgcn_s_setprio(0); } while (0)
; #define PG8_WAIT_V(n) asm volatile("s_waitcnt vmcnt(" #n ")" ::: "memory")
; #define PG8_WAIT_L(n) asm volatile("s_waitcnt lgkmcnt(" #n ")" ::: "memory")
; #define PG8_BAR __builtin_amdgcn_s_barrier()
; #define PG8_SCHED __builtin_amdgcn_sched_barrier(0)
; template <class Epi, class Sched, bool ALIGN_EPI = false, bool SP2 = false>
; __device__ __forceinline__ void gemm_phase(PG8_LAS unsigned char* lds, const Gemm g, const Sched& S, const Epi& E) {
;     ...
;             PG8_WAIT_V(8); PG8_WAIT_L(0); PG8_BAR; PG8_MMA(1, 0, At, B0); PG8_MMA(1, 1, At, B1); PG8_BAR; PG8_SCHED;
;             PG8_LDB(B0, 1, 0); PG8_LDB(B1, 1, 1); PG8_SCHED; PG8_LDA(At, 1, 0); PG8_STAGE(PG8_SA(0, 1), a2 + hstep, voffA);
;             PG8_WAIT_V(8); PG8_WAIT_L(0); PG8_BAR; PG8_MMA(0, 0, At, B0); PG8_MMA(0, 1, At, B1); PG8_BAR; PG8_SCHED;
	s_setprio 1
	s_waitcnt lgkmcnt(0)
	v_mfma_f32_16x16x32_bf16 v[60:63], v[144:147], v[184:187], 0
	v_mfma_f32_16x16x32_bf16 v[56:59], v[160:163], v[184:187], 0
	v_mfma_f32_16x16x32_bf16 v[44:47], v[144:147], v[192:195], 0
	v_mfma_f32_16x16x32_bf16 v[40:43], v[160:163], v[192:195], 0
	v_mfma_f32_16x16x32_bf16 v[28:31], v[144:147], v[200:203], 0
	v_mfma_f32_16x16x32_bf16 v[24:27], v[160:163], v[200:203], 0
	v_mfma_f32_16x16x32_bf16 v[12:15], v[144:147], v[208:211], 0
	v_mfma_f32_16x16x32_bf16 v[8:11], v[160:163], v[208:211], 0
	v_mfma_f32_16x16x32_bf16 v[60:63], v[156:159], v[188:191], v[60:63]
	v_mfma_f32_16x16x32_bf16 v[56:59], v[164:167], v[188:191], v[56:59]
	v_mfma_f32_16x16x32_bf16 v[44:47], v[156:159], v[196:199], v[44:47]
	v_mfma_f32_16x16x32_bf16 v[40:43], v[164:167], v[196:199], v[40:43]
	v_mfma_f32_16x16x32_bf16 v[28:31], v[156:159], v[204:207], v[28:31]
	v_mfma_f32_16x16x32_bf16 v[24:27], v[164:167], v[204:207], v[24:27]
	v_mfma_f32_16x16x32_bf16 v[12:15], v[156:159], v[212:215], v[12:15]
	v_mfma_f32_16x16x32_bf16 v[8:11], v[164:167], v[212:215], v[8:11]
	s_setprio 0
	s_setprio 1
	v_mfma_f32_16x16x32_bf16 v[52:55], v[168:171], v[184:187], 0
	v_mfma_f32_16x16x32_bf16 v[48:51], v[176:179], v[184:187], 0
	v_mfma_f32_16x16x32_bf16 v[36:39], v[168:171], v[192:195], 0
	v_mfma_f32_16x16x32_bf16 v[32:35], v[176:179], v[192:195], 0
	v_mfma_f32_16x16x32_bf16 v[20:23], v[168:171], v[200:203], 0
	v_mfma_f32_16x16x32_bf16 v[16:19], v[176:179], v[200:203], 0
	v_mfma_f32_16x16x32_bf16 v[4:7], v[168:171], v[208:211], 0
	v_mfma_f32_16x16x32_bf16 v[0:3], v[176:179], v[208:211], 0
	v_mfma_f32_16x16x32_bf16 v[52:55], v[172:175], v[188:191], v[52:55]
	v_mfma_f32_16x16x32_bf16 v[48:51], v[180:183], v[188:191], v[48:51]
	v_mfma_f32_16x16x32_bf16 v[36:39], v[172:175], v[196:199], v[36:39]
	v_mfma_f32_16x16x32_bf16 v[32:35], v[180:183], v[196:199], v[32:35]
	v_mfma_f32_16x16x32_bf16 v[20:23], v[172:175], v[204:207], v[20:23]
	v_mfma_f32_16x16x32_bf16 v[16:19], v[180:183], v[204:207], v[16:19]
	v_mfma_f32_16x16x32_bf16 v[4:7], v[172:175], v[212:215], v[4:7]
	v_mfma_f32_16x16x32_bf16 v[0:3], v[180:183], v[212:215], v[0:3]
	s_setprio 0
	s_barrier
	s_add_i32 s67, 0, 0x18000
	v_add_u32_e32 v155, s67, v149
	s_add_i32 s68, 0, 0x1c000
	ds_read_b128 v[144:147], v155
	ds_read_b128 v[156:159], v155 offset:1024
	ds_read_b128 v[160:163], v155 offset:2048
	ds_read_b128 v[164:167], v155 offset:3072
	v_add_u32_e32 v155, s68, v149
	ds_read_b128 v[168:171], v155
	ds_read_b128 v[172:175], v155 offset:1024
	ds_read_b128 v[176:179], v155 offset:2048
	ds_read_b128 v[180:183], v155 offset:3072
	s_add_u32 s50, s50, 0x80000
	s_addc_u32 s51, s51, 0
	s_mov_b32 m0, s56
	v_lshl_add_u64 v[226:227], s[50:51], 0, v[128:129]
	ds_read_b128 v[184:187], v153 offset:32768
	ds_read_b128 v[188:191], v153 offset:33792
	ds_read_b128 v[192:195], v153 offset:34816
	ds_read_b128 v[196:199], v153 offset:35840
	ds_read_b128 v[200:203], v153 offset:36864
	ds_read_b128 v[204:207], v153 offset:37888
	ds_read_b128 v[208:211], v153 offset:38912
	ds_read_b128 v[212:215], v153 offset:39936
	global_load_lds_dwordx4 v[226:227], off
	v_lshl_add_u64 v[226:227], s[50:51], 0, v[132:133]
	s_mov_b32 m0, s57
	s_nop 0
	global_load_lds_dwordx4 v[226:227], off
	s_waitcnt vmcnt(8)
	s_waitcnt lgkmcnt(0)
	s_barrier
	s_setprio 1
	s_waitcnt lgkmcnt(0)
	v_mfma_f32_16x16x32_bf16 v[124:127], v[144:147], v[184:187], v[124:127]
	v_mfma_f32_16x16x32_bf16 v[120:123], v[160:163], v[184:187], v[120:123]
	v_mfma_f32_16x16x32_bf16 v[108:111], v[144:147], v[192:195], v[108:111]
	v_mfma_f32_16x16x32_bf16 v[104:107], v[160:163], v[192:195], v[104:107]
	v_mfma_f32_16x16x32_bf16 v[92:95], v[144:147], v[200:203], v[92:95]
	v_mfma_f32_16x16x32_bf16 v[88:91], v[160:163], v[200:203], v[88:91]
	v_mfma_f32_16x16x32_bf16 v[76:79], v[144:147], v[208:211], v[76:79]
	v_mfma_f32_16x16x32_bf16 v[72:75], v[160:163], v[208:211], v[72:75]
	v_mfma_f32_16x16x32_bf16 v[124:127], v[156:159], v[188:191], v[124:127]
	v_mfma_f32_16x16x32_bf16 v[120:123], v[164:167], v[188:191], v[120:123]
	v_mfma_f32_16x16x32_bf16 v[108:111], v[156:159], v[196:199], v[108:111]
	v_mfma_f32_16x16x32_bf16 v[104:107], v[164:167], v[196:199], v[104:107]
	v_mfma_f32_16x16x32_bf16 v[92:95], v[156:159], v[204:207], v[92:95]
	v_mfma_f32_16x16x32_bf16 v[88:91], v[164:167], v[204:207], v[88:91]
	v_mfma_f32_16x16x32_bf16 v[76:79], v[156:159], v[212:215], v[76:79]
	v_mfma_f32_16x16x32_bf16 v[72:75], v[164:167], v[212:215], v[72:75]
	s_setprio 0
	s_setprio 1
	v_mfma_f32_16x16x32_bf16 v[116:119], v[168:171], v[184:187], v[116:119]
	v_mfma_f32_16x16x32_bf16 v[112:115], v[176:179], v[184:187], v[112:115]
	v_mfma_f32_16x16x32_bf16 v[100:103], v[168:171], v[192:195], v[100:103]
	v_mfma_f32_16x16x32_bf16 v[96:99], v[176:179], v[192:195], v[96:99]
	v_mfma_f32_16x16x32_bf16 v[84:87], v[168:171], v[200:203], v[84:87]
	v_mfma_f32_16x16x32_bf16 v[80:83], v[176:179], v[200:203], v[80:83]
	v_mfma_f32_16x16x32_bf16 v[68:71], v[168:171], v[208:211], v[68:71]
	v_mfma_f32_16x16x32_bf16 v[64:67], v[176:179], v[208:211], v[64:67]
	v_mfma_f32_16x16x32_bf16 v[116:119], v[172:175], v[188:191], v[116:119]
	v_mfma_f32_16x16x32_bf16 v[112:115], v[180:183], v[188:191], v[112:115]
	v_mfma_f32_16x16x32_bf16 v[100:103], v[172:175], v[196:199], v[100:103]
	v_mfma_f32_16x16x32_bf16 v[96:99], v[180:183], v[196:199], v[96:99]
	v_mfma_f32_16x16x32_bf16 v[84:87], v[172:175], v[204:207], v[84:87]
	v_mfma_f32_16x16x32_bf16 v[80:83], v[180:183], v[204:207], v[80:83]
	v_mfma_f32_16x16x32_bf16 v[68:71], v[172:175], v[212:215], v[68:71]
	v_mfma_f32_16x16x32_bf16 v[64:67], v[180:183], v[212:215], v[64:67]
	s_setprio 0
	s_barrier
; #define PG8_STAGE(bufoff, gbase, voff) do { _Pragma("unroll") for (int _i = 0; _i < 2; ++_i) \
;         __builtin_amdgcn_global_load_lds((const unsigned*)((const char*)(gbase) + (voff)[_i]), (PG8_LAS unsigned*)(lds + (bufoff) + ldsw + _i * 8192), 16, 0, 0); } while (0)
; #define PG8_LDA(dst, b, h) do { _Pragma("unroll") for (int m = 0; m < 4; ++m) _Pragma("unroll") for (int k = 0; k < 2; ++k) dst[m][k] = *(const PG8_LAS bf16x8*)(lds + PG8_SA(b, h) + aoff + m * 2048 + k * 1024); } while (0)
; #define PG8_MMA(ai, bj, At, Bt) do { __builtin_amdgcn_s_setprio(1); _Pragma("unroll") for (int m = 0; m < 4; ++m) _Pragma("unroll") for (int n = 0; n < 2; ++n) _Pragma("unroll") for (int k = 0; k < 2; ++k) \
;         acc[ai][bj][m][n] = __builtin_amdgcn_mfma_f32_16x16x32_bf16(Bt[n][k], At[m][k], acc[ai][bj][m][n], 0, 0, 0); __builtin_amdgcn_s_setprio(0); } while (0)
; #define PG8_WAIT_V(n) asm volatile("s_waitcnt vmcnt(" #n ")" ::: "memory")
; #define PG8_WAIT_L(n) asm volatile("s_waitcnt lgkmcnt(" #n ")" ::: "memory")
; #define PG8_BAR __builtin_amdgcn_s_barrier()
; #define PG8_SCHED __builtin_amdgcn_sched_barrier(0)
; template <class Epi, class Sched, bool ALIGN_EPI = false, bool SP2 = false>
; __device__ __forceinline__ void gemm_phase(PG8_LAS unsigned char* lds, const Gemm g, const Sched& S, const Epi& E) {
;     ...
;             PG8_LDA(At, 1, 1); PG8_STAGE(PG8_SB(1, 0), b3, voffB); PG8_STAGE(PG8_SB(1, 1), b3 + hstep, voffB); PG8_STAGE(PG8_SA(1, 0), a3, voffA);
;             PG8_WAIT_V(8); PG8_WAIT_L(0); PG8_BAR; PG8_MMA(1, 0, At, B0); PG8_MMA(1, 1, At, B1); PG8_BAR; PG8_SCHED;
	s_add_i32 s50, s67, s54
	v_lshl_add_u64 v[216:217], v[216:217], 0, s[20:21]
	s_mov_b32 m0, s50
	ds_read_b128 v[184:187], v153 offset:49152
	ds_read_b128 v[188:191], v153 offset:50176
	ds_read_b128 v[192:195], v153 offset:51200
	ds_read_b128 v[196:199], v153 offset:52224
	ds_read_b128 v[200:203], v153 offset:53248
	ds_read_b128 v[204:207], v153 offset:54272
	ds_read_b128 v[208:211], v153 offset:55296
	ds_read_b128 v[212:215], v153 offset:56320
	global_load_lds_dwordx4 v[216:217], off
	s_add_i32 m0, s50, 0x2000
	s_add_u32 s48, s48, 0x80080
	v_lshl_add_u64 v[216:217], v[220:221], 0, s[20:21]
	s_addc_u32 s49, s49, 0
	s_add_i32 s50, s68, s54
	global_load_lds_dwordx4 v[216:217], off
	v_lshl_add_u64 v[216:217], s[48:49], 0, v[130:131]
	s_mov_b32 m0, s50
	s_nop 0
	global_load_lds_dwordx4 v[216:217], off
	v_lshl_add_u64 v[216:217], s[48:49], 0, v[134:135]
	s_add_i32 m0, s50, 0x2000
	s_nop 0
	global_load_lds_dwordx4 v[216:217], off
	v_lshl_add_u64 v[216:217], v[222:223], 0, s[20:21]
	s_mov_b32 m0, s59
	s_nop 0
	global_load_lds_dwordx4 v[216:217], off
	v_lshl_add_u64 v[216:217], v[224:225], 0, s[20:21]
	s_mov_b32 m0, s60
	s_nop 0
	global_load_lds_dwordx4 v[216:217], off
	s_waitcnt vmcnt(8)
	s_waitcnt lgkmcnt(0)
	s_barrier
	s_setprio 1
	s_waitcnt lgkmcnt(0)
	v_mfma_f32_16x16x32_bf16 v[60:63], v[144:147], v[184:187], v[60:63]
	v_mfma_f32_16x16x32_bf16 v[56:59], v[160:163], v[184:187], v[56:59]
	v_mfma_f32_16x16x32_bf16 v[44:47], v[144:147], v[192:195], v[44:47]
	v_mfma_f32_16x16x32_bf16 v[40:43], v[160:163], v[192:195], v[40:43]
	v_mfma_f32_16x16x32_bf16 v[28:31], v[144:147], v[200:203], v[28:31]
	v_mfma_f32_16x16x32_bf16 v[24:27], v[160:163], v[200:203], v[24:27]
	v_mfma_f32_16x16x32_bf16 v[12:15], v[144:147], v[208:211], v[12:15]
	v_mfma_f32_16x16x32_bf16 v[8:11], v[160:163], v[208:211], v[8:11]
	v_mfma_f32_16x16x32_bf16 v[60:63], v[156:159], v[188:191], v[60:63]
	v_mfma_f32_16x16x32_bf16 v[56:59], v[164:167], v[188:191], v[56:59]
	v_mfma_f32_16x16x32_bf16 v[44:47], v[156:159], v[196:199], v[44:47]
	v_mfma_f32_16x16x32_bf16 v[40:43], v[164:167], v[196:199], v[40:43]
	v_mfma_f32_16x16x32_bf16 v[28:31], v[156:159], v[204:207], v[28:31]
	v_mfma_f32_16x16x32_bf16 v[24:27], v[164:167], v[204:207], v[24:27]
	v_mfma_f32_16x16x32_bf16 v[12:15], v[156:159], v[212:215], v[12:15]
	v_mfma_f32_16x16x32_bf16 v[8:11], v[164:167], v[212:215], v[8:11]
	s_setprio 0
	s_setprio 1
	v_mfma_f32_16x16x32_bf16 v[52:55], v[168:171], v[184:187], v[52:55]
	v_mfma_f32_16x16x32_bf16 v[48:51], v[176:179], v[184:187], v[48:51]
	v_mfma_f32_16x16x32_bf16 v[36:39], v[168:171], v[192:195], v[36:39]
	v_mfma_f32_16x16x32_bf16 v[32:35], v[176:179], v[192:195], v[32:35]
	v_mfma_f32_16x16x32_bf16 v[20:23], v[168:171], v[200:203], v[20:23]
	v_mfma_f32_16x16x32_bf16 v[16:19], v[176:179], v[200:203], v[16:19]
	v_mfma_f32_16x16x32_bf16 v[4:7], v[168:171], v[208:211], v[4:7]
	v_mfma_f32_16x16x32_bf16 v[0:3], v[176:179], v[208:211], v[0:3]
	v_mfma_f32_16x16x32_bf16 v[52:55], v[172:175], v[188:191], v[52:55]
	v_mfma_f32_16x16x32_bf16 v[48:51], v[180:183], v[188:191], v[48:51]
	v_mfma_f32_16x16x32_bf16 v[36:39], v[172:175], v[196:199], v[36:39]
	v_mfma_f32_16x16x32_bf16 v[32:35], v[180:183], v[196:199], v[32:35]
	v_mfma_f32_16x16x32_bf16 v[20:23], v[172:175], v[204:207], v[20:23]
	v_mfma_f32_16x16x32_bf16 v[16:19], v[180:183], v[204:207], v[16:19]
	v_mfma_f32_16x16x32_bf16 v[4:7], v[172:175], v[212:215], v[4:7]
	v_mfma_f32_16x16x32_bf16 v[0:3], v[180:183], v[212:215], v[0:3]
	s_setprio 0
	s_barrier
	s_add_i32 s66, s66, 2
	s_add_u32 s46, s46, 0x100
	s_addc_u32 s47, s47, 0
	s_add_u32 s43, s43, 0x100
	s_addc_u32 s65, s65, 0
	s_cmp_gt_u32 s66, 29

; #define PG8_STAGE(bufoff, gbase, voff) do { _Pragma("unroll") for (int _i = 0; _i < 2; ++_i) \
;         __builtin_amdgcn_global_load_lds((const unsigned*)((const char*)(gbase) + (voff)[_i]), (PG8_LAS unsigned*)(lds + (bufoff) + ldsw + _i * 8192), 16, 0, 0); } while (0)
; #define PG8_LDA(dst, b, h) do { _Pragma("unroll") for (int m = 0; m < 4; ++m) _Pragma("unroll") for (int k = 0; k < 2; ++k) dst[m][k] = *(const PG8_LAS bf16x8*)(lds + PG8_SA(b, h) + aoff + m * 2048 + k * 1024); } while (0)
; #define PG8_LDB(dst, b, h) do { _Pragma("unroll") for (int n = 0; n < 2; ++n) _Pragma("unroll") for (int k = 0; k < 2; ++k) dst[n][k] = *(const PG8_LAS bf16x8*)(lds + PG8_SB(b, h) + boff + n * 2048 + k * 1024); } while (0)
; #define PG8_WAIT_V(n) asm volatile("s_waitcnt vmcnt(" #n ")" ::: "memory")
; #define PG8_WAIT_L(n) asm volatile("s_waitcnt lgkmcnt(" #n ")" ::: "memory")
; #define PG8_BAR __builtin_amdgcn_s_barrier()
; #define PG8_SCHED __builtin_amdgcn_sched_barrier(0)
; template <class Epi, class Sched, bool ALIGN_EPI = false, bool SP2 = false>
; __device__ __forceinline__ void gemm_phase(PG8_LAS unsigned char* lds, const Gemm g, const Sched& S, const Epi& E) {
;     ...
;         const char* nA = has_next ? (const char*)g.A + (size_t)nxt.pm * tstep : cA; const char* nB = has_next ? (const char*)g.Bt + (size_t)nxt.pn * tstep : cB;
;         for (int t = 0; t < nt; t += 2) {
;             const bool last = (t == nt - 2);
;             const char* a1 = cA + (size_t)(t + 1) * kstep;
;             const char* a2 = last ? nA : cA + (size_t)(t + 2) * kstep; const char* b2 = last ? nB : cB + (size_t)(t + 2) * kstep;
;             const char* a3 = a2 + kstep; const char* b3 = b2 + kstep;
;             if (last && has_next) S.a_ready(nxt);
;             if constexpr (SP2) {
;             PG8_LDB(B0, 0, 0); PG8_LDB(B1, 0, 1); PG8_SCHED; PG8_LDA(At, 0, 0); PG8_STAGE(PG8_SA(1, 1), a1 + hstep, voffA);
;             PG8_WAIT_V(8); PG8_WAIT_L(0); PG8_BAR; PG8_MMA(0, 0, At, B0); PG8_MMA(0, 1, At, B1); PG8_BAR; PG8_SCHED;
;             PG8_LDA(At, 0, 1); PG8_STAGE(PG8_SB(0, 0), b2, voffB); PG8_STAGE(PG8_SB(0, 1), b2 + hstep, voffB); PG8_STAGE(PG8_SA(0, 0), a2, voffA);
;             PG8_WAIT_V(8); PG8_WAIT_L(0); PG8_BAR; PG8_MMA(1, 0, At, B0); PG8_MMA(1, 1, At, B1); PG8_BAR; PG8_SCHED;
.LBB0_778:
	s_ashr_i32 s43, s42, 31
	s_lshl_b64 s[44:45], s[42:43], 20
	s_add_u32 s44, s55, s44
	s_addc_u32 s45, s56, s45
	s_and_b64 s[46:47], s[2:3], exec
	s_cselect_b32 s43, s45, s49
	s_cselect_b32 s74, s44, s48
	s_ashr_i32 s41, s40, 31
	s_lshl_b64 s[46:47], s[40:41], 20
	s_add_u32 s46, s57, s46
	s_addc_u32 s47, s58, s47
	s_and_b64 s[52:53], s[2:3], exec
	s_cselect_b32 s41, s47, s51
	s_cselect_b32 s75, s46, s50
	s_add_u32 s48, s48, 0x80080
	s_addc_u32 s49, s49, 0
	s_add_u32 s76, s50, 0x100
	s_addc_u32 s77, s51, 0
	s_mov_b32 s78, -2
	ds_read_b128 v[144:147], v155
	ds_read_b128 v[148:151], v155 offset:1024
	ds_read_b128 v[160:163], v155 offset:2048
	ds_read_b128 v[164:167], v155 offset:3072
	ds_read_b128 v[168:171], v156
	ds_read_b128 v[172:175], v156 offset:1024
	ds_read_b128 v[176:179], v156 offset:2048
	ds_read_b128 v[180:183], v156 offset:3072
	s_add_u32 s50, s48, 0xfff80080
	s_addc_u32 s51, s49, -1
	s_cmp_eq_u32 s78, 28
	s_cselect_b32 s53, s43, s51
	s_cselect_b32 s52, s74, s50
	s_cselect_b32 s51, s41, s77
	s_cselect_b32 s50, s75, s76
	v_lshl_add_u64 v[216:217], s[48:49], 0, v[136:137]
	s_add_i32 m0, s60, 0xc000
	ds_read_b128 v[184:187], v157
	ds_read_b128 v[188:191], v157 offset:1024
	ds_read_b128 v[192:195], v157 offset:2048
	ds_read_b128 v[196:199], v157 offset:3072
	ds_read_b128 v[200:203], v157 offset:4096
	ds_read_b128 v[204:207], v157 offset:5120
	ds_read_b128 v[208:211], v157 offset:6144
	ds_read_b128 v[212:215], v157 offset:7168
	global_load_lds_dwordx4 v[216:217], off
	v_lshl_add_u64 v[216:217], s[48:49], 0, v[138:139]
	s_add_i32 m0, s60, 0xe000
	s_nop 0
	global_load_lds_dwordx4 v[216:217], off
	s_waitcnt vmcnt(8)
	s_waitcnt lgkmcnt(0)
	s_barrier
	s_setprio 1
	s_waitcnt lgkmcnt(0)
	v_mfma_f32_16x16x32_bf16 v[124:127], v[144:147], v[184:187], 0
	v_mfma_f32_16x16x32_bf16 v[120:123], v[160:163], v[184:187], 0
	v_mfma_f32_16x16x32_bf16 v[108:111], v[144:147], v[192:195], 0
	v_mfma_f32_16x16x32_bf16 v[104:107], v[160:163], v[192:195], 0
	v_mfma_f32_16x16x32_bf16 v[92:95], v[144:147], v[200:203], 0
	v_mfma_f32_16x16x32_bf16 v[88:91], v[160:163], v[200:203], 0
	v_mfma_f32_16x16x32_bf16 v[76:79], v[144:147], v[208:211], 0
	v_mfma_f32_16x16x32_bf16 v[72:75], v[160:163], v[208:211], 0
	v_mfma_f32_16x16x32_bf16 v[124:127], v[148:151], v[188:191], v[124:127]
	v_mfma_f32_16x16x32_bf16 v[120:123], v[164:167], v[188:191], v[120:123]
	v_mfma_f32_16x16x32_bf16 v[108:111], v[148:151], v[196:199], v[108:111]
	v_mfma_f32_16x16x32_bf16 v[104:107], v[164:167], v[196:199], v[104:107]
	v_mfma_f32_16x16x32_bf16 v[92:95], v[148:151], v[204:207], v[92:95]
	v_mfma_f32_16x16x32_bf16 v[88:91], v[164:167], v[204:207], v[88:91]
	v_mfma_f32_16x16x32_bf16 v[76:79], v[148:151], v[212:215], v[76:79]
	v_mfma_f32_16x16x32_bf16 v[72:75], v[164:167], v[212:215], v[72:75]
	s_setprio 0
	s_setprio 1
	v_mfma_f32_16x16x32_bf16 v[116:119], v[168:171], v[184:187], 0
	v_mfma_f32_16x16x32_bf16 v[112:115], v[176:179], v[184:187], 0
	v_mfma_f32_16x16x32_bf16 v[100:103], v[168:171], v[192:195], 0
	v_mfma_f32_16x16x32_bf16 v[96:99], v[176:179], v[192:195], 0
	v_mfma_f32_16x16x32_bf16 v[84:87], v[168:171], v[200:203], 0
	v_mfma_f32_16x16x32_bf16 v[80:83], v[176:179], v[200:203], 0
	v_mfma_f32_16x16x32_bf16 v[68:71], v[168:171], v[208:211], 0
	v_mfma_f32_16x16x32_bf16 v[64:67], v[176:179], v[208:211], 0
	v_mfma_f32_16x16x32_bf16 v[116:119], v[172:175], v[188:191], v[116:119]
	v_mfma_f32_16x16x32_bf16 v[112:115], v[180:183], v[188:191], v[112:115]
	v_mfma_f32_16x16x32_bf16 v[100:103], v[172:175], v[196:199], v[100:103]
	v_mfma_f32_16x16x32_bf16 v[96:99], v[180:183], v[196:199], v[96:99]
	v_mfma_f32_16x16x32_bf16 v[84:87], v[172:175], v[204:207], v[84:87]
	v_mfma_f32_16x16x32_bf16 v[80:83], v[180:183], v[204:207], v[80:83]
	v_mfma_f32_16x16x32_bf16 v[68:71], v[172:175], v[212:215], v[68:71]
	v_mfma_f32_16x16x32_bf16 v[64:67], v[180:183], v[212:215], v[64:67]
	s_setprio 0
	s_barrier
	s_add_i32 s79, s66, s59
	v_lshl_add_u64 v[216:217], s[50:51], 0, v[130:131]
	s_mov_b32 m0, s79
	ds_read_b128 v[184:187], v157 offset:16384
	ds_read_b128 v[188:191], v157 offset:17408
	ds_read_b128 v[192:195], v157 offset:18432
	ds_read_b128 v[196:199], v157 offset:19456
	ds_read_b128 v[200:203], v157 offset:20480
	ds_read_b128 v[204:207], v157 offset:21504
	ds_read_b128 v[208:211], v157 offset:22528
	ds_read_b128 v[212:215], v157 offset:23552
	global_load_lds_dwordx4 v[216:217], off
	s_add_i32 m0, s79, 0x2000
	s_add_u32 s80, s50, 0x80000
	v_lshl_add_u64 v[220:221], s[50:51], 0, v[134:135]
	s_addc_u32 s81, s51, 0
	s_add_i32 s79, s67, s59
	global_load_lds_dwordx4 v[220:221], off
	v_lshl_add_u64 v[222:223], s[80:81], 0, v[130:131]
	s_mov_b32 m0, s79
	v_lshl_add_u64 v[224:225], s[52:53], 0, v[132:133]
	global_load_lds_dwordx4 v[222:223], off
	v_lshl_add_u64 v[222:223], s[80:81], 0, v[134:135]
	s_add_i32 m0, s79, 0x2000
	s_nop 0
	global_load_lds_dwordx4 v[222:223], off
	v_lshl_add_u64 v[222:223], s[52:53], 0, v[128:129]
	s_mov_b32 m0, s60
	s_nop 0
	global_load_lds_dwordx4 v[222:223], off
	s_mov_b32 m0, s61
	s_nop 0
	global_load_lds_dwordx4 v[224:225], off
	s_waitcnt vmcnt(8)
	s_waitcnt lgkmcnt(0)
	s_barrier
; #define PG8_STAGE(bufoff, gbase, voff) do { _Pragma("unroll") for (int _i = 0; _i < 2; ++_i) \
;         __builtin_amdgcn_global_load_lds((const unsigned*)((const char*)(gbase) + (voff)[_i]), (PG8_LAS unsigned*)(lds + (bufoff) + ldsw + _i * 8192), 16, 0, 0); } while (0)
; #define PG8_LDA(dst, b, h) do { _Pragma("unroll") for (int m = 0; m < 4; ++m) _Pragma("unroll") for (int k = 0; k < 2; ++k) dst[m][k] = *(const PG8_LAS bf16x8*)(lds + PG8_SA(b, h) + aoff + m * 2048 + k * 1024); } while (0)
; #define PG8_LDB(dst, b, h) do { _Pragma("unroll") for (int n = 0; n < 2; ++n) _Pragma("unroll") for (int k = 0; k < 2; ++k) dst[n][k] = *(const PG8_LAS bf16x8*)(lds + PG8_SB(b, h) + boff + n * 2048 + k * 1024); } while (0)
; #define PG8_MMA(ai, bj, At, Bt) do { __builtin_amdgcn_s_setprio(1); _Pragma("unroll") for (int m = 0; m < 4; ++m) _Pragma("unroll") for (int n = 0; n < 2; ++n) _Pragma("unroll") for (int k = 0; k < 2; ++k) \
;         acc[ai][bj][m][n] = __builtin_amdgcn_mfma_f32_16x16x32_bf16(Bt[n][k], At[m][k], acc[ai][bj][m][n], 0, 0, 0); __builtin_amdgcn_s_setprio(0); } while (0)
; #define PG8_WAIT_V(n) asm volatile("s_waitcnt vmcnt(" #n ")" ::: "memory")
; #define PG8_WAIT_L(n) asm volatile("s_waitcnt lgkmcnt(" #n ")" ::: "memory")
; #define PG8_BAR __builtin_amdgcn_s_barrier()
; #define PG8_SCHED __builtin_amdgcn_sched_barrier(0)
; template <class Epi, class Sched, bool ALIGN_EPI = false, bool SP2 = false>
; __device__ __forceinline__ void gemm_phase(PG8_LAS unsigned char* lds, const Gemm g, const Sched& S, const Epi& E) {
;     ...
;             PG8_WAIT_V(8); PG8_WAIT_L(0); PG8_BAR; PG8_MMA(1, 0, At, B0); PG8_MMA(1, 1, At, B1); PG8_BAR; PG8_SCHED;
;             PG8_LDB(B0, 1, 0); PG8_LDB(B1, 1, 1); PG8_SCHED; PG8_LDA(At, 1, 0); PG8_STAGE(PG8_SA(0, 1), a2 + hstep, voffA);
;             PG8_WAIT_V(8); PG8_WAIT_L(0); PG8_BAR; PG8_MMA(0, 0, At, B0); PG8_MMA(0, 1, At, B1); PG8_BAR; PG8_SCHED;
	s_setprio 1
	s_waitcnt lgkmcnt(0)
	v_mfma_f32_16x16x32_bf16 v[60:63], v[144:147], v[184:187], 0
	v_mfma_f32_16x16x32_bf16 v[56:59], v[160:163], v[184:187], 0
	v_mfma_f32_16x16x32_bf16 v[44:47], v[144:147], v[192:195], 0
	v_mfma_f32_16x16x32_bf16 v[40:43], v[160:163], v[192:195], 0
	v_mfma_f32_16x16x32_bf16 v[28:31], v[144:147], v[200:203], 0
	v_mfma_f32_16x16x32_bf16 v[24:27], v[160:163], v[200:203], 0
	v_mfma_f32_16x16x32_bf16 v[12:15], v[144:147], v[208:211], 0
	v_mfma_f32_16x16x32_bf16 v[8:11], v[160:163], v[208:211], 0
	v_mfma_f32_16x16x32_bf16 v[60:63], v[148:151], v[188:191], v[60:63]
	v_mfma_f32_16x16x32_bf16 v[56:59], v[164:167], v[188:191], v[56:59]
	v_mfma_f32_16x16x32_bf16 v[44:47], v[148:151], v[196:199], v[44:47]
	v_mfma_f32_16x16x32_bf16 v[40:43], v[164:167], v[196:199], v[40:43]
	v_mfma_f32_16x16x32_bf16 v[28:31], v[148:151], v[204:207], v[28:31]
	v_mfma_f32_16x16x32_bf16 v[24:27], v[164:167], v[204:207], v[24:27]
	v_mfma_f32_16x16x32_bf16 v[12:15], v[148:151], v[212:215], v[12:15]
	v_mfma_f32_16x16x32_bf16 v[8:11], v[164:167], v[212:215], v[8:11]
	s_setprio 0
	s_setprio 1
	v_mfma_f32_16x16x32_bf16 v[52:55], v[168:171], v[184:187], 0
	v_mfma_f32_16x16x32_bf16 v[48:51], v[176:179], v[184:187], 0
	v_mfma_f32_16x16x32_bf16 v[36:39], v[168:171], v[192:195], 0
	v_mfma_f32_16x16x32_bf16 v[32:35], v[176:179], v[192:195], 0
	v_mfma_f32_16x16x32_bf16 v[20:23], v[168:171], v[200:203], 0
	v_mfma_f32_16x16x32_bf16 v[16:19], v[176:179], v[200:203], 0
	v_mfma_f32_16x16x32_bf16 v[4:7], v[168:171], v[208:211], 0
	v_mfma_f32_16x16x32_bf16 v[0:3], v[176:179], v[208:211], 0
	v_mfma_f32_16x16x32_bf16 v[52:55], v[172:175], v[188:191], v[52:55]
	v_mfma_f32_16x16x32_bf16 v[48:51], v[180:183], v[188:191], v[48:51]
	v_mfma_f32_16x16x32_bf16 v[36:39], v[172:175], v[196:199], v[36:39]
	v_mfma_f32_16x16x32_bf16 v[32:35], v[180:183], v[196:199], v[32:35]
	v_mfma_f32_16x16x32_bf16 v[20:23], v[172:175], v[204:207], v[20:23]
	v_mfma_f32_16x16x32_bf16 v[16:19], v[180:183], v[204:207], v[16:19]
	v_mfma_f32_16x16x32_bf16 v[4:7], v[172:175], v[212:215], v[4:7]
	v_mfma_f32_16x16x32_bf16 v[0:3], v[180:183], v[212:215], v[0:3]
	s_setprio 0
	s_barrier
	s_add_i32 s79, 0, 0x18000
	s_add_i32 s80, 0, 0x1c000
	v_add_u32_e32 v164, s79, v153
	v_add_u32_e32 v180, s80, v153
	ds_read_b128 v[144:147], v164
	ds_read_b128 v[148:151], v164 offset:1024
	ds_read_b128 v[160:163], v164 offset:2048
	ds_read_b128 v[164:167], v164 offset:3072
	ds_read_b128 v[168:171], v180
	ds_read_b128 v[172:175], v180 offset:1024
	ds_read_b128 v[176:179], v180 offset:2048
	ds_read_b128 v[180:183], v180 offset:3072
	s_add_u32 s52, s52, 0x80000
	s_addc_u32 s53, s53, 0
	s_mov_b32 m0, s62
	v_lshl_add_u64 v[226:227], s[52:53], 0, v[128:129]
	ds_read_b128 v[184:187], v157 offset:32768
	ds_read_b128 v[188:191], v157 offset:33792
	ds_read_b128 v[192:195], v157 offset:34816
	ds_read_b128 v[196:199], v157 offset:35840
	ds_read_b128 v[200:203], v157 offset:36864
	ds_read_b128 v[204:207], v157 offset:37888
	ds_read_b128 v[208:211], v157 offset:38912
	ds_read_b128 v[212:215], v157 offset:39936
	global_load_lds_dwordx4 v[226:227], off
	v_lshl_add_u64 v[226:227], s[52:53], 0, v[132:133]
	s_mov_b32 m0, s63
	s_nop 0
	global_load_lds_dwordx4 v[226:227], off
	s_waitcnt vmcnt(8)
	s_waitcnt lgkmcnt(0)
	s_barrier
	s_setprio 1
	s_waitcnt lgkmcnt(0)
	v_mfma_f32_16x16x32_bf16 v[124:127], v[144:147], v[184:187], v[124:127]
	v_mfma_f32_16x16x32_bf16 v[120:123], v[160:163], v[184:187], v[120:123]
	v_mfma_f32_16x16x32_bf16 v[108:111], v[144:147], v[192:195], v[108:111]
	v_mfma_f32_16x16x32_bf16 v[104:107], v[160:163], v[192:195], v[104:107]
	v_mfma_f32_16x16x32_bf16 v[92:95], v[144:147], v[200:203], v[92:95]
	v_mfma_f32_16x16x32_bf16 v[88:91], v[160:163], v[200:203], v[88:91]
	v_mfma_f32_16x16x32_bf16 v[76:79], v[144:147], v[208:211], v[76:79]
	v_mfma_f32_16x16x32_bf16 v[72:75], v[160:163], v[208:211], v[72:75]
	v_mfma_f32_16x16x32_bf16 v[124:127], v[148:151], v[188:191], v[124:127]
	v_mfma_f32_16x16x32_bf16 v[120:123], v[164:167], v[188:191], v[120:123]
	v_mfma_f32_16x16x32_bf16 v[108:111], v[148:151], v[196:199], v[108:111]
	v_mfma_f32_16x16x32_bf16 v[104:107], v[164:167], v[196:199], v[104:107]
	v_mfma_f32_16x16x32_bf16 v[92:95], v[148:151], v[204:207], v[92:95]
	v_mfma_f32_16x16x32_bf16 v[88:91], v[164:167], v[204:207], v[88:91]
	v_mfma_f32_16x16x32_bf16 v[76:79], v[148:151], v[212:215], v[76:79]
	v_mfma_f32_16x16x32_bf16 v[72:75], v[164:167], v[212:215], v[72:75]
	s_setprio 0
	s_setprio 1
	v_mfma_f32_16x16x32_bf16 v[116:119], v[168:171], v[184:187], v[116:119]
	v_mfma_f32_16x16x32_bf16 v[112:115], v[176:179], v[184:187], v[112:115]
	v_mfma_f32_16x16x32_bf16 v[100:103], v[168:171], v[192:195], v[100:103]
	v_mfma_f32_16x16x32_bf16 v[96:99], v[176:179], v[192:195], v[96:99]
	v_mfma_f32_16x16x32_bf16 v[84:87], v[168:171], v[200:203], v[84:87]
	v_mfma_f32_16x16x32_bf16 v[80:83], v[176:179], v[200:203], v[80:83]
	v_mfma_f32_16x16x32_bf16 v[68:71], v[168:171], v[208:211], v[68:71]
	v_mfma_f32_16x16x32_bf16 v[64:67], v[176:179], v[208:211], v[64:67]
	v_mfma_f32_16x16x32_bf16 v[116:119], v[172:175], v[188:191], v[116:119]
	v_mfma_f32_16x16x32_bf16 v[112:115], v[180:183], v[188:191], v[112:115]
	v_mfma_f32_16x16x32_bf16 v[100:103], v[172:175], v[196:199], v[100:103]
	v_mfma_f32_16x16x32_bf16 v[96:99], v[180:183], v[196:199], v[96:99]
	v_mfma_f32_16x16x32_bf16 v[84:87], v[172:175], v[204:207], v[84:87]
	v_mfma_f32_16x16x32_bf16 v[80:83], v[180:183], v[204:207], v[80:83]
	v_mfma_f32_16x16x32_bf16 v[68:71], v[172:175], v[212:215], v[68:71]
	v_mfma_f32_16x16x32_bf16 v[64:67], v[180:183], v[212:215], v[64:67]
	s_setprio 0
	s_barrier
; #define PG8_STAGE(bufoff, gbase, voff) do { _Pragma("unroll") for (int _i = 0; _i < 2; ++_i) \
;         __builtin_amdgcn_global_load_lds((const unsigned*)((const char*)(gbase) + (voff)[_i]), (PG8_LAS unsigned*)(lds + (bufoff) + ldsw + _i * 8192), 16, 0, 0); } while (0)
; #define PG8_LDA(dst, b, h) do { _Pragma("unroll") for (int m = 0; m < 4; ++m) _Pragma("unroll") for (int k = 0; k < 2; ++k) dst[m][k] = *(const PG8_LAS bf16x8*)(lds + PG8_SA(b, h) + aoff + m * 2048 + k * 1024); } while (0)
; #define PG8_MMA(ai, bj, At, Bt) do { __builtin_amdgcn_s_setprio(1); _Pragma("unroll") for (int m = 0; m < 4; ++m) _Pragma("unroll") for (int n = 0; n < 2; ++n) _Pragma("unroll") for (int k = 0; k < 2; ++k) \
;         acc[ai][bj][m][n] = __builtin_amdgcn_mfma_f32_16x16x32_bf16(Bt[n][k], At[m][k], acc[ai][bj][m][n], 0, 0, 0); __builtin_amdgcn_s_setprio(0); } while (0)
; #define PG8_WAIT_V(n) asm volatile("s_waitcnt vmcnt(" #n ")" ::: "memory")
; #define PG8_WAIT_L(n) asm volatile("s_waitcnt lgkmcnt(" #n ")" ::: "memory")
; #define PG8_BAR __builtin_amdgcn_s_barrier()
; #define PG8_SCHED __builtin_amdgcn_sched_barrier(0)
; template <class Epi, class Sched, bool ALIGN_EPI = false, bool SP2 = false>
; __device__ __forceinline__ void gemm_phase(PG8_LAS unsigned char* lds, const Gemm g, const Sched& S, const Epi& E) {
;     ...
;             PG8_LDA(At, 1, 1); PG8_STAGE(PG8_SB(1, 0), b3, voffB); PG8_STAGE(PG8_SB(1, 1), b3 + hstep, voffB); PG8_STAGE(PG8_SA(1, 0), a3, voffA);
;             PG8_WAIT_V(8); PG8_WAIT_L(0); PG8_BAR; PG8_MMA(1, 0, At, B0); PG8_MMA(1, 1, At, B1); PG8_BAR; PG8_SCHED;
	s_add_i32 s52, s79, s59
	v_lshl_add_u64 v[216:217], v[216:217], 0, s[18:19]
	s_mov_b32 m0, s52
	ds_read_b128 v[184:187], v157 offset:49152
	ds_read_b128 v[188:191], v157 offset:50176
	ds_read_b128 v[192:195], v157 offset:51200
	ds_read_b128 v[196:199], v157 offset:52224
	ds_read_b128 v[200:203], v157 offset:53248
	ds_read_b128 v[204:207], v157 offset:54272
	ds_read_b128 v[208:211], v157 offset:55296
	ds_read_b128 v[212:215], v157 offset:56320
	global_load_lds_dwordx4 v[216:217], off
	s_add_i32 m0, s52, 0x2000
	s_add_u32 s50, s50, 0x80080
	v_lshl_add_u64 v[216:217], v[220:221], 0, s[18:19]
	s_addc_u32 s51, s51, 0
	s_add_i32 s52, s80, s59
	global_load_lds_dwordx4 v[216:217], off
	v_lshl_add_u64 v[216:217], s[50:51], 0, v[130:131]
	s_mov_b32 m0, s52
	s_nop 0
	global_load_lds_dwordx4 v[216:217], off
	v_lshl_add_u64 v[216:217], s[50:51], 0, v[134:135]
	s_add_i32 m0, s52, 0x2000
	s_nop 0
	global_load_lds_dwordx4 v[216:217], off
	v_lshl_add_u64 v[216:217], v[222:223], 0, s[18:19]
	s_mov_b32 m0, s28
	s_nop 0
	global_load_lds_dwordx4 v[216:217], off
	v_lshl_add_u64 v[216:217], v[224:225], 0, s[18:19]
	s_mov_b32 m0, s29
	s_nop 0
	global_load_lds_dwordx4 v[216:217], off
	s_waitcnt vmcnt(8)
	s_waitcnt lgkmcnt(0)
	s_barrier
	s_setprio 1
	s_waitcnt lgkmcnt(0)
	v_mfma_f32_16x16x32_bf16 v[60:63], v[144:147], v[184:187], v[60:63]
	v_mfma_f32_16x16x32_bf16 v[56:59], v[160:163], v[184:187], v[56:59]
	v_mfma_f32_16x16x32_bf16 v[44:47], v[144:147], v[192:195], v[44:47]
	v_mfma_f32_16x16x32_bf16 v[40:43], v[160:163], v[192:195], v[40:43]
	v_mfma_f32_16x16x32_bf16 v[28:31], v[144:147], v[200:203], v[28:31]
	v_mfma_f32_16x16x32_bf16 v[24:27], v[160:163], v[200:203], v[24:27]
	v_mfma_f32_16x16x32_bf16 v[12:15], v[144:147], v[208:211], v[12:15]
	v_mfma_f32_16x16x32_bf16 v[8:11], v[160:163], v[208:211], v[8:11]
	v_mfma_f32_16x16x32_bf16 v[60:63], v[148:151], v[188:191], v[60:63]
	v_mfma_f32_16x16x32_bf16 v[56:59], v[164:167], v[188:191], v[56:59]
	v_mfma_f32_16x16x32_bf16 v[44:47], v[148:151], v[196:199], v[44:47]
	v_mfma_f32_16x16x32_bf16 v[40:43], v[164:167], v[196:199], v[40:43]
	v_mfma_f32_16x16x32_bf16 v[28:31], v[148:151], v[204:207], v[28:31]
	v_mfma_f32_16x16x32_bf16 v[24:27], v[164:167], v[204:207], v[24:27]
	v_mfma_f32_16x16x32_bf16 v[12:15], v[148:151], v[212:215], v[12:15]
	v_mfma_f32_16x16x32_bf16 v[8:11], v[164:167], v[212:215], v[8:11]
	s_setprio 0
	s_setprio 1
	v_mfma_f32_16x16x32_bf16 v[52:55], v[168:171], v[184:187], v[52:55]
	v_mfma_f32_16x16x32_bf16 v[48:51], v[176:179], v[184:187], v[48:51]
	v_mfma_f32_16x16x32_bf16 v[36:39], v[168:171], v[192:195], v[36:39]
	v_mfma_f32_16x16x32_bf16 v[32:35], v[176:179], v[192:195], v[32:35]
	v_mfma_f32_16x16x32_bf16 v[20:23], v[168:171], v[200:203], v[20:23]
	v_mfma_f32_16x16x32_bf16 v[16:19], v[176:179], v[200:203], v[16:19]
	v_mfma_f32_16x16x32_bf16 v[4:7], v[168:171], v[208:211], v[4:7]
	v_mfma_f32_16x16x32_bf16 v[0:3], v[176:179], v[208:211], v[0:3]
	v_mfma_f32_16x16x32_bf16 v[52:55], v[172:175], v[188:191], v[52:55]
	v_mfma_f32_16x16x32_bf16 v[48:51], v[180:183], v[188:191], v[48:51]
	v_mfma_f32_16x16x32_bf16 v[36:39], v[172:175], v[196:199], v[36:39]
	v_mfma_f32_16x16x32_bf16 v[32:35], v[180:183], v[196:199], v[32:35]
	v_mfma_f32_16x16x32_bf16 v[20:23], v[172:175], v[204:207], v[20:23]
	v_mfma_f32_16x16x32_bf16 v[16:19], v[180:183], v[204:207], v[16:19]
	v_mfma_f32_16x16x32_bf16 v[4:7], v[172:175], v[212:215], v[4:7]
	v_mfma_f32_16x16x32_bf16 v[0:3], v[180:183], v[212:215], v[0:3]
	s_setprio 0
	s_barrier
	s_add_i32 s78, s78, 2
	s_add_u32 s48, s48, 0x100
	s_addc_u32 s49, s49, 0
	s_add_u32 s76, s76, 0x100
	s_addc_u32 s77, s77, 0
	s_cmp_gt_u32 s78, 29

; #define PG8_STAGE(bufoff, gbase, voff) do { _Pragma("unroll") for (int _i = 0; _i < 2; ++_i) \
;         __builtin_amdgcn_global_load_lds((const unsigned*)((const char*)(gbase) + (voff)[_i]), (PG8_LAS unsigned*)(lds + (bufoff) + ldsw + _i * 8192), 16, 0, 0); } while (0)
; #define PG8_LDA(dst, b, h) do { _Pragma("unroll") for (int m = 0; m < 4; ++m) _Pragma("unroll") for (int k = 0; k < 2; ++k) dst[m][k] = *(const PG8_LAS bf16x8*)(lds + PG8_SA(b, h) + aoff + m * 2048 + k * 1024); } while (0)
; #define PG8_LDB(dst, b, h) do { _Pragma("unroll") for (int n = 0; n < 2; ++n) _Pragma("unroll") for (int k = 0; k < 2; ++k) dst[n][k] = *(const PG8_LAS bf16x8*)(lds + PG8_SB(b, h) + boff + n * 2048 + k * 1024); } while (0)
; #define PG8_WAIT_V(n) asm volatile("s_waitcnt vmcnt(" #n ")" ::: "memory")
; #define PG8_WAIT_L(n) asm volatile("s_waitcnt lgkmcnt(" #n ")" ::: "memory")
; #define PG8_BAR __builtin_amdgcn_s_barrier()
; #define PG8_SCHED __builtin_amdgcn_sched_barrier(0)
; template <class Epi, class Sched, bool ALIGN_EPI = false, bool SP2 = false>
; __device__ __forceinline__ void gemm_phase(PG8_LAS unsigned char* lds, const Gemm g, const Sched& S, const Epi& E) {
;     ...
;         const bool has_next = S.next(ui + 1, nxt);
;         const char* nA = has_next ? (const char*)g.A + (size_t)nxt.pm * tstep : cA; const char* nB = has_next ? (const char*)g.Bt + (size_t)nxt.pn * tstep : cB;
;         for (int t = 0; t < nt; t += 2) {
;             const bool last = (t == nt - 2);
;             const char* a1 = cA + (size_t)(t + 1) * kstep;
;             const char* a2 = last ? nA : cA + (size_t)(t + 2) * kstep; const char* b2 = last ? nB : cB + (size_t)(t + 2) * kstep;
;             const char* a3 = a2 + kstep; const char* b3 = b2 + kstep;
;             if (last && has_next) S.a_ready(nxt);
;             if constexpr (SP2) {
;             PG8_LDB(B0, 0, 0); PG8_LDB(B1, 0, 1); PG8_SCHED; PG8_LDA(At, 0, 0); PG8_STAGE(PG8_SA(1, 1), a1 + hstep, voffA);
;             PG8_WAIT_V(8); PG8_WAIT_L(0); PG8_BAR; PG8_MMA(0, 0, At, B0); PG8_MMA(0, 1, At, B1); PG8_BAR; PG8_SCHED;
;             PG8_LDA(At, 0, 1); PG8_STAGE(PG8_SB(0, 0), b2, voffB); PG8_STAGE(PG8_SB(0, 1), b2 + hstep, voffB); PG8_STAGE(PG8_SA(0, 0), a2, voffA);
;             PG8_WAIT_V(8); PG8_WAIT_L(0); PG8_BAR; PG8_MMA(1, 0, At, B0); PG8_MMA(1, 1, At, B1); PG8_BAR; PG8_SCHED;
.LBB0_932:
	s_ashr_i32 s37, s36, 31
	s_lshl_b64 s[28:29], s[36:37], 18
	s_add_u32 s38, s52, s28
	s_addc_u32 s39, s53, s29
	s_and_b64 s[28:29], s[4:5], exec
	s_cselect_b32 s28, s39, s47
	s_cselect_b32 s29, s38, s46
	s_ashr_i32 s35, s34, 31
	s_lshl_b64 s[40:41], s[34:35], 18
	s_add_u32 s40, s54, s40
	s_addc_u32 s41, s55, s41
	s_and_b64 s[50:51], s[4:5], exec
	s_cselect_b32 s35, s41, s49
	s_cselect_b32 s37, s40, s48
	s_add_u32 s46, s46, 0x20080
	s_addc_u32 s47, s47, 0
	s_add_u32 s43, s48, 0x100
	s_addc_u32 s67, s49, 0
	s_mov_b32 s68, -2
	s_waitcnt lgkmcnt(0)
	ds_read_b128 v[144:147], v151
	ds_read_b128 v[156:159], v151 offset:1024
	ds_read_b128 v[160:163], v151 offset:2048
	ds_read_b128 v[164:167], v151 offset:3072
	ds_read_b128 v[168:171], v152
	ds_read_b128 v[172:175], v152 offset:1024
	ds_read_b128 v[176:179], v152 offset:2048
	ds_read_b128 v[180:183], v152 offset:3072
	s_add_u32 s48, s46, 0xfffe0080
	s_addc_u32 s49, s47, -1
	s_cmp_eq_u32 s68, 4
	s_cselect_b32 s51, s28, s49
	s_cselect_b32 s50, s29, s48
	s_cselect_b32 s49, s35, s67
	s_cselect_b32 s48, s37, s43
	v_lshl_add_u64 v[216:217], s[46:47], 0, v[136:137]
	s_add_i32 m0, s45, 0xc000
	ds_read_b128 v[184:187], v153
	ds_read_b128 v[188:191], v153 offset:1024
	ds_read_b128 v[192:195], v153 offset:2048
	ds_read_b128 v[196:199], v153 offset:3072
	ds_read_b128 v[200:203], v153 offset:4096
	ds_read_b128 v[204:207], v153 offset:5120
	ds_read_b128 v[208:211], v153 offset:6144
	ds_read_b128 v[212:215], v153 offset:7168
	global_load_lds_dwordx4 v[216:217], off
	v_lshl_add_u64 v[216:217], s[46:47], 0, v[138:139]
	s_add_i32 m0, s45, 0xe000
	s_nop 0
	global_load_lds_dwordx4 v[216:217], off
	s_waitcnt vmcnt(8)
	s_waitcnt lgkmcnt(0)
	s_barrier
	s_setprio 1
	s_waitcnt lgkmcnt(0)
	v_mfma_f32_16x16x32_bf16 v[124:127], v[144:147], v[184:187], 0
	v_mfma_f32_16x16x32_bf16 v[120:123], v[160:163], v[184:187], 0
	v_mfma_f32_16x16x32_bf16 v[108:111], v[144:147], v[192:195], 0
	v_mfma_f32_16x16x32_bf16 v[104:107], v[160:163], v[192:195], 0
	v_mfma_f32_16x16x32_bf16 v[92:95], v[144:147], v[200:203], 0
	v_mfma_f32_16x16x32_bf16 v[88:91], v[160:163], v[200:203], 0
	v_mfma_f32_16x16x32_bf16 v[76:79], v[144:147], v[208:211], 0
	v_mfma_f32_16x16x32_bf16 v[72:75], v[160:163], v[208:211], 0
	v_mfma_f32_16x16x32_bf16 v[124:127], v[156:159], v[188:191], v[124:127]
	v_mfma_f32_16x16x32_bf16 v[120:123], v[164:167], v[188:191], v[120:123]
	v_mfma_f32_16x16x32_bf16 v[108:111], v[156:159], v[196:199], v[108:111]
	v_mfma_f32_16x16x32_bf16 v[104:107], v[164:167], v[196:199], v[104:107]
	v_mfma_f32_16x16x32_bf16 v[92:95], v[156:159], v[204:207], v[92:95]
	v_mfma_f32_16x16x32_bf16 v[88:91], v[164:167], v[204:207], v[88:91]
	v_mfma_f32_16x16x32_bf16 v[76:79], v[156:159], v[212:215], v[76:79]
	v_mfma_f32_16x16x32_bf16 v[72:75], v[164:167], v[212:215], v[72:75]
	s_setprio 0
	s_setprio 1
	v_mfma_f32_16x16x32_bf16 v[116:119], v[168:171], v[184:187], 0
	v_mfma_f32_16x16x32_bf16 v[112:115], v[176:179], v[184:187], 0
	v_mfma_f32_16x16x32_bf16 v[100:103], v[168:171], v[192:195], 0
	v_mfma_f32_16x16x32_bf16 v[96:99], v[176:179], v[192:195], 0
	v_mfma_f32_16x16x32_bf16 v[84:87], v[168:171], v[200:203], 0
	v_mfma_f32_16x16x32_bf16 v[80:83], v[176:179], v[200:203], 0
	v_mfma_f32_16x16x32_bf16 v[68:71], v[168:171], v[208:211], 0
	v_mfma_f32_16x16x32_bf16 v[64:67], v[176:179], v[208:211], 0
	v_mfma_f32_16x16x32_bf16 v[116:119], v[172:175], v[188:191], v[116:119]
	v_mfma_f32_16x16x32_bf16 v[112:115], v[180:183], v[188:191], v[112:115]
	v_mfma_f32_16x16x32_bf16 v[100:103], v[172:175], v[196:199], v[100:103]
	v_mfma_f32_16x16x32_bf16 v[96:99], v[180:183], v[196:199], v[96:99]
	v_mfma_f32_16x16x32_bf16 v[84:87], v[172:175], v[204:207], v[84:87]
	v_mfma_f32_16x16x32_bf16 v[80:83], v[180:183], v[204:207], v[80:83]
	v_mfma_f32_16x16x32_bf16 v[68:71], v[172:175], v[212:215], v[68:71]
	v_mfma_f32_16x16x32_bf16 v[64:67], v[180:183], v[212:215], v[64:67]
	s_setprio 0
	s_barrier
	s_add_i32 s69, s65, s56
	v_lshl_add_u64 v[216:217], s[48:49], 0, v[130:131]
	s_mov_b32 m0, s69
	ds_read_b128 v[184:187], v153 offset:16384
	ds_read_b128 v[188:191], v153 offset:17408
	ds_read_b128 v[192:195], v153 offset:18432
	ds_read_b128 v[196:199], v153 offset:19456
	ds_read_b128 v[200:203], v153 offset:20480
	ds_read_b128 v[204:207], v153 offset:21504
	ds_read_b128 v[208:211], v153 offset:22528
	ds_read_b128 v[212:215], v153 offset:23552
	global_load_lds_dwordx4 v[216:217], off
	s_add_i32 m0, s69, 0x2000
	s_add_u32 s70, s48, 0x20000
	v_lshl_add_u64 v[220:221], s[48:49], 0, v[134:135]
	s_addc_u32 s71, s49, 0
	s_add_i32 s69, s66, s56
	global_load_lds_dwordx4 v[220:221], off
	v_lshl_add_u64 v[222:223], s[70:71], 0, v[130:131]
	s_mov_b32 m0, s69
	v_lshl_add_u64 v[224:225], s[50:51], 0, v[132:133]
	global_load_lds_dwordx4 v[222:223], off
	v_lshl_add_u64 v[222:223], s[70:71], 0, v[134:135]
	s_add_i32 m0, s69, 0x2000
	s_nop 0
	global_load_lds_dwordx4 v[222:223], off
	v_lshl_add_u64 v[222:223], s[50:51], 0, v[128:129]
	s_mov_b32 m0, s45
	s_nop 0
	global_load_lds_dwordx4 v[222:223], off
	s_mov_b32 m0, s57
	s_nop 0
	global_load_lds_dwordx4 v[224:225], off
	s_waitcnt vmcnt(8)
	s_waitcnt lgkmcnt(0)
	s_barrier
; #define PG8_STAGE(bufoff, gbase, voff) do { _Pragma("unroll") for (int _i = 0; _i < 2; ++_i) \
;         __builtin_amdgcn_global_load_lds((const unsigned*)((const char*)(gbase) + (voff)[_i]), (PG8_LAS unsigned*)(lds + (bufoff) + ldsw + _i * 8192), 16, 0, 0); } while (0)
; #define PG8_LDA(dst, b, h) do { _Pragma("unroll") for (int m = 0; m < 4; ++m) _Pragma("unroll") for (int k = 0; k < 2; ++k) dst[m][k] = *(const PG8_LAS bf16x8*)(lds + PG8_SA(b, h) + aoff + m * 2048 + k * 1024); } while (0)
; #define PG8_LDB(dst, b, h) do { _Pragma("unroll") for (int n = 0; n < 2; ++n) _Pragma("unroll") for (int k = 0; k < 2; ++k) dst[n][k] = *(const PG8_LAS bf16x8*)(lds + PG8_SB(b, h) + boff + n * 2048 + k * 1024); } while (0)
; #define PG8_MMA(ai, bj, At, Bt) do { __builtin_amdgcn_s_setprio(1); _Pragma("unroll") for (int m = 0; m < 4; ++m) _Pragma("unroll") for (int n = 0; n < 2; ++n) _Pragma("unroll") for (int k = 0; k < 2; ++k) \
;         acc[ai][bj][m][n] = __builtin_amdgcn_mfma_f32_16x16x32_bf16(Bt[n][k], At[m][k], acc[ai][bj][m][n], 0, 0, 0); __builtin_amdgcn_s_setprio(0); } while (0)
; #define PG8_WAIT_V(n) asm volatile("s_waitcnt vmcnt(" #n ")" ::: "memory")
; #define PG8_WAIT_L(n) asm volatile("s_waitcnt lgkmcnt(" #n ")" ::: "memory")
; #define PG8_BAR __builtin_amdgcn_s_barrier()
; #define PG8_SCHED __builtin_amdgcn_sched_barrier(0)
; template <class Epi, class Sched, bool ALIGN_EPI = false, bool SP2 = false>
; __device__ __forceinline__ void gemm_phase(PG8_LAS unsigned char* lds, const Gemm g, const Sched& S, const Epi& E) {
;     ...
;             PG8_WAIT_V(8); PG8_WAIT_L(0); PG8_BAR; PG8_MMA(1, 0, At, B0); PG8_MMA(1, 1, At, B1); PG8_BAR; PG8_SCHED;
;             PG8_LDB(B0, 1, 0); PG8_LDB(B1, 1, 1); PG8_SCHED; PG8_LDA(At, 1, 0); PG8_STAGE(PG8_SA(0, 1), a2 + hstep, voffA);
;             PG8_WAIT_V(8); PG8_WAIT_L(0); PG8_BAR; PG8_MMA(0, 0, At, B0); PG8_MMA(0, 1, At, B1); PG8_BAR; PG8_SCHED;
	s_setprio 1
	s_waitcnt lgkmcnt(0)
	v_mfma_f32_16x16x32_bf16 v[60:63], v[144:147], v[184:187], 0
	v_mfma_f32_16x16x32_bf16 v[56:59], v[160:163], v[184:187], 0
	v_mfma_f32_16x16x32_bf16 v[44:47], v[144:147], v[192:195], 0
	v_mfma_f32_16x16x32_bf16 v[40:43], v[160:163], v[192:195], 0
	v_mfma_f32_16x16x32_bf16 v[28:31], v[144:147], v[200:203], 0
	v_mfma_f32_16x16x32_bf16 v[24:27], v[160:163], v[200:203], 0
	v_mfma_f32_16x16x32_bf16 v[12:15], v[144:147], v[208:211], 0
	v_mfma_f32_16x16x32_bf16 v[8:11], v[160:163], v[208:211], 0
	v_mfma_f32_16x16x32_bf16 v[60:63], v[156:159], v[188:191], v[60:63]
	v_mfma_f32_16x16x32_bf16 v[56:59], v[164:167], v[188:191], v[56:59]
	v_mfma_f32_16x16x32_bf16 v[44:47], v[156:159], v[196:199], v[44:47]
	v_mfma_f32_16x16x32_bf16 v[40:43], v[164:167], v[196:199], v[40:43]
	v_mfma_f32_16x16x32_bf16 v[28:31], v[156:159], v[204:207], v[28:31]
	v_mfma_f32_16x16x32_bf16 v[24:27], v[164:167], v[204:207], v[24:27]
	v_mfma_f32_16x16x32_bf16 v[12:15], v[156:159], v[212:215], v[12:15]
	v_mfma_f32_16x16x32_bf16 v[8:11], v[164:167], v[212:215], v[8:11]
	s_setprio 0
	s_setprio 1
	v_mfma_f32_16x16x32_bf16 v[52:55], v[168:171], v[184:187], 0
	v_mfma_f32_16x16x32_bf16 v[48:51], v[176:179], v[184:187], 0
	v_mfma_f32_16x16x32_bf16 v[36:39], v[168:171], v[192:195], 0
	v_mfma_f32_16x16x32_bf16 v[32:35], v[176:179], v[192:195], 0
	v_mfma_f32_16x16x32_bf16 v[20:23], v[168:171], v[200:203], 0
	v_mfma_f32_16x16x32_bf16 v[16:19], v[176:179], v[200:203], 0
	v_mfma_f32_16x16x32_bf16 v[4:7], v[168:171], v[208:211], 0
	v_mfma_f32_16x16x32_bf16 v[0:3], v[176:179], v[208:211], 0
	v_mfma_f32_16x16x32_bf16 v[52:55], v[172:175], v[188:191], v[52:55]
	v_mfma_f32_16x16x32_bf16 v[48:51], v[180:183], v[188:191], v[48:51]
	v_mfma_f32_16x16x32_bf16 v[36:39], v[172:175], v[196:199], v[36:39]
	v_mfma_f32_16x16x32_bf16 v[32:35], v[180:183], v[196:199], v[32:35]
	v_mfma_f32_16x16x32_bf16 v[20:23], v[172:175], v[204:207], v[20:23]
	v_mfma_f32_16x16x32_bf16 v[16:19], v[180:183], v[204:207], v[16:19]
	v_mfma_f32_16x16x32_bf16 v[4:7], v[172:175], v[212:215], v[4:7]
	v_mfma_f32_16x16x32_bf16 v[0:3], v[180:183], v[212:215], v[0:3]
	s_setprio 0
	s_barrier
	s_add_i32 s69, 0, 0x18000
	v_add_u32_e32 v155, s69, v149
	s_add_i32 s70, 0, 0x1c000
	ds_read_b128 v[144:147], v155
	ds_read_b128 v[156:159], v155 offset:1024
	ds_read_b128 v[160:163], v155 offset:2048
	ds_read_b128 v[164:167], v155 offset:3072
	v_add_u32_e32 v155, s70, v149
	ds_read_b128 v[168:171], v155
	ds_read_b128 v[172:175], v155 offset:1024
	ds_read_b128 v[176:179], v155 offset:2048
	ds_read_b128 v[180:183], v155 offset:3072
	s_add_u32 s50, s50, 0x20000
	s_addc_u32 s51, s51, 0
	s_mov_b32 m0, s58
	v_lshl_add_u64 v[226:227], s[50:51], 0, v[128:129]
	ds_read_b128 v[184:187], v153 offset:32768
	ds_read_b128 v[188:191], v153 offset:33792
	ds_read_b128 v[192:195], v153 offset:34816
	ds_read_b128 v[196:199], v153 offset:35840
	ds_read_b128 v[200:203], v153 offset:36864
	ds_read_b128 v[204:207], v153 offset:37888
	ds_read_b128 v[208:211], v153 offset:38912
	ds_read_b128 v[212:215], v153 offset:39936
	global_load_lds_dwordx4 v[226:227], off
	v_lshl_add_u64 v[226:227], s[50:51], 0, v[132:133]
	s_mov_b32 m0, s59
	s_nop 0
	global_load_lds_dwordx4 v[226:227], off
	s_waitcnt vmcnt(8)
	s_waitcnt lgkmcnt(0)
	s_barrier
	s_setprio 1
	s_waitcnt lgkmcnt(0)
	v_mfma_f32_16x16x32_bf16 v[124:127], v[144:147], v[184:187], v[124:127]
	v_mfma_f32_16x16x32_bf16 v[120:123], v[160:163], v[184:187], v[120:123]
	v_mfma_f32_16x16x32_bf16 v[108:111], v[144:147], v[192:195], v[108:111]
	v_mfma_f32_16x16x32_bf16 v[104:107], v[160:163], v[192:195], v[104:107]
	v_mfma_f32_16x16x32_bf16 v[92:95], v[144:147], v[200:203], v[92:95]
	v_mfma_f32_16x16x32_bf16 v[88:91], v[160:163], v[200:203], v[88:91]
	v_mfma_f32_16x16x32_bf16 v[76:79], v[144:147], v[208:211], v[76:79]
	v_mfma_f32_16x16x32_bf16 v[72:75], v[160:163], v[208:211], v[72:75]
	v_mfma_f32_16x16x32_bf16 v[124:127], v[156:159], v[188:191], v[124:127]
	v_mfma_f32_16x16x32_bf16 v[120:123], v[164:167], v[188:191], v[120:123]
	v_mfma_f32_16x16x32_bf16 v[108:111], v[156:159], v[196:199], v[108:111]
	v_mfma_f32_16x16x32_bf16 v[104:107], v[164:167], v[196:199], v[104:107]
	v_mfma_f32_16x16x32_bf16 v[92:95], v[156:159], v[204:207], v[92:95]
	v_mfma_f32_16x16x32_bf16 v[88:91], v[164:167], v[204:207], v[88:91]
	v_mfma_f32_16x16x32_bf16 v[76:79], v[156:159], v[212:215], v[76:79]
	v_mfma_f32_16x16x32_bf16 v[72:75], v[164:167], v[212:215], v[72:75]
	s_setprio 0
	s_setprio 1
	v_mfma_f32_16x16x32_bf16 v[116:119], v[168:171], v[184:187], v[116:119]
	v_mfma_f32_16x16x32_bf16 v[112:115], v[176:179], v[184:187], v[112:115]
	v_mfma_f32_16x16x32_bf16 v[100:103], v[168:171], v[192:195], v[100:103]
	v_mfma_f32_16x16x32_bf16 v[96:99], v[176:179], v[192:195], v[96:99]
	v_mfma_f32_16x16x32_bf16 v[84:87], v[168:171], v[200:203], v[84:87]
	v_mfma_f32_16x16x32_bf16 v[80:83], v[176:179], v[200:203], v[80:83]
	v_mfma_f32_16x16x32_bf16 v[68:71], v[168:171], v[208:211], v[68:71]
	v_mfma_f32_16x16x32_bf16 v[64:67], v[176:179], v[208:211], v[64:67]
	v_mfma_f32_16x16x32_bf16 v[116:119], v[172:175], v[188:191], v[116:119]
	v_mfma_f32_16x16x32_bf16 v[112:115], v[180:183], v[188:191], v[112:115]
	v_mfma_f32_16x16x32_bf16 v[100:103], v[172:175], v[196:199], v[100:103]
	v_mfma_f32_16x16x32_bf16 v[96:99], v[180:183], v[196:199], v[96:99]
	v_mfma_f32_16x16x32_bf16 v[84:87], v[172:175], v[204:207], v[84:87]
	v_mfma_f32_16x16x32_bf16 v[80:83], v[180:183], v[204:207], v[80:83]
	v_mfma_f32_16x16x32_bf16 v[68:71], v[172:175], v[212:215], v[68:71]
	v_mfma_f32_16x16x32_bf16 v[64:67], v[180:183], v[212:215], v[64:67]
	s_setprio 0
	s_barrier
; #define PG8_STAGE(bufoff, gbase, voff) do { _Pragma("unroll") for (int _i = 0; _i < 2; ++_i) \
;         __builtin_amdgcn_global_load_lds((const unsigned*)((const char*)(gbase) + (voff)[_i]), (PG8_LAS unsigned*)(lds + (bufoff) + ldsw + _i * 8192), 16, 0, 0); } while (0)
; #define PG8_LDA(dst, b, h) do { _Pragma("unroll") for (int m = 0; m < 4; ++m) _Pragma("unroll") for (int k = 0; k < 2; ++k) dst[m][k] = *(const PG8_LAS bf16x8*)(lds + PG8_SA(b, h) + aoff + m * 2048 + k * 1024); } while (0)
; #define PG8_MMA(ai, bj, At, Bt) do { __builtin_amdgcn_s_setprio(1); _Pragma("unroll") for (int m = 0; m < 4; ++m) _Pragma("unroll") for (int n = 0; n < 2; ++n) _Pragma("unroll") for (int k = 0; k < 2; ++k) \
;         acc[ai][bj][m][n] = __builtin_amdgcn_mfma_f32_16x16x32_bf16(Bt[n][k], At[m][k], acc[ai][bj][m][n], 0, 0, 0); __builtin_amdgcn_s_setprio(0); } while (0)
; #define PG8_WAIT_V(n) asm volatile("s_waitcnt vmcnt(" #n ")" ::: "memory")
; #define PG8_WAIT_L(n) asm volatile("s_waitcnt lgkmcnt(" #n ")" ::: "memory")
; #define PG8_BAR __builtin_amdgcn_s_barrier()
; #define PG8_SCHED __builtin_amdgcn_sched_barrier(0)
; template <class Epi, class Sched, bool ALIGN_EPI = false, bool SP2 = false>
; __device__ __forceinline__ void gemm_phase(PG8_LAS unsigned char* lds, const Gemm g, const Sched& S, const Epi& E) {
;     ...
;             PG8_LDA(At, 1, 1); PG8_STAGE(PG8_SB(1, 0), b3, voffB); PG8_STAGE(PG8_SB(1, 1), b3 + hstep, voffB); PG8_STAGE(PG8_SA(1, 0), a3, voffA);
;             PG8_WAIT_V(8); PG8_WAIT_L(0); PG8_BAR; PG8_MMA(1, 0, At, B0); PG8_MMA(1, 1, At, B1); PG8_BAR; PG8_SCHED;
	s_add_i32 s50, s69, s56
	v_lshl_add_u64 v[216:217], v[216:217], 0, s[20:21]
	s_mov_b32 m0, s50
	ds_read_b128 v[184:187], v153 offset:49152
	ds_read_b128 v[188:191], v153 offset:50176
	ds_read_b128 v[192:195], v153 offset:51200
	ds_read_b128 v[196:199], v153 offset:52224
	ds_read_b128 v[200:203], v153 offset:53248
	ds_read_b128 v[204:207], v153 offset:54272
	ds_read_b128 v[208:211], v153 offset:55296
	ds_read_b128 v[212:215], v153 offset:56320
	global_load_lds_dwordx4 v[216:217], off
	s_add_i32 m0, s50, 0x2000
	s_add_u32 s48, s48, 0x20080
	v_lshl_add_u64 v[216:217], v[220:221], 0, s[20:21]
	s_addc_u32 s49, s49, 0
	s_add_i32 s50, s70, s56
	global_load_lds_dwordx4 v[216:217], off
	v_lshl_add_u64 v[216:217], s[48:49], 0, v[130:131]
	s_mov_b32 m0, s50
	s_nop 0
	global_load_lds_dwordx4 v[216:217], off
	v_lshl_add_u64 v[216:217], s[48:49], 0, v[134:135]
	s_add_i32 m0, s50, 0x2000
	s_nop 0
	global_load_lds_dwordx4 v[216:217], off
	v_lshl_add_u64 v[216:217], v[222:223], 0, s[20:21]
	s_mov_b32 m0, s61
	s_nop 0
	global_load_lds_dwordx4 v[216:217], off
	v_lshl_add_u64 v[216:217], v[224:225], 0, s[20:21]
	s_mov_b32 m0, s62
	s_nop 0
	global_load_lds_dwordx4 v[216:217], off
	s_waitcnt vmcnt(8)
	s_waitcnt lgkmcnt(0)
	s_barrier
	s_setprio 1
	s_waitcnt lgkmcnt(0)
	v_mfma_f32_16x16x32_bf16 v[60:63], v[144:147], v[184:187], v[60:63]
	v_mfma_f32_16x16x32_bf16 v[56:59], v[160:163], v[184:187], v[56:59]
	v_mfma_f32_16x16x32_bf16 v[44:47], v[144:147], v[192:195], v[44:47]
	v_mfma_f32_16x16x32_bf16 v[40:43], v[160:163], v[192:195], v[40:43]
	v_mfma_f32_16x16x32_bf16 v[28:31], v[144:147], v[200:203], v[28:31]
	v_mfma_f32_16x16x32_bf16 v[24:27], v[160:163], v[200:203], v[24:27]
	v_mfma_f32_16x16x32_bf16 v[12:15], v[144:147], v[208:211], v[12:15]
	v_mfma_f32_16x16x32_bf16 v[8:11], v[160:163], v[208:211], v[8:11]
	v_mfma_f32_16x16x32_bf16 v[60:63], v[156:159], v[188:191], v[60:63]
	v_mfma_f32_16x16x32_bf16 v[56:59], v[164:167], v[188:191], v[56:59]
	v_mfma_f32_16x16x32_bf16 v[44:47], v[156:159], v[196:199], v[44:47]
	v_mfma_f32_16x16x32_bf16 v[40:43], v[164:167], v[196:199], v[40:43]
	v_mfma_f32_16x16x32_bf16 v[28:31], v[156:159], v[204:207], v[28:31]
	v_mfma_f32_16x16x32_bf16 v[24:27], v[164:167], v[204:207], v[24:27]
	v_mfma_f32_16x16x32_bf16 v[12:15], v[156:159], v[212:215], v[12:15]
	v_mfma_f32_16x16x32_bf16 v[8:11], v[164:167], v[212:215], v[8:11]
	s_setprio 0
	s_setprio 1
	v_mfma_f32_16x16x32_bf16 v[52:55], v[168:171], v[184:187], v[52:55]
	v_mfma_f32_16x16x32_bf16 v[48:51], v[176:179], v[184:187], v[48:51]
	v_mfma_f32_16x16x32_bf16 v[36:39], v[168:171], v[192:195], v[36:39]
	v_mfma_f32_16x16x32_bf16 v[32:35], v[176:179], v[192:195], v[32:35]
	v_mfma_f32_16x16x32_bf16 v[20:23], v[168:171], v[200:203], v[20:23]
	v_mfma_f32_16x16x32_bf16 v[16:19], v[176:179], v[200:203], v[16:19]
	v_mfma_f32_16x16x32_bf16 v[4:7], v[168:171], v[208:211], v[4:7]
	v_mfma_f32_16x16x32_bf16 v[0:3], v[176:179], v[208:211], v[0:3]
	v_mfma_f32_16x16x32_bf16 v[52:55], v[172:175], v[188:191], v[52:55]
	v_mfma_f32_16x16x32_bf16 v[48:51], v[180:183], v[188:191], v[48:51]
	v_mfma_f32_16x16x32_bf16 v[36:39], v[172:175], v[196:199], v[36:39]
	v_mfma_f32_16x16x32_bf16 v[32:35], v[180:183], v[196:199], v[32:35]
	v_mfma_f32_16x16x32_bf16 v[20:23], v[172:175], v[204:207], v[20:23]
	v_mfma_f32_16x16x32_bf16 v[16:19], v[180:183], v[204:207], v[16:19]
	v_mfma_f32_16x16x32_bf16 v[4:7], v[172:175], v[212:215], v[4:7]
	v_mfma_f32_16x16x32_bf16 v[0:3], v[180:183], v[212:215], v[0:3]
	s_setprio 0
	s_barrier
	s_add_i32 s68, s68, 2
	s_add_u32 s46, s46, 0x100
	s_addc_u32 s47, s47, 0
	s_add_u32 s43, s43, 0x100
	s_addc_u32 s67, s67, 0
	s_cmp_gt_u32 s68, 5

; #define PG8_STAGE(bufoff, gbase, voff) do { _Pragma("unroll") for (int _i = 0; _i < 2; ++_i) \
;         __builtin_amdgcn_global_load_lds((const unsigned*)((const char*)(gbase) + (voff)[_i]), (PG8_LAS unsigned*)(lds + (bufoff) + ldsw + _i * 8192), 16, 0, 0); } while (0)
; #define PG8_LDA(dst, b, h) do { _Pragma("unroll") for (int m = 0; m < 4; ++m) _Pragma("unroll") for (int k = 0; k < 2; ++k) dst[m][k] = *(const PG8_LAS bf16x8*)(lds + PG8_SA(b, h) + aoff + m * 2048 + k * 1024); } while (0)
; #define PG8_LDB(dst, b, h) do { _Pragma("unroll") for (int n = 0; n < 2; ++n) _Pragma("unroll") for (int k = 0; k < 2; ++k) dst[n][k] = *(const PG8_LAS bf16x8*)(lds + PG8_SB(b, h) + boff + n * 2048 + k * 1024); } while (0)
; #define PG8_WAIT_V(n) asm volatile("s_waitcnt vmcnt(" #n ")" ::: "memory")
; #define PG8_WAIT_L(n) asm volatile("s_waitcnt lgkmcnt(" #n ")" ::: "memory")
; #define PG8_BAR __builtin_amdgcn_s_barrier()
; #define PG8_SCHED __builtin_amdgcn_sched_barrier(0)
; template <class Epi, class Sched, bool ALIGN_EPI = false, bool SP2 = false>
; __device__ __forceinline__ void gemm_phase(PG8_LAS unsigned char* lds, const Gemm g, const Sched& S, const Epi& E) {
;     ...
;         const bool has_next = S.next(ui + 1, nxt);
;         const char* nA = has_next ? (const char*)g.A + (size_t)nxt.pm * tstep : cA; const char* nB = has_next ? (const char*)g.Bt + (size_t)nxt.pn * tstep : cB;
;         for (int t = 0; t < nt; t += 2) {
;             const bool last = (t == nt - 2);
;             const char* a1 = cA + (size_t)(t + 1) * kstep;
;             const char* a2 = last ? nA : cA + (size_t)(t + 2) * kstep; const char* b2 = last ? nB : cB + (size_t)(t + 2) * kstep;
;             const char* a3 = a2 + kstep; const char* b3 = b2 + kstep;
;             if (last && has_next) S.a_ready(nxt);
;             if constexpr (SP2) {
;             PG8_LDB(B0, 0, 0); PG8_LDB(B1, 0, 1); PG8_SCHED; PG8_LDA(At, 0, 0); PG8_STAGE(PG8_SA(1, 1), a1 + hstep, voffA);
;             PG8_WAIT_V(8); PG8_WAIT_L(0); PG8_BAR; PG8_MMA(0, 0, At, B0); PG8_MMA(0, 1, At, B1); PG8_BAR; PG8_SCHED;
;             PG8_LDA(At, 0, 1); PG8_STAGE(PG8_SB(0, 0), b2, voffB); PG8_STAGE(PG8_SB(0, 1), b2 + hstep, voffB); PG8_STAGE(PG8_SA(0, 0), a2, voffA);
;             PG8_WAIT_V(8); PG8_WAIT_L(0); PG8_BAR; PG8_MMA(1, 0, At, B0); PG8_MMA(1, 1, At, B1); PG8_BAR; PG8_SCHED;
.LBB0_1019:
	s_ashr_i32 s35, s34, 31
	s_lshl_b64 s[28:29], s[34:35], 20
	s_add_u32 s36, s46, s28
	s_addc_u32 s37, s47, s29
	s_and_b64 s[28:29], s[2:3], exec
	s_cselect_b32 s28, s37, s41
	s_cselect_b32 s29, s36, s40
	s_ashr_i32 s31, s30, 31
	s_lshl_b64 s[38:39], s[30:31], 20
	s_add_u32 s38, s48, s38
	s_addc_u32 s39, s49, s39
	s_and_b64 s[44:45], s[2:3], exec
	s_cselect_b32 s31, s39, s43
	s_cselect_b32 s35, s38, s42
	s_add_u32 s40, s40, 0x80080
	s_addc_u32 s41, s41, 0
	s_add_u32 s65, s42, 0x100
	s_addc_u32 s66, s43, 0
	s_mov_b32 s67, -2
	ds_read_b128 v[144:147], v155
	ds_read_b128 v[148:151], v155 offset:1024
	ds_read_b128 v[160:163], v155 offset:2048
	ds_read_b128 v[164:167], v155 offset:3072
	ds_read_b128 v[168:171], v156
	ds_read_b128 v[172:175], v156 offset:1024
	ds_read_b128 v[176:179], v156 offset:2048
	ds_read_b128 v[180:183], v156 offset:3072
	s_add_u32 s42, s40, 0xfff80080
	s_addc_u32 s43, s41, -1
	s_cmp_eq_u32 s67, 28
	s_cselect_b32 s45, s28, s43
	s_cselect_b32 s44, s29, s42
	s_cselect_b32 s43, s31, s66
	s_cselect_b32 s42, s35, s65
	v_lshl_add_u64 v[216:217], s[40:41], 0, v[136:137]
	s_add_i32 m0, s53, 0xc000
	ds_read_b128 v[184:187], v157
	ds_read_b128 v[188:191], v157 offset:1024
	ds_read_b128 v[192:195], v157 offset:2048
	ds_read_b128 v[196:199], v157 offset:3072
	ds_read_b128 v[200:203], v157 offset:4096
	ds_read_b128 v[204:207], v157 offset:5120
	ds_read_b128 v[208:211], v157 offset:6144
	ds_read_b128 v[212:215], v157 offset:7168
	global_load_lds_dwordx4 v[216:217], off
	v_lshl_add_u64 v[216:217], s[40:41], 0, v[138:139]
	s_add_i32 m0, s53, 0xe000
	s_nop 0
	global_load_lds_dwordx4 v[216:217], off
	s_waitcnt vmcnt(8)
	s_waitcnt lgkmcnt(0)
	s_barrier
	s_setprio 1
	s_waitcnt lgkmcnt(0)
	v_mfma_f32_16x16x32_bf16 v[124:127], v[144:147], v[184:187], 0
	v_mfma_f32_16x16x32_bf16 v[120:123], v[160:163], v[184:187], 0
	v_mfma_f32_16x16x32_bf16 v[108:111], v[144:147], v[192:195], 0
	v_mfma_f32_16x16x32_bf16 v[104:107], v[160:163], v[192:195], 0
	v_mfma_f32_16x16x32_bf16 v[92:95], v[144:147], v[200:203], 0
	v_mfma_f32_16x16x32_bf16 v[88:91], v[160:163], v[200:203], 0
	v_mfma_f32_16x16x32_bf16 v[76:79], v[144:147], v[208:211], 0
	v_mfma_f32_16x16x32_bf16 v[72:75], v[160:163], v[208:211], 0
	v_mfma_f32_16x16x32_bf16 v[124:127], v[148:151], v[188:191], v[124:127]
	v_mfma_f32_16x16x32_bf16 v[120:123], v[164:167], v[188:191], v[120:123]
	v_mfma_f32_16x16x32_bf16 v[108:111], v[148:151], v[196:199], v[108:111]
	v_mfma_f32_16x16x32_bf16 v[104:107], v[164:167], v[196:199], v[104:107]
	v_mfma_f32_16x16x32_bf16 v[92:95], v[148:151], v[204:207], v[92:95]
	v_mfma_f32_16x16x32_bf16 v[88:91], v[164:167], v[204:207], v[88:91]
	v_mfma_f32_16x16x32_bf16 v[76:79], v[148:151], v[212:215], v[76:79]
	v_mfma_f32_16x16x32_bf16 v[72:75], v[164:167], v[212:215], v[72:75]
	s_setprio 0
	s_setprio 1
	v_mfma_f32_16x16x32_bf16 v[116:119], v[168:171], v[184:187], 0
	v_mfma_f32_16x16x32_bf16 v[112:115], v[176:179], v[184:187], 0
	v_mfma_f32_16x16x32_bf16 v[100:103], v[168:171], v[192:195], 0
	v_mfma_f32_16x16x32_bf16 v[96:99], v[176:179], v[192:195], 0
	v_mfma_f32_16x16x32_bf16 v[84:87], v[168:171], v[200:203], 0
	v_mfma_f32_16x16x32_bf16 v[80:83], v[176:179], v[200:203], 0
	v_mfma_f32_16x16x32_bf16 v[68:71], v[168:171], v[208:211], 0
	v_mfma_f32_16x16x32_bf16 v[64:67], v[176:179], v[208:211], 0
	v_mfma_f32_16x16x32_bf16 v[116:119], v[172:175], v[188:191], v[116:119]
	v_mfma_f32_16x16x32_bf16 v[112:115], v[180:183], v[188:191], v[112:115]
	v_mfma_f32_16x16x32_bf16 v[100:103], v[172:175], v[196:199], v[100:103]
	v_mfma_f32_16x16x32_bf16 v[96:99], v[180:183], v[196:199], v[96:99]
	v_mfma_f32_16x16x32_bf16 v[84:87], v[172:175], v[204:207], v[84:87]
	v_mfma_f32_16x16x32_bf16 v[80:83], v[180:183], v[204:207], v[80:83]
	v_mfma_f32_16x16x32_bf16 v[68:71], v[172:175], v[212:215], v[68:71]
	v_mfma_f32_16x16x32_bf16 v[64:67], v[180:183], v[212:215], v[64:67]
	s_setprio 0
	s_barrier
	s_add_i32 s68, s61, s50
	v_lshl_add_u64 v[216:217], s[42:43], 0, v[132:133]
	s_mov_b32 m0, s68
	ds_read_b128 v[184:187], v157 offset:16384
	ds_read_b128 v[188:191], v157 offset:17408
	ds_read_b128 v[192:195], v157 offset:18432
	ds_read_b128 v[196:199], v157 offset:19456
	ds_read_b128 v[200:203], v157 offset:20480
	ds_read_b128 v[204:207], v157 offset:21504
	ds_read_b128 v[208:211], v157 offset:22528
	ds_read_b128 v[212:215], v157 offset:23552
	global_load_lds_dwordx4 v[216:217], off
	s_add_i32 m0, s68, 0x2000
	s_add_u32 s68, s42, 0x80000
	v_lshl_add_u64 v[220:221], s[42:43], 0, v[128:129]
	s_addc_u32 s69, s43, 0
	s_add_i32 s70, s62, s50
	global_load_lds_dwordx4 v[220:221], off
	v_lshl_add_u64 v[222:223], s[68:69], 0, v[132:133]
	s_mov_b32 m0, s70
	v_lshl_add_u64 v[224:225], s[44:45], 0, v[130:131]
	global_load_lds_dwordx4 v[222:223], off
	v_lshl_add_u64 v[222:223], s[68:69], 0, v[128:129]
	s_add_i32 m0, s70, 0x2000
	s_nop 0
	global_load_lds_dwordx4 v[222:223], off
	v_lshl_add_u64 v[222:223], s[44:45], 0, v[134:135]
	s_mov_b32 m0, s53
	s_nop 0
	global_load_lds_dwordx4 v[222:223], off
	s_mov_b32 m0, s54
	s_nop 0
	global_load_lds_dwordx4 v[224:225], off
	s_waitcnt vmcnt(8)
	s_waitcnt lgkmcnt(0)
	s_barrier
; #define PG8_STAGE(bufoff, gbase, voff) do { _Pragma("unroll") for (int _i = 0; _i < 2; ++_i) \
;         __builtin_amdgcn_global_load_lds((const unsigned*)((const char*)(gbase) + (voff)[_i]), (PG8_LAS unsigned*)(lds + (bufoff) + ldsw + _i * 8192), 16, 0, 0); } while (0)
; #define PG8_LDA(dst, b, h) do { _Pragma("unroll") for (int m = 0; m < 4; ++m) _Pragma("unroll") for (int k = 0; k < 2; ++k) dst[m][k] = *(const PG8_LAS bf16x8*)(lds + PG8_SA(b, h) + aoff + m * 2048 + k * 1024); } while (0)
; #define PG8_LDB(dst, b, h) do { _Pragma("unroll") for (int n = 0; n < 2; ++n) _Pragma("unroll") for (int k = 0; k < 2; ++k) dst[n][k] = *(const PG8_LAS bf16x8*)(lds + PG8_SB(b, h) + boff + n * 2048 + k * 1024); } while (0)
; #define PG8_MMA(ai, bj, At, Bt) do { __builtin_amdgcn_s_setprio(1); _Pragma("unroll") for (int m = 0; m < 4; ++m) _Pragma("unroll") for (int n = 0; n < 2; ++n) _Pragma("unroll") for (int k = 0; k < 2; ++k) \
;         acc[ai][bj][m][n] = __builtin_amdgcn_mfma_f32_16x16x32_bf16(Bt[n][k], At[m][k], acc[ai][bj][m][n], 0, 0, 0); __builtin_amdgcn_s_setprio(0); } while (0)
; #define PG8_WAIT_V(n) asm volatile("s_waitcnt vmcnt(" #n ")" ::: "memory")
; #define PG8_WAIT_L(n) asm volatile("s_waitcnt lgkmcnt(" #n ")" ::: "memory")
; #define PG8_BAR __builtin_amdgcn_s_barrier()
; #define PG8_SCHED __builtin_amdgcn_sched_barrier(0)
; template <class Epi, class Sched, bool ALIGN_EPI = false, bool SP2 = false>
; __device__ __forceinline__ void gemm_phase(PG8_LAS unsigned char* lds, const Gemm g, const Sched& S, const Epi& E) {
;     ...
;             PG8_WAIT_V(8); PG8_WAIT_L(0); PG8_BAR; PG8_MMA(1, 0, At, B0); PG8_MMA(1, 1, At, B1); PG8_BAR; PG8_SCHED;
;             PG8_LDB(B0, 1, 0); PG8_LDB(B1, 1, 1); PG8_SCHED; PG8_LDA(At, 1, 0); PG8_STAGE(PG8_SA(0, 1), a2 + hstep, voffA);
;             PG8_WAIT_V(8); PG8_WAIT_L(0); PG8_BAR; PG8_MMA(0, 0, At, B0); PG8_MMA(0, 1, At, B1); PG8_BAR; PG8_SCHED;
	s_setprio 1
	s_waitcnt lgkmcnt(0)
	v_mfma_f32_16x16x32_bf16 v[60:63], v[144:147], v[184:187], 0
	v_mfma_f32_16x16x32_bf16 v[56:59], v[160:163], v[184:187], 0
	v_mfma_f32_16x16x32_bf16 v[44:47], v[144:147], v[192:195], 0
	v_mfma_f32_16x16x32_bf16 v[40:43], v[160:163], v[192:195], 0
	v_mfma_f32_16x16x32_bf16 v[28:31], v[144:147], v[200:203], 0
	v_mfma_f32_16x16x32_bf16 v[24:27], v[160:163], v[200:203], 0
	v_mfma_f32_16x16x32_bf16 v[12:15], v[144:147], v[208:211], 0
	v_mfma_f32_16x16x32_bf16 v[8:11], v[160:163], v[208:211], 0
	v_mfma_f32_16x16x32_bf16 v[60:63], v[148:151], v[188:191], v[60:63]
	v_mfma_f32_16x16x32_bf16 v[56:59], v[164:167], v[188:191], v[56:59]
	v_mfma_f32_16x16x32_bf16 v[44:47], v[148:151], v[196:199], v[44:47]
	v_mfma_f32_16x16x32_bf16 v[40:43], v[164:167], v[196:199], v[40:43]
	v_mfma_f32_16x16x32_bf16 v[28:31], v[148:151], v[204:207], v[28:31]
	v_mfma_f32_16x16x32_bf16 v[24:27], v[164:167], v[204:207], v[24:27]
	v_mfma_f32_16x16x32_bf16 v[12:15], v[148:151], v[212:215], v[12:15]
	v_mfma_f32_16x16x32_bf16 v[8:11], v[164:167], v[212:215], v[8:11]
	s_setprio 0
	s_setprio 1
	v_mfma_f32_16x16x32_bf16 v[52:55], v[168:171], v[184:187], 0
	v_mfma_f32_16x16x32_bf16 v[48:51], v[176:179], v[184:187], 0
	v_mfma_f32_16x16x32_bf16 v[36:39], v[168:171], v[192:195], 0
	v_mfma_f32_16x16x32_bf16 v[32:35], v[176:179], v[192:195], 0
	v_mfma_f32_16x16x32_bf16 v[20:23], v[168:171], v[200:203], 0
	v_mfma_f32_16x16x32_bf16 v[16:19], v[176:179], v[200:203], 0
	v_mfma_f32_16x16x32_bf16 v[4:7], v[168:171], v[208:211], 0
	v_mfma_f32_16x16x32_bf16 v[0:3], v[176:179], v[208:211], 0
	v_mfma_f32_16x16x32_bf16 v[52:55], v[172:175], v[188:191], v[52:55]
	v_mfma_f32_16x16x32_bf16 v[48:51], v[180:183], v[188:191], v[48:51]
	v_mfma_f32_16x16x32_bf16 v[36:39], v[172:175], v[196:199], v[36:39]
	v_mfma_f32_16x16x32_bf16 v[32:35], v[180:183], v[196:199], v[32:35]
	v_mfma_f32_16x16x32_bf16 v[20:23], v[172:175], v[204:207], v[20:23]
	v_mfma_f32_16x16x32_bf16 v[16:19], v[180:183], v[204:207], v[16:19]
	v_mfma_f32_16x16x32_bf16 v[4:7], v[172:175], v[212:215], v[4:7]
	v_mfma_f32_16x16x32_bf16 v[0:3], v[180:183], v[212:215], v[0:3]
	s_setprio 0
	s_barrier
	s_add_i32 s68, 0, 0x18000
	s_add_i32 s69, 0, 0x1c000
	v_add_u32_e32 v164, s68, v153
	v_add_u32_e32 v180, s69, v153
	ds_read_b128 v[144:147], v164
	ds_read_b128 v[148:151], v164 offset:1024
	ds_read_b128 v[160:163], v164 offset:2048
	ds_read_b128 v[164:167], v164 offset:3072
	ds_read_b128 v[168:171], v180
	ds_read_b128 v[172:175], v180 offset:1024
	ds_read_b128 v[176:179], v180 offset:2048
	ds_read_b128 v[180:183], v180 offset:3072
	s_add_u32 s44, s44, 0x80000
	s_addc_u32 s45, s45, 0
	s_mov_b32 m0, s55
	v_lshl_add_u64 v[226:227], s[44:45], 0, v[134:135]
	ds_read_b128 v[184:187], v157 offset:32768
	ds_read_b128 v[188:191], v157 offset:33792
	ds_read_b128 v[192:195], v157 offset:34816
	ds_read_b128 v[196:199], v157 offset:35840
	ds_read_b128 v[200:203], v157 offset:36864
	ds_read_b128 v[204:207], v157 offset:37888
	ds_read_b128 v[208:211], v157 offset:38912
	ds_read_b128 v[212:215], v157 offset:39936
	global_load_lds_dwordx4 v[226:227], off
	v_lshl_add_u64 v[226:227], s[44:45], 0, v[130:131]
	s_mov_b32 m0, s56
	s_nop 0
	global_load_lds_dwordx4 v[226:227], off
	s_waitcnt vmcnt(8)
	s_waitcnt lgkmcnt(0)
	s_barrier
	s_setprio 1
	s_waitcnt lgkmcnt(0)
	v_mfma_f32_16x16x32_bf16 v[124:127], v[144:147], v[184:187], v[124:127]
	v_mfma_f32_16x16x32_bf16 v[120:123], v[160:163], v[184:187], v[120:123]
	v_mfma_f32_16x16x32_bf16 v[108:111], v[144:147], v[192:195], v[108:111]
	v_mfma_f32_16x16x32_bf16 v[104:107], v[160:163], v[192:195], v[104:107]
	v_mfma_f32_16x16x32_bf16 v[92:95], v[144:147], v[200:203], v[92:95]
	v_mfma_f32_16x16x32_bf16 v[88:91], v[160:163], v[200:203], v[88:91]
	v_mfma_f32_16x16x32_bf16 v[76:79], v[144:147], v[208:211], v[76:79]
	v_mfma_f32_16x16x32_bf16 v[72:75], v[160:163], v[208:211], v[72:75]
	v_mfma_f32_16x16x32_bf16 v[124:127], v[148:151], v[188:191], v[124:127]
	v_mfma_f32_16x16x32_bf16 v[120:123], v[164:167], v[188:191], v[120:123]
	v_mfma_f32_16x16x32_bf16 v[108:111], v[148:151], v[196:199], v[108:111]
	v_mfma_f32_16x16x32_bf16 v[104:107], v[164:167], v[196:199], v[104:107]
	v_mfma_f32_16x16x32_bf16 v[92:95], v[148:151], v[204:207], v[92:95]
	v_mfma_f32_16x16x32_bf16 v[88:91], v[164:167], v[204:207], v[88:91]
	v_mfma_f32_16x16x32_bf16 v[76:79], v[148:151], v[212:215], v[76:79]
	v_mfma_f32_16x16x32_bf16 v[72:75], v[164:167], v[212:215], v[72:75]
	s_setprio 0
	s_setprio 1
	v_mfma_f32_16x16x32_bf16 v[116:119], v[168:171], v[184:187], v[116:119]
	v_mfma_f32_16x16x32_bf16 v[112:115], v[176:179], v[184:187], v[112:115]
	v_mfma_f32_16x16x32_bf16 v[100:103], v[168:171], v[192:195], v[100:103]
	v_mfma_f32_16x16x32_bf16 v[96:99], v[176:179], v[192:195], v[96:99]
	v_mfma_f32_16x16x32_bf16 v[84:87], v[168:171], v[200:203], v[84:87]
	v_mfma_f32_16x16x32_bf16 v[80:83], v[176:179], v[200:203], v[80:83]
	v_mfma_f32_16x16x32_bf16 v[68:71], v[168:171], v[208:211], v[68:71]
	v_mfma_f32_16x16x32_bf16 v[64:67], v[176:179], v[208:211], v[64:67]
	v_mfma_f32_16x16x32_bf16 v[116:119], v[172:175], v[188:191], v[116:119]
	v_mfma_f32_16x16x32_bf16 v[112:115], v[180:183], v[188:191], v[112:115]
	v_mfma_f32_16x16x32_bf16 v[100:103], v[172:175], v[196:199], v[100:103]
	v_mfma_f32_16x16x32_bf16 v[96:99], v[180:183], v[196:199], v[96:99]
	v_mfma_f32_16x16x32_bf16 v[84:87], v[172:175], v[204:207], v[84:87]
	v_mfma_f32_16x16x32_bf16 v[80:83], v[180:183], v[204:207], v[80:83]
	v_mfma_f32_16x16x32_bf16 v[68:71], v[172:175], v[212:215], v[68:71]
	v_mfma_f32_16x16x32_bf16 v[64:67], v[180:183], v[212:215], v[64:67]
	s_setprio 0
	s_barrier
; #define PG8_STAGE(bufoff, gbase, voff) do { _Pragma("unroll") for (int _i = 0; _i < 2; ++_i) \
;         __builtin_amdgcn_global_load_lds((const unsigned*)((const char*)(gbase) + (voff)[_i]), (PG8_LAS unsigned*)(lds + (bufoff) + ldsw + _i * 8192), 16, 0, 0); } while (0)
; #define PG8_LDA(dst, b, h) do { _Pragma("unroll") for (int m = 0; m < 4; ++m) _Pragma("unroll") for (int k = 0; k < 2; ++k) dst[m][k] = *(const PG8_LAS bf16x8*)(lds + PG8_SA(b, h) + aoff + m * 2048 + k * 1024); } while (0)
; #define PG8_MMA(ai, bj, At, Bt) do { __builtin_amdgcn_s_setprio(1); _Pragma("unroll") for (int m = 0; m < 4; ++m) _Pragma("unroll") for (int n = 0; n < 2; ++n) _Pragma("unroll") for (int k = 0; k < 2; ++k) \
;         acc[ai][bj][m][n] = __builtin_amdgcn_mfma_f32_16x16x32_bf16(Bt[n][k], At[m][k], acc[ai][bj][m][n], 0, 0, 0); __builtin_amdgcn_s_setprio(0); } while (0)
; #define PG8_WAIT_V(n) asm volatile("s_waitcnt vmcnt(" #n ")" ::: "memory")
; #define PG8_WAIT_L(n) asm volatile("s_waitcnt lgkmcnt(" #n ")" ::: "memory")
; #define PG8_BAR __builtin_amdgcn_s_barrier()
; #define PG8_SCHED __builtin_amdgcn_sched_barrier(0)
; template <class Epi, class Sched, bool ALIGN_EPI = false, bool SP2 = false>
; __device__ __forceinline__ void gemm_phase(PG8_LAS unsigned char* lds, const Gemm g, const Sched& S, const Epi& E) {
;     ...
;             PG8_LDA(At, 1, 1); PG8_STAGE(PG8_SB(1, 0), b3, voffB); PG8_STAGE(PG8_SB(1, 1), b3 + hstep, voffB); PG8_STAGE(PG8_SA(1, 0), a3, voffA);
;             PG8_WAIT_V(8); PG8_WAIT_L(0); PG8_BAR; PG8_MMA(1, 0, At, B0); PG8_MMA(1, 1, At, B1); PG8_BAR; PG8_SCHED;
	s_add_i32 s44, s68, s50
	v_lshl_add_u64 v[216:217], v[216:217], 0, s[18:19]
	s_mov_b32 m0, s44
	ds_read_b128 v[184:187], v157 offset:49152
	ds_read_b128 v[188:191], v157 offset:50176
	ds_read_b128 v[192:195], v157 offset:51200
	ds_read_b128 v[196:199], v157 offset:52224
	ds_read_b128 v[200:203], v157 offset:53248
	ds_read_b128 v[204:207], v157 offset:54272
	ds_read_b128 v[208:211], v157 offset:55296
	ds_read_b128 v[212:215], v157 offset:56320
	global_load_lds_dwordx4 v[216:217], off
	s_add_i32 m0, s44, 0x2000
	s_add_u32 s42, s42, 0x80080
	v_lshl_add_u64 v[216:217], v[220:221], 0, s[18:19]
	s_addc_u32 s43, s43, 0
	s_add_i32 s44, s69, s50
	global_load_lds_dwordx4 v[216:217], off
	v_lshl_add_u64 v[216:217], s[42:43], 0, v[132:133]
	s_mov_b32 m0, s44
	s_nop 0
	global_load_lds_dwordx4 v[216:217], off
	v_lshl_add_u64 v[216:217], s[42:43], 0, v[128:129]
	s_add_i32 m0, s44, 0x2000
	s_nop 0
	global_load_lds_dwordx4 v[216:217], off
	v_lshl_add_u64 v[216:217], v[222:223], 0, s[18:19]
	s_mov_b32 m0, s58
	s_nop 0
	global_load_lds_dwordx4 v[216:217], off
	v_lshl_add_u64 v[216:217], v[224:225], 0, s[18:19]
	s_mov_b32 m0, s59
	s_nop 0
	global_load_lds_dwordx4 v[216:217], off
	s_waitcnt vmcnt(8)
	s_waitcnt lgkmcnt(0)
	s_barrier
	s_setprio 1
	s_waitcnt lgkmcnt(0)
	v_mfma_f32_16x16x32_bf16 v[60:63], v[144:147], v[184:187], v[60:63]
	v_mfma_f32_16x16x32_bf16 v[56:59], v[160:163], v[184:187], v[56:59]
	v_mfma_f32_16x16x32_bf16 v[44:47], v[144:147], v[192:195], v[44:47]
	v_mfma_f32_16x16x32_bf16 v[40:43], v[160:163], v[192:195], v[40:43]
	v_mfma_f32_16x16x32_bf16 v[28:31], v[144:147], v[200:203], v[28:31]
	v_mfma_f32_16x16x32_bf16 v[24:27], v[160:163], v[200:203], v[24:27]
	v_mfma_f32_16x16x32_bf16 v[12:15], v[144:147], v[208:211], v[12:15]
	v_mfma_f32_16x16x32_bf16 v[8:11], v[160:163], v[208:211], v[8:11]
	v_mfma_f32_16x16x32_bf16 v[60:63], v[148:151], v[188:191], v[60:63]
	v_mfma_f32_16x16x32_bf16 v[56:59], v[164:167], v[188:191], v[56:59]
	v_mfma_f32_16x16x32_bf16 v[44:47], v[148:151], v[196:199], v[44:47]
	v_mfma_f32_16x16x32_bf16 v[40:43], v[164:167], v[196:199], v[40:43]
	v_mfma_f32_16x16x32_bf16 v[28:31], v[148:151], v[204:207], v[28:31]
	v_mfma_f32_16x16x32_bf16 v[24:27], v[164:167], v[204:207], v[24:27]
	v_mfma_f32_16x16x32_bf16 v[12:15], v[148:151], v[212:215], v[12:15]
	v_mfma_f32_16x16x32_bf16 v[8:11], v[164:167], v[212:215], v[8:11]
	s_setprio 0
	s_setprio 1
	v_mfma_f32_16x16x32_bf16 v[52:55], v[168:171], v[184:187], v[52:55]
	v_mfma_f32_16x16x32_bf16 v[48:51], v[176:179], v[184:187], v[48:51]
	v_mfma_f32_16x16x32_bf16 v[36:39], v[168:171], v[192:195], v[36:39]
	v_mfma_f32_16x16x32_bf16 v[32:35], v[176:179], v[192:195], v[32:35]
	v_mfma_f32_16x16x32_bf16 v[20:23], v[168:171], v[200:203], v[20:23]
	v_mfma_f32_16x16x32_bf16 v[16:19], v[176:179], v[200:203], v[16:19]
	v_mfma_f32_16x16x32_bf16 v[4:7], v[168:171], v[208:211], v[4:7]
	v_mfma_f32_16x16x32_bf16 v[0:3], v[176:179], v[208:211], v[0:3]
	v_mfma_f32_16x16x32_bf16 v[52:55], v[172:175], v[188:191], v[52:55]
	v_mfma_f32_16x16x32_bf16 v[48:51], v[180:183], v[188:191], v[48:51]
	v_mfma_f32_16x16x32_bf16 v[36:39], v[172:175], v[196:199], v[36:39]
	v_mfma_f32_16x16x32_bf16 v[32:35], v[180:183], v[196:199], v[32:35]
	v_mfma_f32_16x16x32_bf16 v[20:23], v[172:175], v[204:207], v[20:23]
	v_mfma_f32_16x16x32_bf16 v[16:19], v[180:183], v[204:207], v[16:19]
	v_mfma_f32_16x16x32_bf16 v[4:7], v[172:175], v[212:215], v[4:7]
	v_mfma_f32_16x16x32_bf16 v[0:3], v[180:183], v[212:215], v[0:3]
	s_setprio 0
	s_barrier
	s_add_i32 s67, s67, 2
	s_add_u32 s40, s40, 0x100
	s_addc_u32 s41, s41, 0
	s_add_u32 s65, s65, 0x100
	s_addc_u32 s66, s66, 0
	s_cmp_gt_u32 s67, 29

; #define PG8_STAGE(bufoff, gbase, voff) do { _Pragma("unroll") for (int _i = 0; _i < 2; ++_i) \
;         __builtin_amdgcn_global_load_lds((const unsigned*)((const char*)(gbase) + (voff)[_i]), (PG8_LAS unsigned*)(lds + (bufoff) + ldsw + _i * 8192), 16, 0, 0); } while (0)
; #define PG8_LDA(dst, b, h) do { _Pragma("unroll") for (int m = 0; m < 4; ++m) _Pragma("unroll") for (int k = 0; k < 2; ++k) dst[m][k] = *(const PG8_LAS bf16x8*)(lds + PG8_SA(b, h) + aoff + m * 2048 + k * 1024); } while (0)
; #define PG8_LDB(dst, b, h) do { _Pragma("unroll") for (int n = 0; n < 2; ++n) _Pragma("unroll") for (int k = 0; k < 2; ++k) dst[n][k] = *(const PG8_LAS bf16x8*)(lds + PG8_SB(b, h) + boff + n * 2048 + k * 1024); } while (0)
; #define PG8_MMA(ai, bj, At, Bt) do { __builtin_amdgcn_s_setprio(1); _Pragma("unroll") for (int m = 0; m < 4; ++m) _Pragma("unroll") for (int n = 0; n < 2; ++n) _Pragma("unroll") for (int k = 0; k < 2; ++k) \
;         acc[ai][bj][m][n] = __builtin_amdgcn_mfma_f32_16x16x32_bf16(Bt[n][k], At[m][k], acc[ai][bj][m][n], 0, 0, 0); __builtin_amdgcn_s_setprio(0); } while (0)
; #define PG8_WAIT_V(n) asm volatile("s_waitcnt vmcnt(" #n ")" ::: "memory")
; #define PG8_WAIT_L(n) asm volatile("s_waitcnt lgkmcnt(" #n ")" ::: "memory")
; #define PG8_BAR __builtin_amdgcn_s_barrier()
; template <class Epi, class Sched, bool ALIGN_EPI = false, bool SP2 = false>
; __device__ __forceinline__ void gemm_phase(PG8_LAS unsigned char* lds, const Gemm g, const Sched& S, const Epi& E) {
;     ...
;             const char* a1 = cA + (size_t)(t + 1) * kstep;
;             const char* a2 = last ? nA : cA + (size_t)(t + 2) * kstep; const char* b2 = last ? nB : cB + (size_t)(t + 2) * kstep;
;             const char* a3 = a2 + kstep; const char* b3 = b2 + kstep;
;             if (last && has_next) S.a_ready(nxt);
;             if constexpr (SP2) {
;             PG8_LDB(B0, 0, 0); PG8_LDB(B1, 0, 1); PG8_SCHED; PG8_LDA(At, 0, 0); PG8_STAGE(PG8_SA(1, 1), a1 + hstep, voffA);
;             PG8_WAIT_V(8); PG8_WAIT_L(0); PG8_BAR; PG8_MMA(0, 0, At, B0); PG8_MMA(0, 1, At, B1); PG8_BAR; PG8_SCHED;
;             PG8_LDA(At, 0, 1); PG8_STAGE(PG8_SB(0, 0), b2, voffB); PG8_STAGE(PG8_SB(0, 1), b2 + hstep, voffB); PG8_STAGE(PG8_SA(0, 0), a2, voffA);
;             PG8_WAIT_V(8); PG8_WAIT_L(0); PG8_BAR; PG8_MMA(1, 0, At, B0); PG8_MMA(1, 1, At, B1); PG8_BAR; PG8_SCHED;
.LBB0_1104:
	s_add_u32 s58, s30, 0x100
	s_addc_u32 s59, s31, 0
	s_mov_b32 s60, -2
	ds_read_b128 v[144:147], v217
	ds_read_b128 v[148:151], v217 offset:1024
	ds_read_b128 v[152:155], v217 offset:2048
	ds_read_b128 v[156:159], v217 offset:3072
	ds_read_b128 v[160:163], v218
	ds_read_b128 v[164:167], v218 offset:1024
	ds_read_b128 v[168:171], v218 offset:2048
	ds_read_b128 v[172:175], v218 offset:3072
	s_add_u32 s0, s28, 0x100
	s_addc_u32 s1, s29, 0
	s_cmpk_eq_i32 s60, 0x54
	s_cselect_b32 s35, s21, s1
	s_cselect_b32 s34, s20, s0
	s_cselect_b32 s31, s27, s59
	s_cselect_b32 s30, s26, s58
	v_lshl_add_u64 v[208:209], s[28:29], 0, v[136:137]
	s_add_i32 m0, s40, 0xc000
	ds_read_b128 v[176:179], v219
	ds_read_b128 v[180:183], v219 offset:1024
	ds_read_b128 v[184:187], v219 offset:2048
	ds_read_b128 v[188:191], v219 offset:3072
	ds_read_b128 v[192:195], v219 offset:4096
	ds_read_b128 v[196:199], v219 offset:5120
	ds_read_b128 v[200:203], v219 offset:6144
	ds_read_b128 v[204:207], v219 offset:7168
	global_load_lds_dwordx4 v[208:209], off
	v_lshl_add_u64 v[208:209], s[28:29], 0, v[138:139]
	s_add_i32 m0, s40, 0xe000
	s_nop 0
	global_load_lds_dwordx4 v[208:209], off
	s_waitcnt vmcnt(8)
	s_waitcnt lgkmcnt(0)
	s_barrier
	s_setprio 1
	s_waitcnt lgkmcnt(0)
	v_mfma_f32_16x16x32_bf16 v[124:127], v[144:147], v[176:179], 0
	v_mfma_f32_16x16x32_bf16 v[120:123], v[152:155], v[176:179], 0
	v_mfma_f32_16x16x32_bf16 v[116:119], v[144:147], v[184:187], 0
	v_mfma_f32_16x16x32_bf16 v[112:115], v[152:155], v[184:187], 0
	v_mfma_f32_16x16x32_bf16 v[100:103], v[144:147], v[192:195], 0
	v_mfma_f32_16x16x32_bf16 v[96:99], v[152:155], v[192:195], 0
	v_mfma_f32_16x16x32_bf16 v[84:87], v[144:147], v[200:203], 0
	v_mfma_f32_16x16x32_bf16 v[80:83], v[152:155], v[200:203], 0
	v_mfma_f32_16x16x32_bf16 v[124:127], v[148:151], v[180:183], v[124:127]
	v_mfma_f32_16x16x32_bf16 v[120:123], v[156:159], v[180:183], v[120:123]
	v_mfma_f32_16x16x32_bf16 v[116:119], v[148:151], v[188:191], v[116:119]
	v_mfma_f32_16x16x32_bf16 v[112:115], v[156:159], v[188:191], v[112:115]
	v_mfma_f32_16x16x32_bf16 v[100:103], v[148:151], v[196:199], v[100:103]
	v_mfma_f32_16x16x32_bf16 v[96:99], v[156:159], v[196:199], v[96:99]
	v_mfma_f32_16x16x32_bf16 v[84:87], v[148:151], v[204:207], v[84:87]
	v_mfma_f32_16x16x32_bf16 v[80:83], v[156:159], v[204:207], v[80:83]
	s_setprio 0
	s_setprio 1
	v_mfma_f32_16x16x32_bf16 v[108:111], v[160:163], v[176:179], 0
	v_mfma_f32_16x16x32_bf16 v[104:107], v[168:171], v[176:179], 0
	v_mfma_f32_16x16x32_bf16 v[92:95], v[160:163], v[184:187], 0
	v_mfma_f32_16x16x32_bf16 v[88:91], v[168:171], v[184:187], 0
	v_mfma_f32_16x16x32_bf16 v[76:79], v[160:163], v[192:195], 0
	v_mfma_f32_16x16x32_bf16 v[72:75], v[168:171], v[192:195], 0
	v_mfma_f32_16x16x32_bf16 v[68:71], v[160:163], v[200:203], 0
	v_mfma_f32_16x16x32_bf16 v[64:67], v[168:171], v[200:203], 0
	v_mfma_f32_16x16x32_bf16 v[108:111], v[164:167], v[180:183], v[108:111]
	v_mfma_f32_16x16x32_bf16 v[104:107], v[172:175], v[180:183], v[104:107]
	v_mfma_f32_16x16x32_bf16 v[92:95], v[164:167], v[188:191], v[92:95]
	v_mfma_f32_16x16x32_bf16 v[88:91], v[172:175], v[188:191], v[88:91]
	v_mfma_f32_16x16x32_bf16 v[76:79], v[164:167], v[196:199], v[76:79]
	v_mfma_f32_16x16x32_bf16 v[72:75], v[172:175], v[196:199], v[72:75]
	v_mfma_f32_16x16x32_bf16 v[68:71], v[164:167], v[204:207], v[68:71]
	v_mfma_f32_16x16x32_bf16 v[64:67], v[172:175], v[204:207], v[64:67]
	s_setprio 0
	s_barrier
	s_add_i32 s28, s51, s39
	v_lshl_add_u64 v[208:209], s[30:31], 0, v[130:131]
	s_mov_b32 m0, s28
	ds_read_b128 v[176:179], v219 offset:16384
	ds_read_b128 v[180:183], v219 offset:17408
	ds_read_b128 v[184:187], v219 offset:18432
	ds_read_b128 v[188:191], v219 offset:19456
	ds_read_b128 v[192:195], v219 offset:20480
	ds_read_b128 v[196:199], v219 offset:21504
	ds_read_b128 v[200:203], v219 offset:22528
	ds_read_b128 v[204:207], v219 offset:23552
	global_load_lds_dwordx4 v[208:209], off
	s_add_i32 m0, s28, 0x2000
	s_add_u32 s28, s30, 0x160000
	v_lshl_add_u64 v[210:211], s[30:31], 0, v[134:135]
	s_addc_u32 s29, s31, 0
	s_add_i32 s61, s52, s39
	global_load_lds_dwordx4 v[210:211], off
	v_lshl_add_u64 v[212:213], s[28:29], 0, v[130:131]
	s_mov_b32 m0, s61
	v_lshl_add_u64 v[224:225], s[34:35], 0, v[132:133]
	global_load_lds_dwordx4 v[212:213], off
	v_lshl_add_u64 v[212:213], s[28:29], 0, v[134:135]
	s_add_i32 m0, s61, 0x2000
	s_nop 0
	global_load_lds_dwordx4 v[212:213], off
	v_lshl_add_u64 v[212:213], s[34:35], 0, v[128:129]
	s_mov_b32 m0, s40
	s_nop 0
	global_load_lds_dwordx4 v[212:213], off
	s_mov_b32 m0, s41
	s_nop 0
	global_load_lds_dwordx4 v[224:225], off
	s_waitcnt vmcnt(8)
	s_waitcnt lgkmcnt(0)
	s_barrier
; #define PG8_STAGE(bufoff, gbase, voff) do { _Pragma("unroll") for (int _i = 0; _i < 2; ++_i) \
;         __builtin_amdgcn_global_load_lds((const unsigned*)((const char*)(gbase) + (voff)[_i]), (PG8_LAS unsigned*)(lds + (bufoff) + ldsw + _i * 8192), 16, 0, 0); } while (0)
; #define PG8_LDA(dst, b, h) do { _Pragma("unroll") for (int m = 0; m < 4; ++m) _Pragma("unroll") for (int k = 0; k < 2; ++k) dst[m][k] = *(const PG8_LAS bf16x8*)(lds + PG8_SA(b, h) + aoff + m * 2048 + k * 1024); } while (0)
; #define PG8_LDB(dst, b, h) do { _Pragma("unroll") for (int n = 0; n < 2; ++n) _Pragma("unroll") for (int k = 0; k < 2; ++k) dst[n][k] = *(const PG8_LAS bf16x8*)(lds + PG8_SB(b, h) + boff + n * 2048 + k * 1024); } while (0)
; #define PG8_MMA(ai, bj, At, Bt) do { __builtin_amdgcn_s_setprio(1); _Pragma("unroll") for (int m = 0; m < 4; ++m) _Pragma("unroll") for (int n = 0; n < 2; ++n) _Pragma("unroll") for (int k = 0; k < 2; ++k) \
;         acc[ai][bj][m][n] = __builtin_amdgcn_mfma_f32_16x16x32_bf16(Bt[n][k], At[m][k], acc[ai][bj][m][n], 0, 0, 0); __builtin_amdgcn_s_setprio(0); } while (0)
; #define PG8_WAIT_V(n) asm volatile("s_waitcnt vmcnt(" #n ")" ::: "memory")
; #define PG8_WAIT_L(n) asm volatile("s_waitcnt lgkmcnt(" #n ")" ::: "memory")
; #define PG8_BAR __builtin_amdgcn_s_barrier()
; #define PG8_SCHED __builtin_amdgcn_sched_barrier(0)
; template <class Epi, class Sched, bool ALIGN_EPI = false, bool SP2 = false>
; __device__ __forceinline__ void gemm_phase(PG8_LAS unsigned char* lds, const Gemm g, const Sched& S, const Epi& E) {
;     ...
;             PG8_WAIT_V(8); PG8_WAIT_L(0); PG8_BAR; PG8_MMA(1, 0, At, B0); PG8_MMA(1, 1, At, B1); PG8_BAR; PG8_SCHED;
;             PG8_LDB(B0, 1, 0); PG8_LDB(B1, 1, 1); PG8_SCHED; PG8_LDA(At, 1, 0); PG8_STAGE(PG8_SA(0, 1), a2 + hstep, voffA);
;             PG8_WAIT_V(8); PG8_WAIT_L(0); PG8_BAR; PG8_MMA(0, 0, At, B0); PG8_MMA(0, 1, At, B1); PG8_BAR; PG8_SCHED;
	s_setprio 1
	s_waitcnt lgkmcnt(0)
	v_mfma_f32_16x16x32_bf16 v[60:63], v[144:147], v[176:179], 0
	v_mfma_f32_16x16x32_bf16 v[56:59], v[152:155], v[176:179], 0
	v_mfma_f32_16x16x32_bf16 v[52:55], v[144:147], v[184:187], 0
	v_mfma_f32_16x16x32_bf16 v[48:51], v[152:155], v[184:187], 0
	v_mfma_f32_16x16x32_bf16 v[36:39], v[144:147], v[192:195], 0
	v_mfma_f32_16x16x32_bf16 v[32:35], v[152:155], v[192:195], 0
	v_mfma_f32_16x16x32_bf16 v[20:23], v[144:147], v[200:203], 0
	v_mfma_f32_16x16x32_bf16 v[16:19], v[152:155], v[200:203], 0
	v_mfma_f32_16x16x32_bf16 v[60:63], v[148:151], v[180:183], v[60:63]
	v_mfma_f32_16x16x32_bf16 v[56:59], v[156:159], v[180:183], v[56:59]
	v_mfma_f32_16x16x32_bf16 v[52:55], v[148:151], v[188:191], v[52:55]
	v_mfma_f32_16x16x32_bf16 v[48:51], v[156:159], v[188:191], v[48:51]
	v_mfma_f32_16x16x32_bf16 v[36:39], v[148:151], v[196:199], v[36:39]
	v_mfma_f32_16x16x32_bf16 v[32:35], v[156:159], v[196:199], v[32:35]
	v_mfma_f32_16x16x32_bf16 v[20:23], v[148:151], v[204:207], v[20:23]
	v_mfma_f32_16x16x32_bf16 v[16:19], v[156:159], v[204:207], v[16:19]
	s_setprio 0
	s_setprio 1
	v_mfma_f32_16x16x32_bf16 v[44:47], v[160:163], v[176:179], 0
	v_mfma_f32_16x16x32_bf16 v[40:43], v[168:171], v[176:179], 0
	v_mfma_f32_16x16x32_bf16 v[28:31], v[160:163], v[184:187], 0
	v_mfma_f32_16x16x32_bf16 v[24:27], v[168:171], v[184:187], 0
	v_mfma_f32_16x16x32_bf16 v[12:15], v[160:163], v[192:195], 0
	v_mfma_f32_16x16x32_bf16 v[8:11], v[168:171], v[192:195], 0
	v_mfma_f32_16x16x32_bf16 v[4:7], v[160:163], v[200:203], 0
	v_mfma_f32_16x16x32_bf16 v[0:3], v[168:171], v[200:203], 0
	v_mfma_f32_16x16x32_bf16 v[44:47], v[164:167], v[180:183], v[44:47]
	v_mfma_f32_16x16x32_bf16 v[40:43], v[172:175], v[180:183], v[40:43]
	v_mfma_f32_16x16x32_bf16 v[28:31], v[164:167], v[188:191], v[28:31]
	v_mfma_f32_16x16x32_bf16 v[24:27], v[172:175], v[188:191], v[24:27]
	v_mfma_f32_16x16x32_bf16 v[12:15], v[164:167], v[196:199], v[12:15]
	v_mfma_f32_16x16x32_bf16 v[8:11], v[172:175], v[196:199], v[8:11]
	v_mfma_f32_16x16x32_bf16 v[4:7], v[164:167], v[204:207], v[4:7]
	v_mfma_f32_16x16x32_bf16 v[0:3], v[172:175], v[204:207], v[0:3]
	s_setprio 0
	s_barrier
	s_add_i32 s61, 0, 0x18000
	s_add_i32 s62, 0, 0x1c000
	v_add_u32_e32 v156, s61, v215
	v_add_u32_e32 v172, s62, v215
	ds_read_b128 v[144:147], v156
	ds_read_b128 v[148:151], v156 offset:1024
	ds_read_b128 v[152:155], v156 offset:2048
	ds_read_b128 v[156:159], v156 offset:3072
	ds_read_b128 v[160:163], v172
	ds_read_b128 v[164:167], v172 offset:1024
	ds_read_b128 v[168:171], v172 offset:2048
	ds_read_b128 v[172:175], v172 offset:3072
	s_add_u32 s28, s34, 0x160000
	s_addc_u32 s29, s35, 0
	s_mov_b32 m0, s42
	v_lshl_add_u64 v[226:227], s[28:29], 0, v[128:129]
	ds_read_b128 v[176:179], v219 offset:32768
	ds_read_b128 v[180:183], v219 offset:33792
	ds_read_b128 v[184:187], v219 offset:34816
	ds_read_b128 v[188:191], v219 offset:35840
	ds_read_b128 v[192:195], v219 offset:36864
	ds_read_b128 v[196:199], v219 offset:37888
	ds_read_b128 v[200:203], v219 offset:38912
	ds_read_b128 v[204:207], v219 offset:39936
	global_load_lds_dwordx4 v[226:227], off
	v_lshl_add_u64 v[226:227], s[28:29], 0, v[132:133]
	s_mov_b32 m0, s43
	s_nop 0
	global_load_lds_dwordx4 v[226:227], off
	s_waitcnt vmcnt(8)
	s_waitcnt lgkmcnt(0)
	s_barrier
	s_setprio 1
	s_waitcnt lgkmcnt(0)
	v_mfma_f32_16x16x32_bf16 v[124:127], v[144:147], v[176:179], v[124:127]
	v_mfma_f32_16x16x32_bf16 v[120:123], v[152:155], v[176:179], v[120:123]
	v_mfma_f32_16x16x32_bf16 v[116:119], v[144:147], v[184:187], v[116:119]
	v_mfma_f32_16x16x32_bf16 v[112:115], v[152:155], v[184:187], v[112:115]
	v_mfma_f32_16x16x32_bf16 v[100:103], v[144:147], v[192:195], v[100:103]
	v_mfma_f32_16x16x32_bf16 v[96:99], v[152:155], v[192:195], v[96:99]
	v_mfma_f32_16x16x32_bf16 v[84:87], v[144:147], v[200:203], v[84:87]
	v_mfma_f32_16x16x32_bf16 v[80:83], v[152:155], v[200:203], v[80:83]
	v_mfma_f32_16x16x32_bf16 v[124:127], v[148:151], v[180:183], v[124:127]
	v_mfma_f32_16x16x32_bf16 v[120:123], v[156:159], v[180:183], v[120:123]
	v_mfma_f32_16x16x32_bf16 v[116:119], v[148:151], v[188:191], v[116:119]
	v_mfma_f32_16x16x32_bf16 v[112:115], v[156:159], v[188:191], v[112:115]
	v_mfma_f32_16x16x32_bf16 v[100:103], v[148:151], v[196:199], v[100:103]
	v_mfma_f32_16x16x32_bf16 v[96:99], v[156:159], v[196:199], v[96:99]
	v_mfma_f32_16x16x32_bf16 v[84:87], v[148:151], v[204:207], v[84:87]
	v_mfma_f32_16x16x32_bf16 v[80:83], v[156:159], v[204:207], v[80:83]
	s_setprio 0
	s_setprio 1
	v_mfma_f32_16x16x32_bf16 v[108:111], v[160:163], v[176:179], v[108:111]
	v_mfma_f32_16x16x32_bf16 v[104:107], v[168:171], v[176:179], v[104:107]
	v_mfma_f32_16x16x32_bf16 v[92:95], v[160:163], v[184:187], v[92:95]
	v_mfma_f32_16x16x32_bf16 v[88:91], v[168:171], v[184:187], v[88:91]
	v_mfma_f32_16x16x32_bf16 v[76:79], v[160:163], v[192:195], v[76:79]
	v_mfma_f32_16x16x32_bf16 v[72:75], v[168:171], v[192:195], v[72:75]
	v_mfma_f32_16x16x32_bf16 v[68:71], v[160:163], v[200:203], v[68:71]
	v_mfma_f32_16x16x32_bf16 v[64:67], v[168:171], v[200:203], v[64:67]
	v_mfma_f32_16x16x32_bf16 v[108:111], v[164:167], v[180:183], v[108:111]
	v_mfma_f32_16x16x32_bf16 v[104:107], v[172:175], v[180:183], v[104:107]
	v_mfma_f32_16x16x32_bf16 v[92:95], v[164:167], v[188:191], v[92:95]
	v_mfma_f32_16x16x32_bf16 v[88:91], v[172:175], v[188:191], v[88:91]
	v_mfma_f32_16x16x32_bf16 v[76:79], v[164:167], v[196:199], v[76:79]
	v_mfma_f32_16x16x32_bf16 v[72:75], v[172:175], v[196:199], v[72:75]
	v_mfma_f32_16x16x32_bf16 v[68:71], v[164:167], v[204:207], v[68:71]
	v_mfma_f32_16x16x32_bf16 v[64:67], v[172:175], v[204:207], v[64:67]
	s_setprio 0
	s_barrier
; #define PG8_STAGE(bufoff, gbase, voff) do { _Pragma("unroll") for (int _i = 0; _i < 2; ++_i) \
;         __builtin_amdgcn_global_load_lds((const unsigned*)((const char*)(gbase) + (voff)[_i]), (PG8_LAS unsigned*)(lds + (bufoff) + ldsw + _i * 8192), 16, 0, 0); } while (0)
; #define PG8_LDA(dst, b, h) do { _Pragma("unroll") for (int m = 0; m < 4; ++m) _Pragma("unroll") for (int k = 0; k < 2; ++k) dst[m][k] = *(const PG8_LAS bf16x8*)(lds + PG8_SA(b, h) + aoff + m * 2048 + k * 1024); } while (0)
; #define PG8_MMA(ai, bj, At, Bt) do { __builtin_amdgcn_s_setprio(1); _Pragma("unroll") for (int m = 0; m < 4; ++m) _Pragma("unroll") for (int n = 0; n < 2; ++n) _Pragma("unroll") for (int k = 0; k < 2; ++k) \
;         acc[ai][bj][m][n] = __builtin_amdgcn_mfma_f32_16x16x32_bf16(Bt[n][k], At[m][k], acc[ai][bj][m][n], 0, 0, 0); __builtin_amdgcn_s_setprio(0); } while (0)
; #define PG8_WAIT_V(n) asm volatile("s_waitcnt vmcnt(" #n ")" ::: "memory")
; #define PG8_WAIT_L(n) asm volatile("s_waitcnt lgkmcnt(" #n ")" ::: "memory")
; #define PG8_BAR __builtin_amdgcn_s_barrier()
; #define PG8_SCHED __builtin_amdgcn_sched_barrier(0)
; template <class Epi, class Sched, bool ALIGN_EPI = false, bool SP2 = false>
; __device__ __forceinline__ void gemm_phase(PG8_LAS unsigned char* lds, const Gemm g, const Sched& S, const Epi& E) {
;     ...
;             PG8_LDA(At, 1, 1); PG8_STAGE(PG8_SB(1, 0), b3, voffB); PG8_STAGE(PG8_SB(1, 1), b3 + hstep, voffB); PG8_STAGE(PG8_SA(1, 0), a3, voffA);
;             PG8_WAIT_V(8); PG8_WAIT_L(0); PG8_BAR; PG8_MMA(1, 0, At, B0); PG8_MMA(1, 1, At, B1); PG8_BAR; PG8_SCHED;
	s_add_i32 s28, s61, s39
	v_lshl_add_u64 v[208:209], v[208:209], 0, s[16:17]
	s_mov_b32 m0, s28
	ds_read_b128 v[176:179], v219 offset:49152
	ds_read_b128 v[180:183], v219 offset:50176
	ds_read_b128 v[184:187], v219 offset:51200
	ds_read_b128 v[188:191], v219 offset:52224
	ds_read_b128 v[192:195], v219 offset:53248
	ds_read_b128 v[196:199], v219 offset:54272
	ds_read_b128 v[200:203], v219 offset:55296
	ds_read_b128 v[204:207], v219 offset:56320
	global_load_lds_dwordx4 v[208:209], off
	s_add_i32 m0, s28, 0x2000
	s_add_u32 s28, s30, 0x160080
	v_lshl_add_u64 v[208:209], v[210:211], 0, s[16:17]
	s_addc_u32 s29, s31, 0
	s_add_i32 s30, s62, s39
	global_load_lds_dwordx4 v[208:209], off
	v_lshl_add_u64 v[208:209], s[28:29], 0, v[130:131]
	s_mov_b32 m0, s30
	s_nop 0
	global_load_lds_dwordx4 v[208:209], off
	v_lshl_add_u64 v[208:209], s[28:29], 0, v[134:135]
	s_add_i32 m0, s30, 0x2000
	s_nop 0
	global_load_lds_dwordx4 v[208:209], off
	v_lshl_add_u64 v[208:209], v[212:213], 0, s[16:17]
	s_mov_b32 m0, s47
	s_nop 0
	global_load_lds_dwordx4 v[208:209], off
	v_lshl_add_u64 v[208:209], v[224:225], 0, s[16:17]
	s_mov_b32 m0, s48
	s_nop 0
	global_load_lds_dwordx4 v[208:209], off
	s_waitcnt vmcnt(8)
	s_waitcnt lgkmcnt(0)
	s_barrier
	s_setprio 1
	s_waitcnt lgkmcnt(0)
	v_mfma_f32_16x16x32_bf16 v[60:63], v[144:147], v[176:179], v[60:63]
	v_mfma_f32_16x16x32_bf16 v[56:59], v[152:155], v[176:179], v[56:59]
	v_mfma_f32_16x16x32_bf16 v[52:55], v[144:147], v[184:187], v[52:55]
	v_mfma_f32_16x16x32_bf16 v[48:51], v[152:155], v[184:187], v[48:51]
	v_mfma_f32_16x16x32_bf16 v[36:39], v[144:147], v[192:195], v[36:39]
	v_mfma_f32_16x16x32_bf16 v[32:35], v[152:155], v[192:195], v[32:35]
	v_mfma_f32_16x16x32_bf16 v[20:23], v[144:147], v[200:203], v[20:23]
	v_mfma_f32_16x16x32_bf16 v[16:19], v[152:155], v[200:203], v[16:19]
	v_mfma_f32_16x16x32_bf16 v[60:63], v[148:151], v[180:183], v[60:63]
	v_mfma_f32_16x16x32_bf16 v[56:59], v[156:159], v[180:183], v[56:59]
	v_mfma_f32_16x16x32_bf16 v[52:55], v[148:151], v[188:191], v[52:55]
	v_mfma_f32_16x16x32_bf16 v[48:51], v[156:159], v[188:191], v[48:51]
	v_mfma_f32_16x16x32_bf16 v[36:39], v[148:151], v[196:199], v[36:39]
	v_mfma_f32_16x16x32_bf16 v[32:35], v[156:159], v[196:199], v[32:35]
	v_mfma_f32_16x16x32_bf16 v[20:23], v[148:151], v[204:207], v[20:23]
	v_mfma_f32_16x16x32_bf16 v[16:19], v[156:159], v[204:207], v[16:19]
	s_setprio 0
	s_setprio 1
	v_mfma_f32_16x16x32_bf16 v[44:47], v[160:163], v[176:179], v[44:47]
	v_mfma_f32_16x16x32_bf16 v[40:43], v[168:171], v[176:179], v[40:43]
	v_mfma_f32_16x16x32_bf16 v[28:31], v[160:163], v[184:187], v[28:31]
	v_mfma_f32_16x16x32_bf16 v[24:27], v[168:171], v[184:187], v[24:27]
	v_mfma_f32_16x16x32_bf16 v[12:15], v[160:163], v[192:195], v[12:15]
	v_mfma_f32_16x16x32_bf16 v[8:11], v[168:171], v[192:195], v[8:11]
	v_mfma_f32_16x16x32_bf16 v[4:7], v[160:163], v[200:203], v[4:7]
	v_mfma_f32_16x16x32_bf16 v[0:3], v[168:171], v[200:203], v[0:3]
	v_mfma_f32_16x16x32_bf16 v[44:47], v[164:167], v[180:183], v[44:47]
	v_mfma_f32_16x16x32_bf16 v[40:43], v[172:175], v[180:183], v[40:43]
	v_mfma_f32_16x16x32_bf16 v[28:31], v[164:167], v[188:191], v[28:31]
	v_mfma_f32_16x16x32_bf16 v[24:27], v[172:175], v[188:191], v[24:27]
	v_mfma_f32_16x16x32_bf16 v[12:15], v[164:167], v[196:199], v[12:15]
	v_mfma_f32_16x16x32_bf16 v[8:11], v[172:175], v[196:199], v[8:11]
	v_mfma_f32_16x16x32_bf16 v[4:7], v[164:167], v[204:207], v[4:7]
	v_mfma_f32_16x16x32_bf16 v[0:3], v[172:175], v[204:207], v[0:3]
	s_setprio 0
	s_barrier
	s_add_i32 s60, s60, 2
	s_add_u32 s58, s58, 0x100
	s_addc_u32 s59, s59, 0
	s_cmpk_gt_u32 s60, 0x55
	s_mov_b64 s[28:29], s[0:1]
